# v21 with the redundant post-barrier lgkmcnt(0) removed from the head of each MFMA segment in the seven GEMM K-loops
# baseline (speedup 1.0000x reference)
; #define PG8_STAGE(bufoff, gbase, voff) do { _Pragma("unroll") for (int _i = 0; _i < 2; ++_i) \
;         __builtin_amdgcn_global_load_lds((const unsigned*)((const char*)(gbase) + (voff)[_i]), (PG8_LAS unsigned*)(lds + (bufoff) + ldsw + _i * 8192), 16, 0, 0); } while (0)
; #define PG8_LDA(dst, b, h) do { _Pragma("unroll") for (int m = 0; m < 4; ++m) _Pragma("unroll") for (int k = 0; k < 2; ++k) dst[m][k] = *(const PG8_LAS bf16x8*)(lds + PG8_SA(b, h) + aoff + m * 2048 + k * 1024); } while (0)
; #define PG8_LDB(dst, b, h) do { _Pragma("unroll") for (int n = 0; n < 2; ++n) _Pragma("unroll") for (int k = 0; k < 2; ++k) dst[n][k] = *(const PG8_LAS bf16x8*)(lds + PG8_SB(b, h) + boff + n * 2048 + k * 1024); } while (0)
; #define PG8_MMA(ai, bj, At, Bt) do { __builtin_amdgcn_s_setprio(1); _Pragma("unroll") for (int m = 0; m < 4; ++m) _Pragma("unroll") for (int n = 0; n < 2; ++n) _Pragma("unroll") for (int k = 0; k < 2; ++k) \
;         acc[ai][bj][m][n] = __builtin_amdgcn_mfma_f32_16x16x32_bf16(Bt[n][k], At[m][k], acc[ai][bj][m][n], 0, 0, 0); __builtin_amdgcn_s_setprio(0); } while (0)
; #define PG8_WAIT_V(n) asm volatile("s_waitcnt vmcnt(" #n ")" ::: "memory")
; #define PG8_WAIT_L(n) asm volatile("s_waitcnt lgkmcnt(" #n ")" ::: "memory")
; #define PG8_BAR __builtin_amdgcn_s_barrier()
; template <class Epi, class Sched, bool ALIGN_EPI = false, bool SP2 = false>
; __device__ __forceinline__ void gemm_phase(PG8_LAS unsigned char* lds, const Gemm g, const Sched& S, const Epi& E, const int wave_id) {
;     ...
;             const char* a1 = cA + (size_t)(t + 1) * kstep;
;             const char* a2 = last ? nA : cA + (size_t)(t + 2) * kstep; const char* b2 = last ? nB : cB + (size_t)(t + 2) * kstep;
;             const char* a3 = a2 + kstep; const char* b3 = b2 + kstep;
;             if (last && has_next) S.a_ready(nxt);
;             if constexpr (SP2) {
;             PG8_LDB(B0, 0, 0); PG8_LDB(B1, 0, 1); PG8_SCHED; PG8_LDA(At, 0, 0); PG8_STAGE(PG8_SA(1, 1), a1 + hstepA, voffA);
;             PG8_WAIT_V(8); PG8_WAIT_L(0); PG8_BAR; PG8_MMA(0, 0, At, B0); PG8_MMA(0, 1, At, B1); PG8_BAR; PG8_SCHED;
;             PG8_LDA(At, 0, 1); PG8_STAGE(PG8_SB(0, 0), b2, voffB); PG8_STAGE(PG8_SB(0, 1), b2 + hstepB, voffB); PG8_STAGE(PG8_SA(0, 0), a2, voffA);
;             PG8_WAIT_V(8); PG8_WAIT_L(0); PG8_BAR; PG8_MMA(1, 0, At, B0); PG8_MMA(1, 1, At, B1); PG8_BAR; PG8_SCHED;
.LBB0_35:
	s_add_u32 s28, s26, 0xfff00080
	s_addc_u32 s29, s27, -1
	s_add_i32 s86, 0, 0x10000
	s_cmp_eq_u32 s83, 60
	s_cselect_b32 s31, s0, s29
	s_cselect_b32 s30, s1, s28
	v_add_u32_e32 v0, s86, v188
	s_cselect_b32 s29, s3, s38
	s_cselect_b32 s28, s19, s21
	s_add_i32 s91, 0, 0x14000
	ds_read_b128 v[130:133], v0
	ds_read_b128 v[134:137], v0 offset:1024
	ds_read_b128 v[138:141], v0 offset:2048
	ds_read_b128 v[142:145], v0 offset:3072
	v_add_u32_e32 v0, s91, v188
	ds_read_b128 v[146:149], v0
	ds_read_b128 v[150:153], v0 offset:1024
	ds_read_b128 v[166:169], v0 offset:2048
	ds_read_b128 v[178:181], v0 offset:3072
	v_lshl_add_u64 v[186:187], s[26:27], 0, v[162:163]
	s_add_i32 m0, s9, 0xc000
	ds_read_b128 v[182:185], v194
	ds_read_b128 v[196:199], v194 offset:1024
	ds_read_b128 v[200:203], v194 offset:2048
	ds_read_b128 v[204:207], v194 offset:3072
	ds_read_b128 v[208:211], v194 offset:4096
	ds_read_b128 v[212:215], v194 offset:5120
	ds_read_b128 v[216:219], v194 offset:6144
	ds_read_b128 v[220:223], v194 offset:7168
	global_load_lds_dwordx4 v[186:187], off
	v_lshl_add_u64 v[186:187], s[26:27], 0, v[164:165]
	s_add_i32 m0, s9, 0xe000
	s_nop 0
	global_load_lds_dwordx4 v[186:187], off
	s_waitcnt vmcnt(8)
	s_waitcnt lgkmcnt(0)
	s_barrier
	s_setprio 1
	v_mfma_f32_16x16x32_bf16 v[126:129], v[130:133], v[182:185], v[126:129]
	v_mfma_f32_16x16x32_bf16 v[122:125], v[138:141], v[182:185], v[122:125]
	v_mfma_f32_16x16x32_bf16 v[110:113], v[130:133], v[200:203], v[110:113]
	v_mfma_f32_16x16x32_bf16 v[106:109], v[138:141], v[200:203], v[106:109]
	v_mfma_f32_16x16x32_bf16 v[94:97], v[130:133], v[208:211], v[94:97]
	v_mfma_f32_16x16x32_bf16 v[90:93], v[138:141], v[208:211], v[90:93]
	v_mfma_f32_16x16x32_bf16 v[78:81], v[130:133], v[216:219], v[78:81]
	v_mfma_f32_16x16x32_bf16 v[74:77], v[138:141], v[216:219], v[74:77]
	v_mfma_f32_16x16x32_bf16 v[126:129], v[134:137], v[196:199], v[126:129]
	v_mfma_f32_16x16x32_bf16 v[122:125], v[142:145], v[196:199], v[122:125]
	v_mfma_f32_16x16x32_bf16 v[110:113], v[134:137], v[204:207], v[110:113]
	v_mfma_f32_16x16x32_bf16 v[106:109], v[142:145], v[204:207], v[106:109]
	v_mfma_f32_16x16x32_bf16 v[94:97], v[134:137], v[212:215], v[94:97]
	v_mfma_f32_16x16x32_bf16 v[90:93], v[142:145], v[212:215], v[90:93]
	v_mfma_f32_16x16x32_bf16 v[78:81], v[134:137], v[220:223], v[78:81]
	v_mfma_f32_16x16x32_bf16 v[74:77], v[142:145], v[220:223], v[74:77]
	v_mfma_f32_16x16x32_bf16 v[118:121], v[146:149], v[182:185], v[118:121]
	v_mfma_f32_16x16x32_bf16 v[114:117], v[166:169], v[182:185], v[114:117]
	v_mfma_f32_16x16x32_bf16 v[102:105], v[146:149], v[200:203], v[102:105]
	v_mfma_f32_16x16x32_bf16 v[98:101], v[166:169], v[200:203], v[98:101]
	v_mfma_f32_16x16x32_bf16 v[86:89], v[146:149], v[208:211], v[86:89]
	v_mfma_f32_16x16x32_bf16 v[82:85], v[166:169], v[208:211], v[82:85]
	v_mfma_f32_16x16x32_bf16 v[70:73], v[146:149], v[216:219], v[70:73]
	v_mfma_f32_16x16x32_bf16 v[66:69], v[166:169], v[216:219], v[66:69]
	v_mfma_f32_16x16x32_bf16 v[118:121], v[150:153], v[196:199], v[118:121]
	v_mfma_f32_16x16x32_bf16 v[114:117], v[178:181], v[196:199], v[114:117]
	v_mfma_f32_16x16x32_bf16 v[102:105], v[150:153], v[204:207], v[102:105]
	v_mfma_f32_16x16x32_bf16 v[98:101], v[178:181], v[204:207], v[98:101]
	v_mfma_f32_16x16x32_bf16 v[86:89], v[150:153], v[212:215], v[86:89]
	v_mfma_f32_16x16x32_bf16 v[82:85], v[178:181], v[212:215], v[82:85]
	v_mfma_f32_16x16x32_bf16 v[70:73], v[150:153], v[220:223], v[70:73]
	v_mfma_f32_16x16x32_bf16 v[66:69], v[178:181], v[220:223], v[66:69]
	s_setprio 0
	s_barrier
	s_add_i32 s86, s86, s14
	v_lshl_add_u64 v[186:187], s[28:29], 0, v[156:157]
	s_mov_b32 m0, s86
	ds_read_b128 v[182:185], v194 offset:16384
	ds_read_b128 v[196:199], v194 offset:17408
	ds_read_b128 v[200:203], v194 offset:18432
	ds_read_b128 v[204:207], v194 offset:19456
	ds_read_b128 v[208:211], v194 offset:20480
	ds_read_b128 v[212:215], v194 offset:21504
	ds_read_b128 v[216:219], v194 offset:22528
	ds_read_b128 v[220:223], v194 offset:23552
	global_load_lds_dwordx4 v[186:187], off
	s_add_i32 m0, s86, 0x2000
	s_add_u32 s86, s28, 0x100000
	v_lshl_add_u64 v[224:225], s[28:29], 0, v[160:161]
	s_addc_u32 s87, s29, 0
	s_add_i32 s91, s91, s14
	global_load_lds_dwordx4 v[224:225], off
	v_lshl_add_u64 v[234:235], s[86:87], 0, v[156:157]
	s_mov_b32 m0, s91
	v_lshl_add_u64 v[236:237], s[30:31], 0, v[158:159]
	global_load_lds_dwordx4 v[234:235], off
	v_lshl_add_u64 v[234:235], s[86:87], 0, v[160:161]
	s_add_i32 m0, s91, 0x2000
	s_nop 0
	global_load_lds_dwordx4 v[234:235], off
	v_lshl_add_u64 v[234:235], s[30:31], 0, v[154:155]
	s_mov_b32 m0, s9
	s_nop 0
	global_load_lds_dwordx4 v[234:235], off
	s_mov_b32 m0, s15
	s_nop 0
	global_load_lds_dwordx4 v[236:237], off
	s_waitcnt vmcnt(8)
	s_waitcnt lgkmcnt(0)
	s_barrier
; #define PG8_STAGE(bufoff, gbase, voff) do { _Pragma("unroll") for (int _i = 0; _i < 2; ++_i) \
;         __builtin_amdgcn_global_load_lds((const unsigned*)((const char*)(gbase) + (voff)[_i]), (PG8_LAS unsigned*)(lds + (bufoff) + ldsw + _i * 8192), 16, 0, 0); } while (0)
; #define PG8_LDA(dst, b, h) do { _Pragma("unroll") for (int m = 0; m < 4; ++m) _Pragma("unroll") for (int k = 0; k < 2; ++k) dst[m][k] = *(const PG8_LAS bf16x8*)(lds + PG8_SA(b, h) + aoff + m * 2048 + k * 1024); } while (0)
; #define PG8_LDB(dst, b, h) do { _Pragma("unroll") for (int n = 0; n < 2; ++n) _Pragma("unroll") for (int k = 0; k < 2; ++k) dst[n][k] = *(const PG8_LAS bf16x8*)(lds + PG8_SB(b, h) + boff + n * 2048 + k * 1024); } while (0)
; #define PG8_MMA(ai, bj, At, Bt) do { __builtin_amdgcn_s_setprio(1); _Pragma("unroll") for (int m = 0; m < 4; ++m) _Pragma("unroll") for (int n = 0; n < 2; ++n) _Pragma("unroll") for (int k = 0; k < 2; ++k) \
;         acc[ai][bj][m][n] = __builtin_amdgcn_mfma_f32_16x16x32_bf16(Bt[n][k], At[m][k], acc[ai][bj][m][n], 0, 0, 0); __builtin_amdgcn_s_setprio(0); } while (0)
; #define PG8_WAIT_V(n) asm volatile("s_waitcnt vmcnt(" #n ")" ::: "memory")
; #define PG8_WAIT_L(n) asm volatile("s_waitcnt lgkmcnt(" #n ")" ::: "memory")
; #define PG8_BAR __builtin_amdgcn_s_barrier()
; #define PG8_SCHED __builtin_amdgcn_sched_barrier(0)
; template <class Epi, class Sched, bool ALIGN_EPI = false, bool SP2 = false>
; __device__ __forceinline__ void gemm_phase(PG8_LAS unsigned char* lds, const Gemm g, const Sched& S, const Epi& E, const int wave_id) {
;     ...
;             PG8_WAIT_V(8); PG8_WAIT_L(0); PG8_BAR; PG8_MMA(1, 0, At, B0); PG8_MMA(1, 1, At, B1); PG8_BAR; PG8_SCHED;
;             PG8_LDB(B0, 1, 0); PG8_LDB(B1, 1, 1); PG8_SCHED; PG8_LDA(At, 1, 0); PG8_STAGE(PG8_SA(0, 1), a2 + hstepA, voffA);
;             PG8_WAIT_V(8); PG8_WAIT_L(0); PG8_BAR; PG8_MMA(0, 0, At, B0); PG8_MMA(0, 1, At, B1); PG8_BAR; PG8_SCHED;
	s_setprio 1
	v_mfma_f32_16x16x32_bf16 v[62:65], v[130:133], v[182:185], v[62:65]
	v_mfma_f32_16x16x32_bf16 v[58:61], v[138:141], v[182:185], v[58:61]
	v_mfma_f32_16x16x32_bf16 v[46:49], v[130:133], v[200:203], v[46:49]
	v_mfma_f32_16x16x32_bf16 v[42:45], v[138:141], v[200:203], v[42:45]
	v_mfma_f32_16x16x32_bf16 v[30:33], v[130:133], v[208:211], v[30:33]
	v_mfma_f32_16x16x32_bf16 v[26:29], v[138:141], v[208:211], v[26:29]
	v_mfma_f32_16x16x32_bf16 v[14:17], v[130:133], v[216:219], v[14:17]
	v_mfma_f32_16x16x32_bf16 v[10:13], v[138:141], v[216:219], v[10:13]
	v_mfma_f32_16x16x32_bf16 v[62:65], v[134:137], v[196:199], v[62:65]
	v_mfma_f32_16x16x32_bf16 v[58:61], v[142:145], v[196:199], v[58:61]
	v_mfma_f32_16x16x32_bf16 v[46:49], v[134:137], v[204:207], v[46:49]
	v_mfma_f32_16x16x32_bf16 v[42:45], v[142:145], v[204:207], v[42:45]
	v_mfma_f32_16x16x32_bf16 v[30:33], v[134:137], v[212:215], v[30:33]
	v_mfma_f32_16x16x32_bf16 v[26:29], v[142:145], v[212:215], v[26:29]
	v_mfma_f32_16x16x32_bf16 v[14:17], v[134:137], v[220:223], v[14:17]
	v_mfma_f32_16x16x32_bf16 v[10:13], v[142:145], v[220:223], v[10:13]
	v_mfma_f32_16x16x32_bf16 v[54:57], v[146:149], v[182:185], v[54:57]
	v_mfma_f32_16x16x32_bf16 v[50:53], v[166:169], v[182:185], v[50:53]
	v_mfma_f32_16x16x32_bf16 v[38:41], v[146:149], v[200:203], v[38:41]
	v_mfma_f32_16x16x32_bf16 v[34:37], v[166:169], v[200:203], v[34:37]
	v_mfma_f32_16x16x32_bf16 v[22:25], v[146:149], v[208:211], v[22:25]
	v_mfma_f32_16x16x32_bf16 v[18:21], v[166:169], v[208:211], v[18:21]
	v_mfma_f32_16x16x32_bf16 v[6:9], v[146:149], v[216:219], v[6:9]
	v_mfma_f32_16x16x32_bf16 v[2:5], v[166:169], v[216:219], v[2:5]
	v_mfma_f32_16x16x32_bf16 v[54:57], v[150:153], v[196:199], v[54:57]
	v_mfma_f32_16x16x32_bf16 v[50:53], v[178:181], v[196:199], v[50:53]
	v_mfma_f32_16x16x32_bf16 v[38:41], v[150:153], v[204:207], v[38:41]
	v_mfma_f32_16x16x32_bf16 v[34:37], v[178:181], v[204:207], v[34:37]
	v_mfma_f32_16x16x32_bf16 v[22:25], v[150:153], v[212:215], v[22:25]
	v_mfma_f32_16x16x32_bf16 v[18:21], v[178:181], v[212:215], v[18:21]
	v_mfma_f32_16x16x32_bf16 v[6:9], v[150:153], v[220:223], v[6:9]
	v_mfma_f32_16x16x32_bf16 v[2:5], v[178:181], v[220:223], v[2:5]
	s_setprio 0
	s_barrier
	s_add_i32 s86, 0, 0x18000
	v_add_u32_e32 v0, s86, v188
	s_add_i32 s87, 0, 0x1c000
	ds_read_b128 v[130:133], v0
	ds_read_b128 v[134:137], v0 offset:1024
	ds_read_b128 v[138:141], v0 offset:2048
	ds_read_b128 v[142:145], v0 offset:3072
	v_add_u32_e32 v0, s87, v188
	ds_read_b128 v[146:149], v0
	ds_read_b128 v[150:153], v0 offset:1024
	ds_read_b128 v[166:169], v0 offset:2048
	ds_read_b128 v[178:181], v0 offset:3072
	s_add_u32 s30, s30, 0x100000
	s_addc_u32 s31, s31, 0
	s_mov_b32 m0, s34
	v_lshl_add_u64 v[240:241], s[30:31], 0, v[154:155]
	ds_read_b128 v[182:185], v194 offset:32768
	ds_read_b128 v[196:199], v194 offset:33792
	ds_read_b128 v[200:203], v194 offset:34816
	ds_read_b128 v[204:207], v194 offset:35840
	ds_read_b128 v[208:211], v194 offset:36864
	ds_read_b128 v[212:215], v194 offset:37888
	ds_read_b128 v[216:219], v194 offset:38912
	ds_read_b128 v[220:223], v194 offset:39936
	global_load_lds_dwordx4 v[240:241], off
	v_lshl_add_u64 v[240:241], s[30:31], 0, v[158:159]
	s_mov_b32 m0, s35
	s_nop 0
	global_load_lds_dwordx4 v[240:241], off
	s_waitcnt vmcnt(8)
	s_waitcnt lgkmcnt(0)
	s_barrier
	s_setprio 1
	v_mfma_f32_16x16x32_bf16 v[126:129], v[130:133], v[182:185], v[126:129]
	v_mfma_f32_16x16x32_bf16 v[122:125], v[138:141], v[182:185], v[122:125]
	v_mfma_f32_16x16x32_bf16 v[110:113], v[130:133], v[200:203], v[110:113]
	v_mfma_f32_16x16x32_bf16 v[106:109], v[138:141], v[200:203], v[106:109]
	v_mfma_f32_16x16x32_bf16 v[94:97], v[130:133], v[208:211], v[94:97]
	v_mfma_f32_16x16x32_bf16 v[90:93], v[138:141], v[208:211], v[90:93]
	v_mfma_f32_16x16x32_bf16 v[78:81], v[130:133], v[216:219], v[78:81]
	v_mfma_f32_16x16x32_bf16 v[74:77], v[138:141], v[216:219], v[74:77]
	v_mfma_f32_16x16x32_bf16 v[126:129], v[134:137], v[196:199], v[126:129]
	v_mfma_f32_16x16x32_bf16 v[122:125], v[142:145], v[196:199], v[122:125]
	v_mfma_f32_16x16x32_bf16 v[110:113], v[134:137], v[204:207], v[110:113]
	v_mfma_f32_16x16x32_bf16 v[106:109], v[142:145], v[204:207], v[106:109]
	v_mfma_f32_16x16x32_bf16 v[94:97], v[134:137], v[212:215], v[94:97]
	v_mfma_f32_16x16x32_bf16 v[90:93], v[142:145], v[212:215], v[90:93]
	v_mfma_f32_16x16x32_bf16 v[78:81], v[134:137], v[220:223], v[78:81]
	v_mfma_f32_16x16x32_bf16 v[74:77], v[142:145], v[220:223], v[74:77]
	v_mfma_f32_16x16x32_bf16 v[118:121], v[146:149], v[182:185], v[118:121]
	v_mfma_f32_16x16x32_bf16 v[114:117], v[166:169], v[182:185], v[114:117]
	v_mfma_f32_16x16x32_bf16 v[102:105], v[146:149], v[200:203], v[102:105]
	v_mfma_f32_16x16x32_bf16 v[98:101], v[166:169], v[200:203], v[98:101]
	v_mfma_f32_16x16x32_bf16 v[86:89], v[146:149], v[208:211], v[86:89]
	v_mfma_f32_16x16x32_bf16 v[82:85], v[166:169], v[208:211], v[82:85]
	v_mfma_f32_16x16x32_bf16 v[70:73], v[146:149], v[216:219], v[70:73]
	v_mfma_f32_16x16x32_bf16 v[66:69], v[166:169], v[216:219], v[66:69]
	v_mfma_f32_16x16x32_bf16 v[118:121], v[150:153], v[196:199], v[118:121]
	v_mfma_f32_16x16x32_bf16 v[114:117], v[178:181], v[196:199], v[114:117]
	v_mfma_f32_16x16x32_bf16 v[102:105], v[150:153], v[204:207], v[102:105]
	v_mfma_f32_16x16x32_bf16 v[98:101], v[178:181], v[204:207], v[98:101]
	v_mfma_f32_16x16x32_bf16 v[86:89], v[150:153], v[212:215], v[86:89]
	v_mfma_f32_16x16x32_bf16 v[82:85], v[178:181], v[212:215], v[82:85]
	v_mfma_f32_16x16x32_bf16 v[70:73], v[150:153], v[220:223], v[70:73]
	v_mfma_f32_16x16x32_bf16 v[66:69], v[178:181], v[220:223], v[66:69]
	s_setprio 0
	s_barrier
; #define PG8_STAGE(bufoff, gbase, voff) do { _Pragma("unroll") for (int _i = 0; _i < 2; ++_i) \
;         __builtin_amdgcn_global_load_lds((const unsigned*)((const char*)(gbase) + (voff)[_i]), (PG8_LAS unsigned*)(lds + (bufoff) + ldsw + _i * 8192), 16, 0, 0); } while (0)
; #define PG8_LDA(dst, b, h) do { _Pragma("unroll") for (int m = 0; m < 4; ++m) _Pragma("unroll") for (int k = 0; k < 2; ++k) dst[m][k] = *(const PG8_LAS bf16x8*)(lds + PG8_SA(b, h) + aoff + m * 2048 + k * 1024); } while (0)
; #define PG8_MMA(ai, bj, At, Bt) do { __builtin_amdgcn_s_setprio(1); _Pragma("unroll") for (int m = 0; m < 4; ++m) _Pragma("unroll") for (int n = 0; n < 2; ++n) _Pragma("unroll") for (int k = 0; k < 2; ++k) \
;         acc[ai][bj][m][n] = __builtin_amdgcn_mfma_f32_16x16x32_bf16(Bt[n][k], At[m][k], acc[ai][bj][m][n], 0, 0, 0); __builtin_amdgcn_s_setprio(0); } while (0)
; #define PG8_WAIT_V(n) asm volatile("s_waitcnt vmcnt(" #n ")" ::: "memory")
; #define PG8_WAIT_L(n) asm volatile("s_waitcnt lgkmcnt(" #n ")" ::: "memory")
; #define PG8_BAR __builtin_amdgcn_s_barrier()
; #define PG8_SCHED __builtin_amdgcn_sched_barrier(0)
; template <class Epi, class Sched, bool ALIGN_EPI = false, bool SP2 = false>
; __device__ __forceinline__ void gemm_phase(PG8_LAS unsigned char* lds, const Gemm g, const Sched& S, const Epi& E, const int wave_id) {
;     ...
;         for (int t = 0; t < nt; t += 2) {
;             const bool last = (t == nt - 2);
;     ...
;             PG8_LDA(At, 1, 1); PG8_STAGE(PG8_SB(1, 0), b3, voffB); PG8_STAGE(PG8_SB(1, 1), b3 + hstepB, voffB); PG8_STAGE(PG8_SA(1, 0), a3, voffA);
;             PG8_WAIT_V(8); PG8_WAIT_L(0); PG8_BAR; PG8_MMA(1, 0, At, B0); PG8_MMA(1, 1, At, B1); PG8_BAR; PG8_SCHED;
	s_add_i32 s30, s86, s14
	v_lshl_add_u64 v[186:187], v[186:187], 0, s[62:63]
	s_mov_b32 m0, s30
	ds_read_b128 v[182:185], v194 offset:49152
	ds_read_b128 v[196:199], v194 offset:50176
	ds_read_b128 v[200:203], v194 offset:51200
	ds_read_b128 v[204:207], v194 offset:52224
	ds_read_b128 v[208:211], v194 offset:53248
	ds_read_b128 v[212:215], v194 offset:54272
	ds_read_b128 v[216:219], v194 offset:55296
	ds_read_b128 v[220:223], v194 offset:56320
	global_load_lds_dwordx4 v[186:187], off
	s_add_i32 m0, s30, 0x2000
	s_add_u32 s28, s28, 0x100080
	v_lshl_add_u64 v[186:187], v[224:225], 0, s[62:63]
	s_addc_u32 s29, s29, 0
	s_add_i32 s30, s87, s14
	global_load_lds_dwordx4 v[186:187], off
	v_lshl_add_u64 v[186:187], s[28:29], 0, v[156:157]
	s_mov_b32 m0, s30
	s_nop 0
	global_load_lds_dwordx4 v[186:187], off
	v_lshl_add_u64 v[186:187], s[28:29], 0, v[160:161]
	s_add_i32 m0, s30, 0x2000
	s_nop 0
	global_load_lds_dwordx4 v[186:187], off
	v_lshl_add_u64 v[186:187], v[234:235], 0, s[62:63]
	s_mov_b32 m0, s50
	s_nop 0
	global_load_lds_dwordx4 v[186:187], off
	v_lshl_add_u64 v[186:187], v[236:237], 0, s[62:63]
	s_mov_b32 m0, s76
	s_nop 0
	global_load_lds_dwordx4 v[186:187], off
	s_waitcnt vmcnt(8)
	s_waitcnt lgkmcnt(0)
	s_barrier
	s_setprio 1
	v_mfma_f32_16x16x32_bf16 v[62:65], v[130:133], v[182:185], v[62:65]
	v_mfma_f32_16x16x32_bf16 v[58:61], v[138:141], v[182:185], v[58:61]
	v_mfma_f32_16x16x32_bf16 v[46:49], v[130:133], v[200:203], v[46:49]
	v_mfma_f32_16x16x32_bf16 v[42:45], v[138:141], v[200:203], v[42:45]
	v_mfma_f32_16x16x32_bf16 v[30:33], v[130:133], v[208:211], v[30:33]
	v_mfma_f32_16x16x32_bf16 v[26:29], v[138:141], v[208:211], v[26:29]
	v_mfma_f32_16x16x32_bf16 v[14:17], v[130:133], v[216:219], v[14:17]
	v_mfma_f32_16x16x32_bf16 v[10:13], v[138:141], v[216:219], v[10:13]
	v_mfma_f32_16x16x32_bf16 v[62:65], v[134:137], v[196:199], v[62:65]
	v_mfma_f32_16x16x32_bf16 v[58:61], v[142:145], v[196:199], v[58:61]
	v_mfma_f32_16x16x32_bf16 v[46:49], v[134:137], v[204:207], v[46:49]
	v_mfma_f32_16x16x32_bf16 v[42:45], v[142:145], v[204:207], v[42:45]
	v_mfma_f32_16x16x32_bf16 v[30:33], v[134:137], v[212:215], v[30:33]
	v_mfma_f32_16x16x32_bf16 v[26:29], v[142:145], v[212:215], v[26:29]
	v_mfma_f32_16x16x32_bf16 v[14:17], v[134:137], v[220:223], v[14:17]
	v_mfma_f32_16x16x32_bf16 v[10:13], v[142:145], v[220:223], v[10:13]
	v_mfma_f32_16x16x32_bf16 v[54:57], v[146:149], v[182:185], v[54:57]
	v_mfma_f32_16x16x32_bf16 v[50:53], v[166:169], v[182:185], v[50:53]
	v_mfma_f32_16x16x32_bf16 v[38:41], v[146:149], v[200:203], v[38:41]
	v_mfma_f32_16x16x32_bf16 v[34:37], v[166:169], v[200:203], v[34:37]
	v_mfma_f32_16x16x32_bf16 v[22:25], v[146:149], v[208:211], v[22:25]
	v_mfma_f32_16x16x32_bf16 v[18:21], v[166:169], v[208:211], v[18:21]
	v_mfma_f32_16x16x32_bf16 v[6:9], v[146:149], v[216:219], v[6:9]
	v_mfma_f32_16x16x32_bf16 v[2:5], v[166:169], v[216:219], v[2:5]
	v_mfma_f32_16x16x32_bf16 v[54:57], v[150:153], v[196:199], v[54:57]
	v_mfma_f32_16x16x32_bf16 v[50:53], v[178:181], v[196:199], v[50:53]
	v_mfma_f32_16x16x32_bf16 v[38:41], v[150:153], v[204:207], v[38:41]
	v_mfma_f32_16x16x32_bf16 v[34:37], v[178:181], v[204:207], v[34:37]
	v_mfma_f32_16x16x32_bf16 v[22:25], v[150:153], v[212:215], v[22:25]
	v_mfma_f32_16x16x32_bf16 v[18:21], v[178:181], v[212:215], v[18:21]
	v_mfma_f32_16x16x32_bf16 v[6:9], v[150:153], v[220:223], v[6:9]
	v_mfma_f32_16x16x32_bf16 v[2:5], v[178:181], v[220:223], v[2:5]
	s_setprio 0
	s_barrier
	s_add_i32 s83, s83, 2
	s_add_u32 s26, s26, 0x100
	s_addc_u32 s27, s27, 0
	s_add_u32 s21, s21, 0x100
	s_addc_u32 s38, s38, 0
	s_cmp_gt_u32 s83, 61
	s_cbranch_scc0 .LBB0_35
	s_and_b64 vcc, exec, s[16:17]
	s_cbranch_vccz .LBB0_38
	s_barrier

; #define PG8_STAGE(bufoff, gbase, voff) do { _Pragma("unroll") for (int _i = 0; _i < 2; ++_i) \
;         __builtin_amdgcn_global_load_lds((const unsigned*)((const char*)(gbase) + (voff)[_i]), (PG8_LAS unsigned*)(lds + (bufoff) + ldsw + _i * 8192), 16, 0, 0); } while (0)
; #define PG8_LDA(dst, b, h) do { _Pragma("unroll") for (int m = 0; m < 4; ++m) _Pragma("unroll") for (int k = 0; k < 2; ++k) dst[m][k] = *(const PG8_LAS bf16x8*)(lds + PG8_SA(b, h) + aoff + m * 2048 + k * 1024); } while (0)
; #define PG8_LDB(dst, b, h) do { _Pragma("unroll") for (int n = 0; n < 2; ++n) _Pragma("unroll") for (int k = 0; k < 2; ++k) dst[n][k] = *(const PG8_LAS bf16x8*)(lds + PG8_SB(b, h) + boff + n * 2048 + k * 1024); } while (0)
; #define PG8_MMA(ai, bj, At, Bt) do { __builtin_amdgcn_s_setprio(1); _Pragma("unroll") for (int m = 0; m < 4; ++m) _Pragma("unroll") for (int n = 0; n < 2; ++n) _Pragma("unroll") for (int k = 0; k < 2; ++k) \
;         acc[ai][bj][m][n] = __builtin_amdgcn_mfma_f32_16x16x32_bf16(Bt[n][k], At[m][k], acc[ai][bj][m][n], 0, 0, 0); __builtin_amdgcn_s_setprio(0); } while (0)
; #define PG8_WAIT_V(n) asm volatile("s_waitcnt vmcnt(" #n ")" ::: "memory")
; #define PG8_WAIT_L(n) asm volatile("s_waitcnt lgkmcnt(" #n ")" ::: "memory")
; #define PG8_BAR __builtin_amdgcn_s_barrier()
; template <class Epi, class Sched, bool ALIGN_EPI = false, bool SP2 = false>
; __device__ __forceinline__ void gemm_phase(PG8_LAS unsigned char* lds, const Gemm g, const Sched& S, const Epi& E, const int wave_id) {
;     ...
;             const char* a1 = cA + (size_t)(t + 1) * kstep;
;             const char* a2 = last ? nA : cA + (size_t)(t + 2) * kstep; const char* b2 = last ? nB : cB + (size_t)(t + 2) * kstep;
;             const char* a3 = a2 + kstep; const char* b3 = b2 + kstep;
;             if (last && has_next) S.a_ready(nxt);
;             if constexpr (SP2) {
;             PG8_LDB(B0, 0, 0); PG8_LDB(B1, 0, 1); PG8_SCHED; PG8_LDA(At, 0, 0); PG8_STAGE(PG8_SA(1, 1), a1 + hstepA, voffA);
;             PG8_WAIT_V(8); PG8_WAIT_L(0); PG8_BAR; PG8_MMA(0, 0, At, B0); PG8_MMA(0, 1, At, B1); PG8_BAR; PG8_SCHED;
;             PG8_LDA(At, 0, 1); PG8_STAGE(PG8_SB(0, 0), b2, voffB); PG8_STAGE(PG8_SB(0, 1), b2 + hstepB, voffB); PG8_STAGE(PG8_SA(0, 0), a2, voffA);
;             PG8_WAIT_V(8); PG8_WAIT_L(0); PG8_BAR; PG8_MMA(1, 0, At, B0); PG8_MMA(1, 1, At, B1); PG8_BAR; PG8_SCHED;
.LBB0_69:
	s_add_u32 s18, s16, 0xfff00080
	s_addc_u32 s19, s17, -1
	s_add_i32 s39, 0, 0x10000
	s_cmp_eq_u32 s38, 4
	s_cselect_b32 s21, s30, s19
	s_cselect_b32 s20, s31, s18
	v_add_u32_e32 v0, s39, v139
	s_cselect_b32 s19, s34, s37
	s_cselect_b32 s18, s35, s36
	s_add_i32 s50, 0, 0x14000
	ds_read_b128 v[142:145], v0
	ds_read_b128 v[146:149], v0 offset:1024
	ds_read_b128 v[150:153], v0 offset:2048
	ds_read_b128 v[154:157], v0 offset:3072
	v_add_u32_e32 v0, s50, v139
	ds_read_b128 v[158:161], v0
	ds_read_b128 v[162:165], v0 offset:1024
	ds_read_b128 v[166:169], v0 offset:2048
	ds_read_b128 v[178:181], v0 offset:3072
	v_lshl_add_u64 v[214:215], s[16:17], 0, v[134:135]
	s_add_i32 m0, s3, 0xc000
	ds_read_b128 v[182:185], v141
	ds_read_b128 v[186:189], v141 offset:1024
	ds_read_b128 v[190:193], v141 offset:2048
	ds_read_b128 v[194:197], v141 offset:3072
	ds_read_b128 v[198:201], v141 offset:4096
	ds_read_b128 v[202:205], v141 offset:5120
	ds_read_b128 v[206:209], v141 offset:6144
	ds_read_b128 v[210:213], v141 offset:7168
	global_load_lds_dwordx4 v[214:215], off
	v_lshl_add_u64 v[214:215], s[16:17], 0, v[136:137]
	s_add_i32 m0, s3, 0xe000
	s_nop 0
	global_load_lds_dwordx4 v[214:215], off
	s_waitcnt vmcnt(8)
	s_waitcnt lgkmcnt(0)
	s_barrier
	s_setprio 1
	v_mfma_f32_16x16x32_bf16 v[126:129], v[142:145], v[182:185], v[126:129]
	v_mfma_f32_16x16x32_bf16 v[122:125], v[150:153], v[182:185], v[122:125]
	v_mfma_f32_16x16x32_bf16 v[118:121], v[142:145], v[190:193], v[118:121]
	v_mfma_f32_16x16x32_bf16 v[114:117], v[150:153], v[190:193], v[114:117]
	v_mfma_f32_16x16x32_bf16 v[106:109], v[142:145], v[198:201], v[106:109]
	v_mfma_f32_16x16x32_bf16 v[98:101], v[150:153], v[198:201], v[98:101]
	v_mfma_f32_16x16x32_bf16 v[90:93], v[142:145], v[206:209], v[90:93]
	v_mfma_f32_16x16x32_bf16 v[82:85], v[150:153], v[206:209], v[82:85]
	v_mfma_f32_16x16x32_bf16 v[126:129], v[146:149], v[186:189], v[126:129]
	v_mfma_f32_16x16x32_bf16 v[122:125], v[154:157], v[186:189], v[122:125]
	v_mfma_f32_16x16x32_bf16 v[118:121], v[146:149], v[194:197], v[118:121]
	v_mfma_f32_16x16x32_bf16 v[114:117], v[154:157], v[194:197], v[114:117]
	v_mfma_f32_16x16x32_bf16 v[106:109], v[146:149], v[202:205], v[106:109]
	v_mfma_f32_16x16x32_bf16 v[98:101], v[154:157], v[202:205], v[98:101]
	v_mfma_f32_16x16x32_bf16 v[90:93], v[146:149], v[210:213], v[90:93]
	v_mfma_f32_16x16x32_bf16 v[82:85], v[154:157], v[210:213], v[82:85]
	v_mfma_f32_16x16x32_bf16 v[110:113], v[158:161], v[182:185], v[110:113]
	v_mfma_f32_16x16x32_bf16 v[102:105], v[166:169], v[182:185], v[102:105]
	v_mfma_f32_16x16x32_bf16 v[94:97], v[158:161], v[190:193], v[94:97]
	v_mfma_f32_16x16x32_bf16 v[86:89], v[166:169], v[190:193], v[86:89]
	v_mfma_f32_16x16x32_bf16 v[78:81], v[158:161], v[198:201], v[78:81]
	v_mfma_f32_16x16x32_bf16 v[74:77], v[166:169], v[198:201], v[74:77]
	v_mfma_f32_16x16x32_bf16 v[70:73], v[158:161], v[206:209], v[70:73]
	v_mfma_f32_16x16x32_bf16 v[66:69], v[166:169], v[206:209], v[66:69]
	v_mfma_f32_16x16x32_bf16 v[110:113], v[162:165], v[186:189], v[110:113]
	v_mfma_f32_16x16x32_bf16 v[102:105], v[178:181], v[186:189], v[102:105]
	v_mfma_f32_16x16x32_bf16 v[94:97], v[162:165], v[194:197], v[94:97]
	v_mfma_f32_16x16x32_bf16 v[86:89], v[178:181], v[194:197], v[86:89]
	v_mfma_f32_16x16x32_bf16 v[78:81], v[162:165], v[202:205], v[78:81]
	v_mfma_f32_16x16x32_bf16 v[74:77], v[178:181], v[202:205], v[74:77]
	v_mfma_f32_16x16x32_bf16 v[70:73], v[162:165], v[210:213], v[70:73]
	v_mfma_f32_16x16x32_bf16 v[66:69], v[178:181], v[210:213], v[66:69]
	s_setprio 0
	s_barrier
	s_add_i32 s39, s39, s0
	v_lshl_add_u64 v[214:215], s[18:19], 0, v[132:133]
	s_mov_b32 m0, s39
	ds_read_b128 v[182:185], v141 offset:16384
	ds_read_b128 v[186:189], v141 offset:17408
	ds_read_b128 v[190:193], v141 offset:18432
	ds_read_b128 v[194:197], v141 offset:19456
	ds_read_b128 v[198:201], v141 offset:20480
	ds_read_b128 v[202:205], v141 offset:21504
	ds_read_b128 v[206:209], v141 offset:22528
	ds_read_b128 v[210:213], v141 offset:23552
	global_load_lds_dwordx4 v[214:215], off
	s_add_i32 m0, s39, 0x2000
	s_add_u32 s44, s18, 0x100000
	v_lshl_add_u64 v[216:217], s[18:19], 0, v[130:131]
	s_addc_u32 s45, s19, 0
	s_add_i32 s39, s50, s0
	global_load_lds_dwordx4 v[216:217], off
	v_lshl_add_u64 v[218:219], s[44:45], 0, v[132:133]
	s_mov_b32 m0, s39
	v_lshl_add_u64 v[220:221], s[20:21], 0, v[130:131]
	global_load_lds_dwordx4 v[218:219], off
	v_lshl_add_u64 v[218:219], s[44:45], 0, v[130:131]
	s_add_i32 m0, s39, 0x2000
	s_nop 0
	global_load_lds_dwordx4 v[218:219], off
	v_lshl_add_u64 v[218:219], s[20:21], 0, v[132:133]
	s_mov_b32 m0, s3
	s_nop 0
	global_load_lds_dwordx4 v[218:219], off
	s_mov_b32 m0, s15
	s_nop 0
	global_load_lds_dwordx4 v[220:221], off
	s_waitcnt vmcnt(8)
	s_waitcnt lgkmcnt(0)
	s_barrier
; #define PG8_STAGE(bufoff, gbase, voff) do { _Pragma("unroll") for (int _i = 0; _i < 2; ++_i) \
;         __builtin_amdgcn_global_load_lds((const unsigned*)((const char*)(gbase) + (voff)[_i]), (PG8_LAS unsigned*)(lds + (bufoff) + ldsw + _i * 8192), 16, 0, 0); } while (0)
; #define PG8_LDA(dst, b, h) do { _Pragma("unroll") for (int m = 0; m < 4; ++m) _Pragma("unroll") for (int k = 0; k < 2; ++k) dst[m][k] = *(const PG8_LAS bf16x8*)(lds + PG8_SA(b, h) + aoff + m * 2048 + k * 1024); } while (0)
; #define PG8_LDB(dst, b, h) do { _Pragma("unroll") for (int n = 0; n < 2; ++n) _Pragma("unroll") for (int k = 0; k < 2; ++k) dst[n][k] = *(const PG8_LAS bf16x8*)(lds + PG8_SB(b, h) + boff + n * 2048 + k * 1024); } while (0)
; #define PG8_MMA(ai, bj, At, Bt) do { __builtin_amdgcn_s_setprio(1); _Pragma("unroll") for (int m = 0; m < 4; ++m) _Pragma("unroll") for (int n = 0; n < 2; ++n) _Pragma("unroll") for (int k = 0; k < 2; ++k) \
;         acc[ai][bj][m][n] = __builtin_amdgcn_mfma_f32_16x16x32_bf16(Bt[n][k], At[m][k], acc[ai][bj][m][n], 0, 0, 0); __builtin_amdgcn_s_setprio(0); } while (0)
; #define PG8_WAIT_V(n) asm volatile("s_waitcnt vmcnt(" #n ")" ::: "memory")
; #define PG8_WAIT_L(n) asm volatile("s_waitcnt lgkmcnt(" #n ")" ::: "memory")
; #define PG8_BAR __builtin_amdgcn_s_barrier()
; #define PG8_SCHED __builtin_amdgcn_sched_barrier(0)
; template <class Epi, class Sched, bool ALIGN_EPI = false, bool SP2 = false>
; __device__ __forceinline__ void gemm_phase(PG8_LAS unsigned char* lds, const Gemm g, const Sched& S, const Epi& E, const int wave_id) {
;     ...
;             PG8_WAIT_V(8); PG8_WAIT_L(0); PG8_BAR; PG8_MMA(1, 0, At, B0); PG8_MMA(1, 1, At, B1); PG8_BAR; PG8_SCHED;
;             PG8_LDB(B0, 1, 0); PG8_LDB(B1, 1, 1); PG8_SCHED; PG8_LDA(At, 1, 0); PG8_STAGE(PG8_SA(0, 1), a2 + hstepA, voffA);
;             PG8_WAIT_V(8); PG8_WAIT_L(0); PG8_BAR; PG8_MMA(0, 0, At, B0); PG8_MMA(0, 1, At, B1); PG8_BAR; PG8_SCHED;
	s_setprio 1
	v_mfma_f32_16x16x32_bf16 v[62:65], v[142:145], v[182:185], v[62:65]
	v_mfma_f32_16x16x32_bf16 v[58:61], v[150:153], v[182:185], v[58:61]
	v_mfma_f32_16x16x32_bf16 v[54:57], v[142:145], v[190:193], v[54:57]
	v_mfma_f32_16x16x32_bf16 v[50:53], v[150:153], v[190:193], v[50:53]
	v_mfma_f32_16x16x32_bf16 v[42:45], v[142:145], v[198:201], v[42:45]
	v_mfma_f32_16x16x32_bf16 v[34:37], v[150:153], v[198:201], v[34:37]
	v_mfma_f32_16x16x32_bf16 v[26:29], v[142:145], v[206:209], v[26:29]
	v_mfma_f32_16x16x32_bf16 v[18:21], v[150:153], v[206:209], v[18:21]
	v_mfma_f32_16x16x32_bf16 v[62:65], v[146:149], v[186:189], v[62:65]
	v_mfma_f32_16x16x32_bf16 v[58:61], v[154:157], v[186:189], v[58:61]
	v_mfma_f32_16x16x32_bf16 v[54:57], v[146:149], v[194:197], v[54:57]
	v_mfma_f32_16x16x32_bf16 v[50:53], v[154:157], v[194:197], v[50:53]
	v_mfma_f32_16x16x32_bf16 v[42:45], v[146:149], v[202:205], v[42:45]
	v_mfma_f32_16x16x32_bf16 v[34:37], v[154:157], v[202:205], v[34:37]
	v_mfma_f32_16x16x32_bf16 v[26:29], v[146:149], v[210:213], v[26:29]
	v_mfma_f32_16x16x32_bf16 v[18:21], v[154:157], v[210:213], v[18:21]
	v_mfma_f32_16x16x32_bf16 v[46:49], v[158:161], v[182:185], v[46:49]
	v_mfma_f32_16x16x32_bf16 v[38:41], v[166:169], v[182:185], v[38:41]
	v_mfma_f32_16x16x32_bf16 v[30:33], v[158:161], v[190:193], v[30:33]
	v_mfma_f32_16x16x32_bf16 v[22:25], v[166:169], v[190:193], v[22:25]
	v_mfma_f32_16x16x32_bf16 v[14:17], v[158:161], v[198:201], v[14:17]
	v_mfma_f32_16x16x32_bf16 v[10:13], v[166:169], v[198:201], v[10:13]
	v_mfma_f32_16x16x32_bf16 v[6:9], v[158:161], v[206:209], v[6:9]
	v_mfma_f32_16x16x32_bf16 v[2:5], v[166:169], v[206:209], v[2:5]
	v_mfma_f32_16x16x32_bf16 v[46:49], v[162:165], v[186:189], v[46:49]
	v_mfma_f32_16x16x32_bf16 v[38:41], v[178:181], v[186:189], v[38:41]
	v_mfma_f32_16x16x32_bf16 v[30:33], v[162:165], v[194:197], v[30:33]
	v_mfma_f32_16x16x32_bf16 v[22:25], v[178:181], v[194:197], v[22:25]
	v_mfma_f32_16x16x32_bf16 v[14:17], v[162:165], v[202:205], v[14:17]
	v_mfma_f32_16x16x32_bf16 v[10:13], v[178:181], v[202:205], v[10:13]
	v_mfma_f32_16x16x32_bf16 v[6:9], v[162:165], v[210:213], v[6:9]
	v_mfma_f32_16x16x32_bf16 v[2:5], v[178:181], v[210:213], v[2:5]
	s_setprio 0
	s_barrier
	s_add_i32 s39, 0, 0x18000
	v_add_u32_e32 v0, s39, v139
	s_add_i32 s44, 0, 0x1c000
	ds_read_b128 v[142:145], v0
	ds_read_b128 v[146:149], v0 offset:1024
	ds_read_b128 v[150:153], v0 offset:2048
	ds_read_b128 v[154:157], v0 offset:3072
	v_add_u32_e32 v0, s44, v139
	ds_read_b128 v[158:161], v0
	ds_read_b128 v[162:165], v0 offset:1024
	ds_read_b128 v[166:169], v0 offset:2048
	ds_read_b128 v[178:181], v0 offset:3072
	s_add_u32 s20, s20, 0x100000
	s_addc_u32 s21, s21, 0
	s_mov_b32 m0, s22
	v_lshl_add_u64 v[222:223], s[20:21], 0, v[132:133]
	ds_read_b128 v[182:185], v141 offset:32768
	ds_read_b128 v[186:189], v141 offset:33792
	ds_read_b128 v[190:193], v141 offset:34816
	ds_read_b128 v[194:197], v141 offset:35840
	ds_read_b128 v[198:201], v141 offset:36864
	ds_read_b128 v[202:205], v141 offset:37888
	ds_read_b128 v[206:209], v141 offset:38912
	ds_read_b128 v[210:213], v141 offset:39936
	global_load_lds_dwordx4 v[222:223], off
	v_lshl_add_u64 v[222:223], s[20:21], 0, v[130:131]
	s_mov_b32 m0, s23
	s_nop 0
	global_load_lds_dwordx4 v[222:223], off
	s_waitcnt vmcnt(8)
	s_waitcnt lgkmcnt(0)
	s_barrier
	s_setprio 1
	v_mfma_f32_16x16x32_bf16 v[126:129], v[142:145], v[182:185], v[126:129]
	v_mfma_f32_16x16x32_bf16 v[122:125], v[150:153], v[182:185], v[122:125]
	v_mfma_f32_16x16x32_bf16 v[118:121], v[142:145], v[190:193], v[118:121]
	v_mfma_f32_16x16x32_bf16 v[114:117], v[150:153], v[190:193], v[114:117]
	v_mfma_f32_16x16x32_bf16 v[106:109], v[142:145], v[198:201], v[106:109]
	v_mfma_f32_16x16x32_bf16 v[98:101], v[150:153], v[198:201], v[98:101]
	v_mfma_f32_16x16x32_bf16 v[90:93], v[142:145], v[206:209], v[90:93]
	v_mfma_f32_16x16x32_bf16 v[82:85], v[150:153], v[206:209], v[82:85]
	v_mfma_f32_16x16x32_bf16 v[126:129], v[146:149], v[186:189], v[126:129]
	v_mfma_f32_16x16x32_bf16 v[122:125], v[154:157], v[186:189], v[122:125]
	v_mfma_f32_16x16x32_bf16 v[118:121], v[146:149], v[194:197], v[118:121]
	v_mfma_f32_16x16x32_bf16 v[114:117], v[154:157], v[194:197], v[114:117]
	v_mfma_f32_16x16x32_bf16 v[106:109], v[146:149], v[202:205], v[106:109]
	v_mfma_f32_16x16x32_bf16 v[98:101], v[154:157], v[202:205], v[98:101]
	v_mfma_f32_16x16x32_bf16 v[90:93], v[146:149], v[210:213], v[90:93]
	v_mfma_f32_16x16x32_bf16 v[82:85], v[154:157], v[210:213], v[82:85]
	v_mfma_f32_16x16x32_bf16 v[110:113], v[158:161], v[182:185], v[110:113]
	v_mfma_f32_16x16x32_bf16 v[102:105], v[166:169], v[182:185], v[102:105]
	v_mfma_f32_16x16x32_bf16 v[94:97], v[158:161], v[190:193], v[94:97]
	v_mfma_f32_16x16x32_bf16 v[86:89], v[166:169], v[190:193], v[86:89]
	v_mfma_f32_16x16x32_bf16 v[78:81], v[158:161], v[198:201], v[78:81]
	v_mfma_f32_16x16x32_bf16 v[74:77], v[166:169], v[198:201], v[74:77]
	v_mfma_f32_16x16x32_bf16 v[70:73], v[158:161], v[206:209], v[70:73]
	v_mfma_f32_16x16x32_bf16 v[66:69], v[166:169], v[206:209], v[66:69]
	v_mfma_f32_16x16x32_bf16 v[110:113], v[162:165], v[186:189], v[110:113]
	v_mfma_f32_16x16x32_bf16 v[102:105], v[178:181], v[186:189], v[102:105]
	v_mfma_f32_16x16x32_bf16 v[94:97], v[162:165], v[194:197], v[94:97]
	v_mfma_f32_16x16x32_bf16 v[86:89], v[178:181], v[194:197], v[86:89]
	v_mfma_f32_16x16x32_bf16 v[78:81], v[162:165], v[202:205], v[78:81]
	v_mfma_f32_16x16x32_bf16 v[74:77], v[178:181], v[202:205], v[74:77]
	v_mfma_f32_16x16x32_bf16 v[70:73], v[162:165], v[210:213], v[70:73]
	v_mfma_f32_16x16x32_bf16 v[66:69], v[178:181], v[210:213], v[66:69]
	s_setprio 0
	s_barrier
; #define PG8_STAGE(bufoff, gbase, voff) do { _Pragma("unroll") for (int _i = 0; _i < 2; ++_i) \
;         __builtin_amdgcn_global_load_lds((const unsigned*)((const char*)(gbase) + (voff)[_i]), (PG8_LAS unsigned*)(lds + (bufoff) + ldsw + _i * 8192), 16, 0, 0); } while (0)
; #define PG8_LDA(dst, b, h) do { _Pragma("unroll") for (int m = 0; m < 4; ++m) _Pragma("unroll") for (int k = 0; k < 2; ++k) dst[m][k] = *(const PG8_LAS bf16x8*)(lds + PG8_SA(b, h) + aoff + m * 2048 + k * 1024); } while (0)
; #define PG8_MMA(ai, bj, At, Bt) do { __builtin_amdgcn_s_setprio(1); _Pragma("unroll") for (int m = 0; m < 4; ++m) _Pragma("unroll") for (int n = 0; n < 2; ++n) _Pragma("unroll") for (int k = 0; k < 2; ++k) \
;         acc[ai][bj][m][n] = __builtin_amdgcn_mfma_f32_16x16x32_bf16(Bt[n][k], At[m][k], acc[ai][bj][m][n], 0, 0, 0); __builtin_amdgcn_s_setprio(0); } while (0)
; #define PG8_WAIT_V(n) asm volatile("s_waitcnt vmcnt(" #n ")" ::: "memory")
; #define PG8_WAIT_L(n) asm volatile("s_waitcnt lgkmcnt(" #n ")" ::: "memory")
; #define PG8_BAR __builtin_amdgcn_s_barrier()
; #define PG8_SCHED __builtin_amdgcn_sched_barrier(0)
; template <class Epi, class Sched, bool ALIGN_EPI = false, bool SP2 = false>
; __device__ __forceinline__ void gemm_phase(PG8_LAS unsigned char* lds, const Gemm g, const Sched& S, const Epi& E, const int wave_id) {
;     ...
;         for (int t = 0; t < nt; t += 2) {
;             const bool last = (t == nt - 2);
;     ...
;             PG8_LDA(At, 1, 1); PG8_STAGE(PG8_SB(1, 0), b3, voffB); PG8_STAGE(PG8_SB(1, 1), b3 + hstepB, voffB); PG8_STAGE(PG8_SA(1, 0), a3, voffA);
;             PG8_WAIT_V(8); PG8_WAIT_L(0); PG8_BAR; PG8_MMA(1, 0, At, B0); PG8_MMA(1, 1, At, B1); PG8_BAR; PG8_SCHED;
	s_add_i32 s20, s39, s0
	v_lshl_add_u64 v[214:215], v[214:215], 0, s[62:63]
	s_mov_b32 m0, s20
	ds_read_b128 v[182:185], v141 offset:49152
	ds_read_b128 v[186:189], v141 offset:50176
	ds_read_b128 v[190:193], v141 offset:51200
	ds_read_b128 v[194:197], v141 offset:52224
	ds_read_b128 v[198:201], v141 offset:53248
	ds_read_b128 v[202:205], v141 offset:54272
	ds_read_b128 v[206:209], v141 offset:55296
	ds_read_b128 v[210:213], v141 offset:56320
	global_load_lds_dwordx4 v[214:215], off
	s_add_i32 m0, s20, 0x2000
	s_add_u32 s18, s18, 0x100080
	v_lshl_add_u64 v[214:215], v[216:217], 0, s[62:63]
	s_addc_u32 s19, s19, 0
	s_add_i32 s20, s44, s0
	global_load_lds_dwordx4 v[214:215], off
	v_lshl_add_u64 v[214:215], s[18:19], 0, v[132:133]
	s_mov_b32 m0, s20
	s_nop 0
	global_load_lds_dwordx4 v[214:215], off
	v_lshl_add_u64 v[214:215], s[18:19], 0, v[130:131]
	s_add_i32 m0, s20, 0x2000
	s_nop 0
	global_load_lds_dwordx4 v[214:215], off
	v_lshl_add_u64 v[214:215], v[218:219], 0, s[62:63]
	s_mov_b32 m0, s24
	s_nop 0
	global_load_lds_dwordx4 v[214:215], off
	v_lshl_add_u64 v[214:215], v[220:221], 0, s[62:63]
	s_mov_b32 m0, s25
	s_nop 0
	global_load_lds_dwordx4 v[214:215], off
	s_waitcnt vmcnt(8)
	s_waitcnt lgkmcnt(0)
	s_barrier
	s_setprio 1
	v_mfma_f32_16x16x32_bf16 v[62:65], v[142:145], v[182:185], v[62:65]
	v_mfma_f32_16x16x32_bf16 v[58:61], v[150:153], v[182:185], v[58:61]
	v_mfma_f32_16x16x32_bf16 v[54:57], v[142:145], v[190:193], v[54:57]
	v_mfma_f32_16x16x32_bf16 v[50:53], v[150:153], v[190:193], v[50:53]
	v_mfma_f32_16x16x32_bf16 v[42:45], v[142:145], v[198:201], v[42:45]
	v_mfma_f32_16x16x32_bf16 v[34:37], v[150:153], v[198:201], v[34:37]
	v_mfma_f32_16x16x32_bf16 v[26:29], v[142:145], v[206:209], v[26:29]
	v_mfma_f32_16x16x32_bf16 v[18:21], v[150:153], v[206:209], v[18:21]
	v_mfma_f32_16x16x32_bf16 v[62:65], v[146:149], v[186:189], v[62:65]
	v_mfma_f32_16x16x32_bf16 v[58:61], v[154:157], v[186:189], v[58:61]
	v_mfma_f32_16x16x32_bf16 v[54:57], v[146:149], v[194:197], v[54:57]
	v_mfma_f32_16x16x32_bf16 v[50:53], v[154:157], v[194:197], v[50:53]
	v_mfma_f32_16x16x32_bf16 v[42:45], v[146:149], v[202:205], v[42:45]
	v_mfma_f32_16x16x32_bf16 v[34:37], v[154:157], v[202:205], v[34:37]
	v_mfma_f32_16x16x32_bf16 v[26:29], v[146:149], v[210:213], v[26:29]
	v_mfma_f32_16x16x32_bf16 v[18:21], v[154:157], v[210:213], v[18:21]
	v_mfma_f32_16x16x32_bf16 v[46:49], v[158:161], v[182:185], v[46:49]
	v_mfma_f32_16x16x32_bf16 v[38:41], v[166:169], v[182:185], v[38:41]
	v_mfma_f32_16x16x32_bf16 v[30:33], v[158:161], v[190:193], v[30:33]
	v_mfma_f32_16x16x32_bf16 v[22:25], v[166:169], v[190:193], v[22:25]
	v_mfma_f32_16x16x32_bf16 v[14:17], v[158:161], v[198:201], v[14:17]
	v_mfma_f32_16x16x32_bf16 v[10:13], v[166:169], v[198:201], v[10:13]
	v_mfma_f32_16x16x32_bf16 v[6:9], v[158:161], v[206:209], v[6:9]
	v_mfma_f32_16x16x32_bf16 v[2:5], v[166:169], v[206:209], v[2:5]
	v_mfma_f32_16x16x32_bf16 v[46:49], v[162:165], v[186:189], v[46:49]
	v_mfma_f32_16x16x32_bf16 v[38:41], v[178:181], v[186:189], v[38:41]
	v_mfma_f32_16x16x32_bf16 v[30:33], v[162:165], v[194:197], v[30:33]
	v_mfma_f32_16x16x32_bf16 v[22:25], v[178:181], v[194:197], v[22:25]
	v_mfma_f32_16x16x32_bf16 v[14:17], v[162:165], v[202:205], v[14:17]
	v_mfma_f32_16x16x32_bf16 v[10:13], v[178:181], v[202:205], v[10:13]
	v_mfma_f32_16x16x32_bf16 v[6:9], v[162:165], v[210:213], v[6:9]
	v_mfma_f32_16x16x32_bf16 v[2:5], v[178:181], v[210:213], v[2:5]
	s_setprio 0
	s_barrier
	s_add_i32 s38, s38, 2
	s_add_u32 s16, s16, 0x100
	s_addc_u32 s17, s17, 0
	s_add_u32 s36, s36, 0x100
	s_addc_u32 s37, s37, 0
	s_cmp_gt_u32 s38, 5
	s_cbranch_scc0 .LBB0_69
	s_and_b64 vcc, exec, s[10:11]
	s_cbranch_vccz .LBB0_72
	s_barrier

; #define PG8_STAGE(bufoff, gbase, voff) do { _Pragma("unroll") for (int _i = 0; _i < 2; ++_i) \
;         __builtin_amdgcn_global_load_lds((const unsigned*)((const char*)(gbase) + (voff)[_i]), (PG8_LAS unsigned*)(lds + (bufoff) + ldsw + _i * 8192), 16, 0, 0); } while (0)
; #define PG8_LDA(dst, b, h) do { _Pragma("unroll") for (int m = 0; m < 4; ++m) _Pragma("unroll") for (int k = 0; k < 2; ++k) dst[m][k] = *(const PG8_LAS bf16x8*)(lds + PG8_SA(b, h) + aoff + m * 2048 + k * 1024); } while (0)
; #define PG8_MMA(ai, bj, At, Bt) do { __builtin_amdgcn_s_setprio(1); _Pragma("unroll") for (int m = 0; m < 4; ++m) _Pragma("unroll") for (int n = 0; n < 2; ++n) _Pragma("unroll") for (int k = 0; k < 2; ++k) \
;         acc[ai][bj][m][n] = __builtin_amdgcn_mfma_f32_16x16x32_bf16(Bt[n][k], At[m][k], acc[ai][bj][m][n], 0, 0, 0); __builtin_amdgcn_s_setprio(0); } while (0)
; #define PG8_WAIT_V(n) asm volatile("s_waitcnt vmcnt(" #n ")" ::: "memory")
; #define PG8_WAIT_L(n) asm volatile("s_waitcnt lgkmcnt(" #n ")" ::: "memory")
; #define PG8_BAR __builtin_amdgcn_s_barrier()
; #define PG8_SCHED __builtin_amdgcn_sched_barrier(0)
; template <class Epi, class Sched, bool ALIGN_EPI = false, bool SP2 = false>
; __device__ __forceinline__ void gemm_phase(PG8_LAS unsigned char* lds, const Gemm g, const Sched& S, const Epi& E, const int wave_id) {
;     ...
;             PG8_WAIT_V(8); PG8_WAIT_L(0); PG8_BAR; PG8_MMA(0, 0, At, B0); PG8_MMA(0, 1, At, B1); PG8_BAR; PG8_SCHED;
;             PG8_LDA(At, 0, 1); PG8_STAGE(PG8_SB(0, 0), b2, voffB); PG8_STAGE(PG8_SB(0, 1), b2 + hstepB, voffB); PG8_STAGE(PG8_SA(0, 0), a2, voffA);
;             PG8_WAIT_V(8); PG8_WAIT_L(0); PG8_BAR; PG8_MMA(1, 0, At, B0); PG8_MMA(1, 1, At, B1); PG8_BAR; PG8_SCHED;
.Lrw_1:
	s_waitcnt lgkmcnt(0)
	s_barrier
	s_setprio 1
	v_mfma_f32_16x16x32_bf16 v[134:137], v[138:141], v[190:193], v[134:137]
	v_mfma_f32_16x16x32_bf16 v[130:133], v[146:149], v[190:193], v[130:133]
	v_mfma_f32_16x16x32_bf16 v[118:121], v[138:141], v[198:201], v[118:121]
	v_mfma_f32_16x16x32_bf16 v[114:117], v[146:149], v[198:201], v[114:117]
	v_mfma_f32_16x16x32_bf16 v[102:105], v[138:141], v[214:217], v[102:105]
	v_mfma_f32_16x16x32_bf16 v[98:101], v[146:149], v[214:217], v[98:101]
	v_mfma_f32_16x16x32_bf16 v[86:89], v[138:141], v[222:225], v[86:89]
	v_mfma_f32_16x16x32_bf16 v[82:85], v[146:149], v[222:225], v[82:85]
	v_mfma_f32_16x16x32_bf16 v[134:137], v[142:145], v[194:197], v[134:137]
	v_mfma_f32_16x16x32_bf16 v[130:133], v[150:153], v[194:197], v[130:133]
	v_mfma_f32_16x16x32_bf16 v[118:121], v[142:145], v[210:213], v[118:121]
	v_mfma_f32_16x16x32_bf16 v[114:117], v[150:153], v[210:213], v[114:117]
	v_mfma_f32_16x16x32_bf16 v[102:105], v[142:145], v[218:221], v[102:105]
	v_mfma_f32_16x16x32_bf16 v[98:101], v[150:153], v[218:221], v[98:101]
	v_mfma_f32_16x16x32_bf16 v[86:89], v[142:145], v[234:237], v[86:89]
	v_mfma_f32_16x16x32_bf16 v[82:85], v[150:153], v[234:237], v[82:85]
	v_mfma_f32_16x16x32_bf16 v[126:129], v[154:157], v[190:193], v[126:129]
	v_mfma_f32_16x16x32_bf16 v[122:125], v[162:165], v[190:193], v[122:125]
	v_mfma_f32_16x16x32_bf16 v[110:113], v[154:157], v[198:201], v[110:113]
	v_mfma_f32_16x16x32_bf16 v[106:109], v[162:165], v[198:201], v[106:109]
	v_mfma_f32_16x16x32_bf16 v[94:97], v[154:157], v[214:217], v[94:97]
	v_mfma_f32_16x16x32_bf16 v[90:93], v[162:165], v[214:217], v[90:93]
	v_mfma_f32_16x16x32_bf16 v[78:81], v[154:157], v[222:225], v[78:81]
	v_mfma_f32_16x16x32_bf16 v[74:77], v[162:165], v[222:225], v[74:77]
	v_mfma_f32_16x16x32_bf16 v[126:129], v[158:161], v[194:197], v[126:129]
	v_mfma_f32_16x16x32_bf16 v[122:125], v[166:169], v[194:197], v[122:125]
	v_mfma_f32_16x16x32_bf16 v[110:113], v[158:161], v[210:213], v[110:113]
	v_mfma_f32_16x16x32_bf16 v[106:109], v[166:169], v[210:213], v[106:109]
	v_mfma_f32_16x16x32_bf16 v[94:97], v[158:161], v[218:221], v[94:97]
	v_mfma_f32_16x16x32_bf16 v[90:93], v[166:169], v[218:221], v[90:93]
	v_mfma_f32_16x16x32_bf16 v[78:81], v[158:161], v[234:237], v[78:81]
	v_mfma_f32_16x16x32_bf16 v[74:77], v[166:169], v[234:237], v[74:77]
	s_setprio 0
	s_barrier
	s_add_i32 s10, s37, s15
	v_lshl_add_u64 v[240:241], s[28:29], 0, v[180:181]
	s_mov_b32 m0, s10
	ds_read_b128 v[190:193], v208 offset:16384
	ds_read_b128 v[194:197], v208 offset:17408
	ds_read_b128 v[198:201], v208 offset:18432
	ds_read_b128 v[210:213], v208 offset:19456
	ds_read_b128 v[214:217], v208 offset:20480
	ds_read_b128 v[218:221], v208 offset:21504
	ds_read_b128 v[222:225], v208 offset:22528
	ds_read_b128 v[234:237], v208 offset:23552
	global_load_lds_dwordx4 v[240:241], off
	s_add_i32 m0, s10, 0x2000
	s_add_u32 s10, s28, 0x40000
	v_lshl_add_u64 v[242:243], s[28:29], 0, v[184:185]
	s_addc_u32 s11, s29, 0
	s_add_i32 s37, s39, s15
	global_load_lds_dwordx4 v[242:243], off
	v_lshl_add_u64 v[244:245], s[10:11], 0, v[180:181]
	s_mov_b32 m0, s37
	v_lshl_add_u64 v[246:247], s[30:31], 0, v[182:183]
	global_load_lds_dwordx4 v[244:245], off
	v_lshl_add_u64 v[244:245], s[10:11], 0, v[184:185]
	s_add_i32 m0, s37, 0x2000
	s_nop 0
	global_load_lds_dwordx4 v[244:245], off
	v_lshl_add_u64 v[244:245], s[30:31], 0, v[178:179]
	s_mov_b32 m0, s27
	s_nop 0
	global_load_lds_dwordx4 v[244:245], off
	s_mov_b32 m0, s34
	s_nop 0
	global_load_lds_dwordx4 v[246:247], off
	s_waitcnt vmcnt(24)
	s_cmp_eq_u32 s98, 1
	s_cbranch_scc1 .Lrw_2
	s_waitcnt vmcnt(8)
.Lrw_2:
	s_mov_b32 s98, 0
	s_waitcnt lgkmcnt(0)
	s_barrier
	s_setprio 1
	v_mfma_f32_16x16x32_bf16 v[70:73], v[138:141], v[190:193], v[70:73]
	v_mfma_f32_16x16x32_bf16 v[66:69], v[146:149], v[190:193], v[66:69]
	v_mfma_f32_16x16x32_bf16 v[54:57], v[138:141], v[198:201], v[54:57]
	v_mfma_f32_16x16x32_bf16 v[50:53], v[146:149], v[198:201], v[50:53]
	v_mfma_f32_16x16x32_bf16 v[38:41], v[138:141], v[214:217], v[38:41]
	v_mfma_f32_16x16x32_bf16 v[34:37], v[146:149], v[214:217], v[34:37]
	v_mfma_f32_16x16x32_bf16 v[22:25], v[138:141], v[222:225], v[22:25]
	v_mfma_f32_16x16x32_bf16 v[18:21], v[146:149], v[222:225], v[18:21]
	v_mfma_f32_16x16x32_bf16 v[70:73], v[142:145], v[194:197], v[70:73]
	v_mfma_f32_16x16x32_bf16 v[66:69], v[150:153], v[194:197], v[66:69]
	v_mfma_f32_16x16x32_bf16 v[54:57], v[142:145], v[210:213], v[54:57]
	v_mfma_f32_16x16x32_bf16 v[50:53], v[150:153], v[210:213], v[50:53]
	v_mfma_f32_16x16x32_bf16 v[38:41], v[142:145], v[218:221], v[38:41]
	v_mfma_f32_16x16x32_bf16 v[34:37], v[150:153], v[218:221], v[34:37]
	v_mfma_f32_16x16x32_bf16 v[22:25], v[142:145], v[234:237], v[22:25]
	v_mfma_f32_16x16x32_bf16 v[18:21], v[150:153], v[234:237], v[18:21]
	v_mfma_f32_16x16x32_bf16 v[62:65], v[154:157], v[190:193], v[62:65]
	v_mfma_f32_16x16x32_bf16 v[58:61], v[162:165], v[190:193], v[58:61]
	v_mfma_f32_16x16x32_bf16 v[46:49], v[154:157], v[198:201], v[46:49]
	v_mfma_f32_16x16x32_bf16 v[42:45], v[162:165], v[198:201], v[42:45]
	v_mfma_f32_16x16x32_bf16 v[30:33], v[154:157], v[214:217], v[30:33]
	v_mfma_f32_16x16x32_bf16 v[26:29], v[162:165], v[214:217], v[26:29]
	v_mfma_f32_16x16x32_bf16 v[14:17], v[154:157], v[222:225], v[14:17]
	v_mfma_f32_16x16x32_bf16 v[10:13], v[162:165], v[222:225], v[10:13]
	v_mfma_f32_16x16x32_bf16 v[62:65], v[158:161], v[194:197], v[62:65]
	v_mfma_f32_16x16x32_bf16 v[58:61], v[166:169], v[194:197], v[58:61]
	v_mfma_f32_16x16x32_bf16 v[46:49], v[158:161], v[210:213], v[46:49]
	v_mfma_f32_16x16x32_bf16 v[42:45], v[166:169], v[210:213], v[42:45]
	v_mfma_f32_16x16x32_bf16 v[30:33], v[158:161], v[218:221], v[30:33]
	v_mfma_f32_16x16x32_bf16 v[26:29], v[166:169], v[218:221], v[26:29]
	v_mfma_f32_16x16x32_bf16 v[14:17], v[158:161], v[234:237], v[14:17]
	v_mfma_f32_16x16x32_bf16 v[10:13], v[166:169], v[234:237], v[10:13]
	s_setprio 0
	s_barrier
; #define PG8_STAGE(bufoff, gbase, voff) do { _Pragma("unroll") for (int _i = 0; _i < 2; ++_i) \
;         __builtin_amdgcn_global_load_lds((const unsigned*)((const char*)(gbase) + (voff)[_i]), (PG8_LAS unsigned*)(lds + (bufoff) + ldsw + _i * 8192), 16, 0, 0); } while (0)
; #define PG8_LDA(dst, b, h) do { _Pragma("unroll") for (int m = 0; m < 4; ++m) _Pragma("unroll") for (int k = 0; k < 2; ++k) dst[m][k] = *(const PG8_LAS bf16x8*)(lds + PG8_SA(b, h) + aoff + m * 2048 + k * 1024); } while (0)
; #define PG8_LDB(dst, b, h) do { _Pragma("unroll") for (int n = 0; n < 2; ++n) _Pragma("unroll") for (int k = 0; k < 2; ++k) dst[n][k] = *(const PG8_LAS bf16x8*)(lds + PG8_SB(b, h) + boff + n * 2048 + k * 1024); } while (0)
; #define PG8_MMA(ai, bj, At, Bt) do { __builtin_amdgcn_s_setprio(1); _Pragma("unroll") for (int m = 0; m < 4; ++m) _Pragma("unroll") for (int n = 0; n < 2; ++n) _Pragma("unroll") for (int k = 0; k < 2; ++k) \
;         acc[ai][bj][m][n] = __builtin_amdgcn_mfma_f32_16x16x32_bf16(Bt[n][k], At[m][k], acc[ai][bj][m][n], 0, 0, 0); __builtin_amdgcn_s_setprio(0); } while (0)
; #define PG8_WAIT_V(n) asm volatile("s_waitcnt vmcnt(" #n ")" ::: "memory")
; #define PG8_WAIT_L(n) asm volatile("s_waitcnt lgkmcnt(" #n ")" ::: "memory")
; #define PG8_BAR __builtin_amdgcn_s_barrier()
; #define PG8_SCHED __builtin_amdgcn_sched_barrier(0)
; template <class Epi, class Sched, bool ALIGN_EPI = false, bool SP2 = false>
; __device__ __forceinline__ void gemm_phase(PG8_LAS unsigned char* lds, const Gemm g, const Sched& S, const Epi& E, const int wave_id) {
;     ...
;             PG8_LDB(B0, 1, 0); PG8_LDB(B1, 1, 1); PG8_SCHED; PG8_LDA(At, 1, 0); PG8_STAGE(PG8_SA(0, 1), a2 + hstepA, voffA);
;             PG8_WAIT_V(8); PG8_WAIT_L(0); PG8_BAR; PG8_MMA(0, 0, At, B0); PG8_MMA(0, 1, At, B1); PG8_BAR; PG8_SCHED;
	s_add_i32 s37, 0, 0x18000
	v_add_u32_e32 v0, s37, v203
	s_add_i32 s39, 0, 0x1c000
	ds_read_b128 v[138:141], v0
	ds_read_b128 v[142:145], v0 offset:1024
	ds_read_b128 v[146:149], v0 offset:2048
	ds_read_b128 v[150:153], v0 offset:3072
	v_add_u32_e32 v0, s39, v203
	ds_read_b128 v[154:157], v0
	ds_read_b128 v[158:161], v0 offset:1024
	ds_read_b128 v[162:165], v0 offset:2048
	ds_read_b128 v[166:169], v0 offset:3072
	s_add_u32 s10, s30, 0x40000
	s_addc_u32 s11, s31, 0
	s_mov_b32 m0, s35
	v_lshl_add_u64 v[248:249], s[10:11], 0, v[178:179]
	ds_read_b128 v[190:193], v208 offset:32768
	ds_read_b128 v[194:197], v208 offset:33792
	ds_read_b128 v[198:201], v208 offset:34816
	ds_read_b128 v[210:213], v208 offset:35840
	ds_read_b128 v[214:217], v208 offset:36864
	ds_read_b128 v[218:221], v208 offset:37888
	ds_read_b128 v[222:225], v208 offset:38912
	ds_read_b128 v[234:237], v208 offset:39936
	global_load_lds_dwordx4 v[248:249], off
	v_lshl_add_u64 v[248:249], s[10:11], 0, v[182:183]
	s_mov_b32 m0, s36
	s_nop 0
	global_load_lds_dwordx4 v[248:249], off
	s_waitcnt vmcnt(8)
	s_waitcnt lgkmcnt(0)
	s_barrier
	s_setprio 1
	v_mfma_f32_16x16x32_bf16 v[134:137], v[138:141], v[190:193], v[134:137]
	v_mfma_f32_16x16x32_bf16 v[130:133], v[146:149], v[190:193], v[130:133]
	v_mfma_f32_16x16x32_bf16 v[118:121], v[138:141], v[198:201], v[118:121]
	v_mfma_f32_16x16x32_bf16 v[114:117], v[146:149], v[198:201], v[114:117]
	v_mfma_f32_16x16x32_bf16 v[102:105], v[138:141], v[214:217], v[102:105]
	v_mfma_f32_16x16x32_bf16 v[98:101], v[146:149], v[214:217], v[98:101]
	v_mfma_f32_16x16x32_bf16 v[86:89], v[138:141], v[222:225], v[86:89]
	v_mfma_f32_16x16x32_bf16 v[82:85], v[146:149], v[222:225], v[82:85]
	v_mfma_f32_16x16x32_bf16 v[134:137], v[142:145], v[194:197], v[134:137]
	v_mfma_f32_16x16x32_bf16 v[130:133], v[150:153], v[194:197], v[130:133]
	v_mfma_f32_16x16x32_bf16 v[118:121], v[142:145], v[210:213], v[118:121]
	v_mfma_f32_16x16x32_bf16 v[114:117], v[150:153], v[210:213], v[114:117]
	v_mfma_f32_16x16x32_bf16 v[102:105], v[142:145], v[218:221], v[102:105]
	v_mfma_f32_16x16x32_bf16 v[98:101], v[150:153], v[218:221], v[98:101]
	v_mfma_f32_16x16x32_bf16 v[86:89], v[142:145], v[234:237], v[86:89]
	v_mfma_f32_16x16x32_bf16 v[82:85], v[150:153], v[234:237], v[82:85]
	v_mfma_f32_16x16x32_bf16 v[126:129], v[154:157], v[190:193], v[126:129]
	v_mfma_f32_16x16x32_bf16 v[122:125], v[162:165], v[190:193], v[122:125]
	v_mfma_f32_16x16x32_bf16 v[110:113], v[154:157], v[198:201], v[110:113]
	v_mfma_f32_16x16x32_bf16 v[106:109], v[162:165], v[198:201], v[106:109]
	v_mfma_f32_16x16x32_bf16 v[94:97], v[154:157], v[214:217], v[94:97]
	v_mfma_f32_16x16x32_bf16 v[90:93], v[162:165], v[214:217], v[90:93]
	v_mfma_f32_16x16x32_bf16 v[78:81], v[154:157], v[222:225], v[78:81]
	v_mfma_f32_16x16x32_bf16 v[74:77], v[162:165], v[222:225], v[74:77]
	v_mfma_f32_16x16x32_bf16 v[126:129], v[158:161], v[194:197], v[126:129]
	v_mfma_f32_16x16x32_bf16 v[122:125], v[166:169], v[194:197], v[122:125]
	v_mfma_f32_16x16x32_bf16 v[110:113], v[158:161], v[210:213], v[110:113]
	v_mfma_f32_16x16x32_bf16 v[106:109], v[166:169], v[210:213], v[106:109]
	v_mfma_f32_16x16x32_bf16 v[94:97], v[158:161], v[218:221], v[94:97]
	v_mfma_f32_16x16x32_bf16 v[90:93], v[166:169], v[218:221], v[90:93]
	v_mfma_f32_16x16x32_bf16 v[78:81], v[158:161], v[234:237], v[78:81]
	v_mfma_f32_16x16x32_bf16 v[74:77], v[166:169], v[234:237], v[74:77]
	s_setprio 0
	s_barrier
; #define PG8_STAGE(bufoff, gbase, voff) do { _Pragma("unroll") for (int _i = 0; _i < 2; ++_i) \
;         __builtin_amdgcn_global_load_lds((const unsigned*)((const char*)(gbase) + (voff)[_i]), (PG8_LAS unsigned*)(lds + (bufoff) + ldsw + _i * 8192), 16, 0, 0); } while (0)
; #define PG8_LDA(dst, b, h) do { _Pragma("unroll") for (int m = 0; m < 4; ++m) _Pragma("unroll") for (int k = 0; k < 2; ++k) dst[m][k] = *(const PG8_LAS bf16x8*)(lds + PG8_SA(b, h) + aoff + m * 2048 + k * 1024); } while (0)
; #define PG8_MMA(ai, bj, At, Bt) do { __builtin_amdgcn_s_setprio(1); _Pragma("unroll") for (int m = 0; m < 4; ++m) _Pragma("unroll") for (int n = 0; n < 2; ++n) _Pragma("unroll") for (int k = 0; k < 2; ++k) \
;         acc[ai][bj][m][n] = __builtin_amdgcn_mfma_f32_16x16x32_bf16(Bt[n][k], At[m][k], acc[ai][bj][m][n], 0, 0, 0); __builtin_amdgcn_s_setprio(0); } while (0)
; #define PG8_WAIT_V(n) asm volatile("s_waitcnt vmcnt(" #n ")" ::: "memory")
; #define PG8_WAIT_L(n) asm volatile("s_waitcnt lgkmcnt(" #n ")" ::: "memory")
; #define PG8_BAR __builtin_amdgcn_s_barrier()
; #define PG8_SCHED __builtin_amdgcn_sched_barrier(0)
; template <class Epi, class Sched, bool ALIGN_EPI = false, bool SP2 = false>
; __device__ __forceinline__ void gemm_phase(PG8_LAS unsigned char* lds, const Gemm g, const Sched& S, const Epi& E, const int wave_id) {
;     ...
;         for (int t = 0; t < nt; t += 2) {
;             const bool last = (t == nt - 2);
;     ...
;             PG8_LDA(At, 1, 1); PG8_STAGE(PG8_SB(1, 0), b3, voffB); PG8_STAGE(PG8_SB(1, 1), b3 + hstepB, voffB); PG8_STAGE(PG8_SA(1, 0), a3, voffA);
;             PG8_WAIT_V(8); PG8_WAIT_L(0); PG8_BAR; PG8_MMA(1, 0, At, B0); PG8_MMA(1, 1, At, B1); PG8_BAR; PG8_SCHED;
	s_add_i32 s10, s37, s15
	v_lshl_add_u64 v[240:241], v[240:241], 0, s[62:63]
	s_mov_b32 m0, s10
	ds_read_b128 v[190:193], v208 offset:49152
	ds_read_b128 v[194:197], v208 offset:50176
	ds_read_b128 v[198:201], v208 offset:51200
	ds_read_b128 v[210:213], v208 offset:52224
	ds_read_b128 v[214:217], v208 offset:53248
	ds_read_b128 v[218:221], v208 offset:54272
	ds_read_b128 v[222:225], v208 offset:55296
	ds_read_b128 v[234:237], v208 offset:56320
	global_load_lds_dwordx4 v[240:241], off
	s_add_i32 m0, s10, 0x2000
	s_add_u32 s10, s28, 0x40080
	v_lshl_add_u64 v[240:241], v[242:243], 0, s[62:63]
	s_addc_u32 s11, s29, 0
	s_add_i32 s28, s39, s15
	global_load_lds_dwordx4 v[240:241], off
	v_lshl_add_u64 v[240:241], s[10:11], 0, v[180:181]
	s_mov_b32 m0, s28
	s_nop 0
	global_load_lds_dwordx4 v[240:241], off
	v_lshl_add_u64 v[240:241], s[10:11], 0, v[184:185]
	s_add_i32 m0, s28, 0x2000
	s_nop 0
	global_load_lds_dwordx4 v[240:241], off
	v_lshl_add_u64 v[240:241], v[244:245], 0, s[62:63]
	s_mov_b32 m0, s76
	s_nop 0
	global_load_lds_dwordx4 v[240:241], off
	v_lshl_add_u64 v[240:241], v[246:247], 0, s[62:63]
	s_mov_b32 m0, s77
	s_nop 0
	global_load_lds_dwordx4 v[240:241], off
	s_waitcnt vmcnt(8)
	s_waitcnt lgkmcnt(0)
	s_barrier
	s_setprio 1
	v_mfma_f32_16x16x32_bf16 v[70:73], v[138:141], v[190:193], v[70:73]
	v_mfma_f32_16x16x32_bf16 v[66:69], v[146:149], v[190:193], v[66:69]
	v_mfma_f32_16x16x32_bf16 v[54:57], v[138:141], v[198:201], v[54:57]
	v_mfma_f32_16x16x32_bf16 v[50:53], v[146:149], v[198:201], v[50:53]
	v_mfma_f32_16x16x32_bf16 v[38:41], v[138:141], v[214:217], v[38:41]
	v_mfma_f32_16x16x32_bf16 v[34:37], v[146:149], v[214:217], v[34:37]
	v_mfma_f32_16x16x32_bf16 v[22:25], v[138:141], v[222:225], v[22:25]
	v_mfma_f32_16x16x32_bf16 v[18:21], v[146:149], v[222:225], v[18:21]
	v_mfma_f32_16x16x32_bf16 v[70:73], v[142:145], v[194:197], v[70:73]
	v_mfma_f32_16x16x32_bf16 v[66:69], v[150:153], v[194:197], v[66:69]
	v_mfma_f32_16x16x32_bf16 v[54:57], v[142:145], v[210:213], v[54:57]
	v_mfma_f32_16x16x32_bf16 v[50:53], v[150:153], v[210:213], v[50:53]
	v_mfma_f32_16x16x32_bf16 v[38:41], v[142:145], v[218:221], v[38:41]
	v_mfma_f32_16x16x32_bf16 v[34:37], v[150:153], v[218:221], v[34:37]
	v_mfma_f32_16x16x32_bf16 v[22:25], v[142:145], v[234:237], v[22:25]
	v_mfma_f32_16x16x32_bf16 v[18:21], v[150:153], v[234:237], v[18:21]
	v_mfma_f32_16x16x32_bf16 v[62:65], v[154:157], v[190:193], v[62:65]
	v_mfma_f32_16x16x32_bf16 v[58:61], v[162:165], v[190:193], v[58:61]
	v_mfma_f32_16x16x32_bf16 v[46:49], v[154:157], v[198:201], v[46:49]
	v_mfma_f32_16x16x32_bf16 v[42:45], v[162:165], v[198:201], v[42:45]
	v_mfma_f32_16x16x32_bf16 v[30:33], v[154:157], v[214:217], v[30:33]
	v_mfma_f32_16x16x32_bf16 v[26:29], v[162:165], v[214:217], v[26:29]
	v_mfma_f32_16x16x32_bf16 v[14:17], v[154:157], v[222:225], v[14:17]
	v_mfma_f32_16x16x32_bf16 v[10:13], v[162:165], v[222:225], v[10:13]
	v_mfma_f32_16x16x32_bf16 v[62:65], v[158:161], v[194:197], v[62:65]
	v_mfma_f32_16x16x32_bf16 v[58:61], v[166:169], v[194:197], v[58:61]
	v_mfma_f32_16x16x32_bf16 v[46:49], v[158:161], v[210:213], v[46:49]
	v_mfma_f32_16x16x32_bf16 v[42:45], v[166:169], v[210:213], v[42:45]
	v_mfma_f32_16x16x32_bf16 v[30:33], v[158:161], v[218:221], v[30:33]
	v_mfma_f32_16x16x32_bf16 v[26:29], v[166:169], v[218:221], v[26:29]
	v_mfma_f32_16x16x32_bf16 v[14:17], v[158:161], v[234:237], v[14:17]
	v_mfma_f32_16x16x32_bf16 v[10:13], v[166:169], v[234:237], v[10:13]
	s_setprio 0
	s_barrier
	s_add_i32 s5, s5, 2
	s_add_u32 s8, s8, 0x100
	s_addc_u32 s9, s9, 0
	s_add_u32 s38, s38, 0x100
	s_addc_u32 s4, s4, 0
	s_cmp_gt_u32 s5, 13
	s_cbranch_scc0 .LBB0_90

; #define PG8_STAGE(bufoff, gbase, voff) do { _Pragma("unroll") for (int _i = 0; _i < 2; ++_i) \
;         __builtin_amdgcn_global_load_lds((const unsigned*)((const char*)(gbase) + (voff)[_i]), (PG8_LAS unsigned*)(lds + (bufoff) + ldsw + _i * 8192), 16, 0, 0); } while (0)
; #define PG8_LDA(dst, b, h) do { _Pragma("unroll") for (int m = 0; m < 4; ++m) _Pragma("unroll") for (int k = 0; k < 2; ++k) dst[m][k] = *(const PG8_LAS bf16x8*)(lds + PG8_SA(b, h) + aoff + m * 2048 + k * 1024); } while (0)
; #define PG8_LDB(dst, b, h) do { _Pragma("unroll") for (int n = 0; n < 2; ++n) _Pragma("unroll") for (int k = 0; k < 2; ++k) dst[n][k] = *(const PG8_LAS bf16x8*)(lds + PG8_SB(b, h) + boff + n * 2048 + k * 1024); } while (0)
; #define PG8_MMA(ai, bj, At, Bt) do { __builtin_amdgcn_s_setprio(1); _Pragma("unroll") for (int m = 0; m < 4; ++m) _Pragma("unroll") for (int n = 0; n < 2; ++n) _Pragma("unroll") for (int k = 0; k < 2; ++k) \
;         acc[ai][bj][m][n] = __builtin_amdgcn_mfma_f32_16x16x32_bf16(Bt[n][k], At[m][k], acc[ai][bj][m][n], 0, 0, 0); __builtin_amdgcn_s_setprio(0); } while (0)
; #define PG8_WAIT_V(n) asm volatile("s_waitcnt vmcnt(" #n ")" ::: "memory")
; #define PG8_WAIT_L(n) asm volatile("s_waitcnt lgkmcnt(" #n ")" ::: "memory")
; #define PG8_BAR __builtin_amdgcn_s_barrier()
; template <class Epi, class Sched, bool ALIGN_EPI = false, bool SP2 = false>
; __device__ __forceinline__ void gemm_phase(PG8_LAS unsigned char* lds, const Gemm g, const Sched& S, const Epi& E, const int wave_id) {
;     ...
;             const char* a1 = cA + (size_t)(t + 1) * kstep;
;             const char* a2 = last ? nA : cA + (size_t)(t + 2) * kstep; const char* b2 = last ? nB : cB + (size_t)(t + 2) * kstep;
;             const char* a3 = a2 + kstep; const char* b3 = b2 + kstep;
;             if (last && has_next) S.a_ready(nxt);
;             if constexpr (SP2) {
;             PG8_LDB(B0, 0, 0); PG8_LDB(B1, 0, 1); PG8_SCHED; PG8_LDA(At, 0, 0); PG8_STAGE(PG8_SA(1, 1), a1 + hstepA, voffA);
;             PG8_WAIT_V(8); PG8_WAIT_L(0); PG8_BAR; PG8_MMA(0, 0, At, B0); PG8_MMA(0, 1, At, B1); PG8_BAR; PG8_SCHED;
;             PG8_LDA(At, 0, 1); PG8_STAGE(PG8_SB(0, 0), b2, voffB); PG8_STAGE(PG8_SB(0, 1), b2 + hstepB, voffB); PG8_STAGE(PG8_SA(0, 0), a2, voffA);
;             PG8_WAIT_V(8); PG8_WAIT_L(0); PG8_BAR; PG8_MMA(1, 0, At, B0); PG8_MMA(1, 1, At, B1); PG8_BAR; PG8_SCHED;
.LBB0_189:
	s_add_u32 s10, s12, 0x100
	s_addc_u32 s11, s13, 0
	s_add_i32 s39, 0, 0x10000
	s_cmp_eq_u32 vcc_lo, 28
	s_cselect_b32 s31, s25, s11
	s_cselect_b32 s30, s24, s10
	v_add_u32_e32 v0, s39, v206
	s_cselect_b32 s29, s23, s91
	s_cselect_b32 s28, s87, s38
	s_add_i32 vcc_hi, 0, 0x14000
	ds_read_b128 v[122:125], v0
	ds_read_b128 v[134:137], v0 offset:1024
	ds_read_b128 v[138:141], v0 offset:2048
	ds_read_b128 v[142:145], v0 offset:3072
	v_add_u32_e32 v0, vcc_hi, v206
	ds_read_b128 v[146:149], v0
	ds_read_b128 v[150:153], v0 offset:1024
	ds_read_b128 v[154:157], v0 offset:2048
	ds_read_b128 v[158:161], v0 offset:3072
	v_lshl_add_u64 v[222:223], s[12:13], 0, v[178:179]
	s_add_i32 m0, s17, 0xc000
	ds_read_b128 v[182:185], v212
	ds_read_b128 v[186:189], v212 offset:1024
	ds_read_b128 v[190:193], v212 offset:2048
	ds_read_b128 v[194:197], v212 offset:3072
	ds_read_b128 v[198:201], v212 offset:4096
	ds_read_b128 v[202:205], v212 offset:5120
	ds_read_b128 v[214:217], v212 offset:6144
	ds_read_b128 v[218:221], v212 offset:7168
	global_load_lds_dwordx4 v[222:223], off
	v_lshl_add_u64 v[222:223], s[12:13], 0, v[180:181]
	s_add_i32 m0, s17, 0xe000
	s_nop 0
	global_load_lds_dwordx4 v[222:223], off
	s_waitcnt vmcnt(8)
	s_waitcnt lgkmcnt(0)
	s_barrier
	s_setprio 1
	v_mfma_f32_16x16x32_bf16 v[130:133], v[122:125], v[182:185], v[130:133]
	v_mfma_f32_16x16x32_bf16 v[126:129], v[138:141], v[182:185], v[126:129]
	v_mfma_f32_16x16x32_bf16 v[110:113], v[122:125], v[190:193], v[110:113]
	v_mfma_f32_16x16x32_bf16 v[106:109], v[138:141], v[190:193], v[106:109]
	v_mfma_f32_16x16x32_bf16 v[94:97], v[122:125], v[198:201], v[94:97]
	v_mfma_f32_16x16x32_bf16 v[90:93], v[138:141], v[198:201], v[90:93]
	v_mfma_f32_16x16x32_bf16 v[78:81], v[122:125], v[214:217], v[78:81]
	v_mfma_f32_16x16x32_bf16 v[74:77], v[138:141], v[214:217], v[74:77]
	v_mfma_f32_16x16x32_bf16 v[130:133], v[134:137], v[186:189], v[130:133]
	v_mfma_f32_16x16x32_bf16 v[126:129], v[142:145], v[186:189], v[126:129]
	v_mfma_f32_16x16x32_bf16 v[110:113], v[134:137], v[194:197], v[110:113]
	v_mfma_f32_16x16x32_bf16 v[106:109], v[142:145], v[194:197], v[106:109]
	v_mfma_f32_16x16x32_bf16 v[94:97], v[134:137], v[202:205], v[94:97]
	v_mfma_f32_16x16x32_bf16 v[90:93], v[142:145], v[202:205], v[90:93]
	v_mfma_f32_16x16x32_bf16 v[78:81], v[134:137], v[218:221], v[78:81]
	v_mfma_f32_16x16x32_bf16 v[74:77], v[142:145], v[218:221], v[74:77]
	v_mfma_f32_16x16x32_bf16 v[118:121], v[146:149], v[182:185], v[118:121]
	v_mfma_f32_16x16x32_bf16 v[114:117], v[154:157], v[182:185], v[114:117]
	v_mfma_f32_16x16x32_bf16 v[102:105], v[146:149], v[190:193], v[102:105]
	v_mfma_f32_16x16x32_bf16 v[98:101], v[154:157], v[190:193], v[98:101]
	v_mfma_f32_16x16x32_bf16 v[86:89], v[146:149], v[198:201], v[86:89]
	v_mfma_f32_16x16x32_bf16 v[82:85], v[154:157], v[198:201], v[82:85]
	v_mfma_f32_16x16x32_bf16 v[70:73], v[146:149], v[214:217], v[70:73]
	v_mfma_f32_16x16x32_bf16 v[66:69], v[154:157], v[214:217], v[66:69]
	v_mfma_f32_16x16x32_bf16 v[118:121], v[150:153], v[186:189], v[118:121]
	v_mfma_f32_16x16x32_bf16 v[114:117], v[158:161], v[186:189], v[114:117]
	v_mfma_f32_16x16x32_bf16 v[102:105], v[150:153], v[194:197], v[102:105]
	v_mfma_f32_16x16x32_bf16 v[98:101], v[158:161], v[194:197], v[98:101]
	v_mfma_f32_16x16x32_bf16 v[86:89], v[150:153], v[202:205], v[86:89]
	v_mfma_f32_16x16x32_bf16 v[82:85], v[158:161], v[202:205], v[82:85]
	v_mfma_f32_16x16x32_bf16 v[70:73], v[150:153], v[218:221], v[70:73]
	v_mfma_f32_16x16x32_bf16 v[66:69], v[158:161], v[218:221], v[66:69]
	s_setprio 0
	s_barrier
	s_add_i32 s12, s39, s35
	v_lshl_add_u64 v[222:223], s[28:29], 0, v[164:165]
	s_mov_b32 m0, s12
	ds_read_b128 v[182:185], v212 offset:16384
	ds_read_b128 v[186:189], v212 offset:17408
	ds_read_b128 v[190:193], v212 offset:18432
	ds_read_b128 v[194:197], v212 offset:19456
	ds_read_b128 v[198:201], v212 offset:20480
	ds_read_b128 v[202:205], v212 offset:21504
	ds_read_b128 v[214:217], v212 offset:22528
	ds_read_b128 v[218:221], v212 offset:23552
	global_load_lds_dwordx4 v[222:223], off
	s_add_i32 m0, s12, 0x2000
	s_add_u32 s12, s28, 0x80000
	v_lshl_add_u64 v[224:225], s[28:29], 0, v[168:169]
	s_addc_u32 s13, s29, 0
	s_add_i32 s39, vcc_hi, s35
	global_load_lds_dwordx4 v[224:225], off
	v_lshl_add_u64 v[234:235], s[12:13], 0, v[164:165]
	s_mov_b32 m0, s39
	v_lshl_add_u64 v[236:237], s[30:31], 0, v[166:167]
	global_load_lds_dwordx4 v[234:235], off
	v_lshl_add_u64 v[234:235], s[12:13], 0, v[168:169]
	s_add_i32 m0, s39, 0x2000
	s_nop 0
	global_load_lds_dwordx4 v[234:235], off
	v_lshl_add_u64 v[234:235], s[30:31], 0, v[162:163]
	s_mov_b32 m0, s17
	s_nop 0
	global_load_lds_dwordx4 v[234:235], off
	s_mov_b32 m0, s36
	s_nop 0
	global_load_lds_dwordx4 v[236:237], off
	s_waitcnt vmcnt(8)
	s_waitcnt lgkmcnt(0)
	s_barrier
; #define PG8_STAGE(bufoff, gbase, voff) do { _Pragma("unroll") for (int _i = 0; _i < 2; ++_i) \
;         __builtin_amdgcn_global_load_lds((const unsigned*)((const char*)(gbase) + (voff)[_i]), (PG8_LAS unsigned*)(lds + (bufoff) + ldsw + _i * 8192), 16, 0, 0); } while (0)
; #define PG8_LDA(dst, b, h) do { _Pragma("unroll") for (int m = 0; m < 4; ++m) _Pragma("unroll") for (int k = 0; k < 2; ++k) dst[m][k] = *(const PG8_LAS bf16x8*)(lds + PG8_SA(b, h) + aoff + m * 2048 + k * 1024); } while (0)
; #define PG8_LDB(dst, b, h) do { _Pragma("unroll") for (int n = 0; n < 2; ++n) _Pragma("unroll") for (int k = 0; k < 2; ++k) dst[n][k] = *(const PG8_LAS bf16x8*)(lds + PG8_SB(b, h) + boff + n * 2048 + k * 1024); } while (0)
; #define PG8_MMA(ai, bj, At, Bt) do { __builtin_amdgcn_s_setprio(1); _Pragma("unroll") for (int m = 0; m < 4; ++m) _Pragma("unroll") for (int n = 0; n < 2; ++n) _Pragma("unroll") for (int k = 0; k < 2; ++k) \
;         acc[ai][bj][m][n] = __builtin_amdgcn_mfma_f32_16x16x32_bf16(Bt[n][k], At[m][k], acc[ai][bj][m][n], 0, 0, 0); __builtin_amdgcn_s_setprio(0); } while (0)
; #define PG8_WAIT_V(n) asm volatile("s_waitcnt vmcnt(" #n ")" ::: "memory")
; #define PG8_WAIT_L(n) asm volatile("s_waitcnt lgkmcnt(" #n ")" ::: "memory")
; #define PG8_BAR __builtin_amdgcn_s_barrier()
; #define PG8_SCHED __builtin_amdgcn_sched_barrier(0)
; template <class Epi, class Sched, bool ALIGN_EPI = false, bool SP2 = false>
; __device__ __forceinline__ void gemm_phase(PG8_LAS unsigned char* lds, const Gemm g, const Sched& S, const Epi& E, const int wave_id) {
;     ...
;             PG8_WAIT_V(8); PG8_WAIT_L(0); PG8_BAR; PG8_MMA(1, 0, At, B0); PG8_MMA(1, 1, At, B1); PG8_BAR; PG8_SCHED;
;             PG8_LDB(B0, 1, 0); PG8_LDB(B1, 1, 1); PG8_SCHED; PG8_LDA(At, 1, 0); PG8_STAGE(PG8_SA(0, 1), a2 + hstepA, voffA);
;             PG8_WAIT_V(8); PG8_WAIT_L(0); PG8_BAR; PG8_MMA(0, 0, At, B0); PG8_MMA(0, 1, At, B1); PG8_BAR; PG8_SCHED;
	s_setprio 1
	v_mfma_f32_16x16x32_bf16 v[62:65], v[122:125], v[182:185], v[62:65]
	v_mfma_f32_16x16x32_bf16 v[58:61], v[138:141], v[182:185], v[58:61]
	v_mfma_f32_16x16x32_bf16 v[46:49], v[122:125], v[190:193], v[46:49]
	v_mfma_f32_16x16x32_bf16 v[42:45], v[138:141], v[190:193], v[42:45]
	v_mfma_f32_16x16x32_bf16 v[30:33], v[122:125], v[198:201], v[30:33]
	v_mfma_f32_16x16x32_bf16 v[26:29], v[138:141], v[198:201], v[26:29]
	v_mfma_f32_16x16x32_bf16 v[14:17], v[122:125], v[214:217], v[14:17]
	v_mfma_f32_16x16x32_bf16 v[10:13], v[138:141], v[214:217], v[10:13]
	v_mfma_f32_16x16x32_bf16 v[62:65], v[134:137], v[186:189], v[62:65]
	v_mfma_f32_16x16x32_bf16 v[58:61], v[142:145], v[186:189], v[58:61]
	v_mfma_f32_16x16x32_bf16 v[46:49], v[134:137], v[194:197], v[46:49]
	v_mfma_f32_16x16x32_bf16 v[42:45], v[142:145], v[194:197], v[42:45]
	v_mfma_f32_16x16x32_bf16 v[30:33], v[134:137], v[202:205], v[30:33]
	v_mfma_f32_16x16x32_bf16 v[26:29], v[142:145], v[202:205], v[26:29]
	v_mfma_f32_16x16x32_bf16 v[14:17], v[134:137], v[218:221], v[14:17]
	v_mfma_f32_16x16x32_bf16 v[10:13], v[142:145], v[218:221], v[10:13]
	v_mfma_f32_16x16x32_bf16 v[54:57], v[146:149], v[182:185], v[54:57]
	v_mfma_f32_16x16x32_bf16 v[50:53], v[154:157], v[182:185], v[50:53]
	v_mfma_f32_16x16x32_bf16 v[38:41], v[146:149], v[190:193], v[38:41]
	v_mfma_f32_16x16x32_bf16 v[34:37], v[154:157], v[190:193], v[34:37]
	v_mfma_f32_16x16x32_bf16 v[22:25], v[146:149], v[198:201], v[22:25]
	v_mfma_f32_16x16x32_bf16 v[18:21], v[154:157], v[198:201], v[18:21]
	v_mfma_f32_16x16x32_bf16 v[6:9], v[146:149], v[214:217], v[6:9]
	v_mfma_f32_16x16x32_bf16 v[2:5], v[154:157], v[214:217], v[2:5]
	v_mfma_f32_16x16x32_bf16 v[54:57], v[150:153], v[186:189], v[54:57]
	v_mfma_f32_16x16x32_bf16 v[50:53], v[158:161], v[186:189], v[50:53]
	v_mfma_f32_16x16x32_bf16 v[38:41], v[150:153], v[194:197], v[38:41]
	v_mfma_f32_16x16x32_bf16 v[34:37], v[158:161], v[194:197], v[34:37]
	v_mfma_f32_16x16x32_bf16 v[22:25], v[150:153], v[202:205], v[22:25]
	v_mfma_f32_16x16x32_bf16 v[18:21], v[158:161], v[202:205], v[18:21]
	v_mfma_f32_16x16x32_bf16 v[6:9], v[150:153], v[218:221], v[6:9]
	v_mfma_f32_16x16x32_bf16 v[2:5], v[158:161], v[218:221], v[2:5]
	s_setprio 0
	s_barrier
	s_add_i32 s39, 0, 0x18000
	v_add_u32_e32 v0, s39, v206
	s_add_i32 vcc_hi, 0, 0x1c000
	ds_read_b128 v[122:125], v0
	ds_read_b128 v[134:137], v0 offset:1024
	ds_read_b128 v[138:141], v0 offset:2048
	ds_read_b128 v[142:145], v0 offset:3072
	v_add_u32_e32 v0, vcc_hi, v206
	ds_read_b128 v[146:149], v0
	ds_read_b128 v[150:153], v0 offset:1024
	ds_read_b128 v[154:157], v0 offset:2048
	ds_read_b128 v[158:161], v0 offset:3072
	s_add_u32 s12, s30, 0x180000
	s_addc_u32 s13, s31, 0
	s_mov_b32 m0, s37
	v_lshl_add_u64 v[240:241], s[12:13], 0, v[162:163]
	ds_read_b128 v[182:185], v212 offset:32768
	ds_read_b128 v[186:189], v212 offset:33792
	ds_read_b128 v[190:193], v212 offset:34816
	ds_read_b128 v[194:197], v212 offset:35840
	ds_read_b128 v[198:201], v212 offset:36864
	ds_read_b128 v[202:205], v212 offset:37888
	ds_read_b128 v[214:217], v212 offset:38912
	ds_read_b128 v[218:221], v212 offset:39936
	global_load_lds_dwordx4 v[240:241], off
	v_lshl_add_u64 v[240:241], s[12:13], 0, v[166:167]
	s_mov_b32 m0, s76
	s_nop 0
	global_load_lds_dwordx4 v[240:241], off
	s_waitcnt vmcnt(8)
	s_waitcnt lgkmcnt(0)
	s_barrier
	s_setprio 1
	v_mfma_f32_16x16x32_bf16 v[130:133], v[122:125], v[182:185], v[130:133]
	v_mfma_f32_16x16x32_bf16 v[126:129], v[138:141], v[182:185], v[126:129]
	v_mfma_f32_16x16x32_bf16 v[110:113], v[122:125], v[190:193], v[110:113]
	v_mfma_f32_16x16x32_bf16 v[106:109], v[138:141], v[190:193], v[106:109]
	v_mfma_f32_16x16x32_bf16 v[94:97], v[122:125], v[198:201], v[94:97]
	v_mfma_f32_16x16x32_bf16 v[90:93], v[138:141], v[198:201], v[90:93]
	v_mfma_f32_16x16x32_bf16 v[78:81], v[122:125], v[214:217], v[78:81]
	v_mfma_f32_16x16x32_bf16 v[74:77], v[138:141], v[214:217], v[74:77]
	v_mfma_f32_16x16x32_bf16 v[130:133], v[134:137], v[186:189], v[130:133]
	v_mfma_f32_16x16x32_bf16 v[126:129], v[142:145], v[186:189], v[126:129]
	v_mfma_f32_16x16x32_bf16 v[110:113], v[134:137], v[194:197], v[110:113]
	v_mfma_f32_16x16x32_bf16 v[106:109], v[142:145], v[194:197], v[106:109]
	v_mfma_f32_16x16x32_bf16 v[94:97], v[134:137], v[202:205], v[94:97]
	v_mfma_f32_16x16x32_bf16 v[90:93], v[142:145], v[202:205], v[90:93]
	v_mfma_f32_16x16x32_bf16 v[78:81], v[134:137], v[218:221], v[78:81]
	v_mfma_f32_16x16x32_bf16 v[74:77], v[142:145], v[218:221], v[74:77]
	v_mfma_f32_16x16x32_bf16 v[118:121], v[146:149], v[182:185], v[118:121]
	v_mfma_f32_16x16x32_bf16 v[114:117], v[154:157], v[182:185], v[114:117]
	v_mfma_f32_16x16x32_bf16 v[102:105], v[146:149], v[190:193], v[102:105]
	v_mfma_f32_16x16x32_bf16 v[98:101], v[154:157], v[190:193], v[98:101]
	v_mfma_f32_16x16x32_bf16 v[86:89], v[146:149], v[198:201], v[86:89]
	v_mfma_f32_16x16x32_bf16 v[82:85], v[154:157], v[198:201], v[82:85]
	v_mfma_f32_16x16x32_bf16 v[70:73], v[146:149], v[214:217], v[70:73]
	v_mfma_f32_16x16x32_bf16 v[66:69], v[154:157], v[214:217], v[66:69]
	v_mfma_f32_16x16x32_bf16 v[118:121], v[150:153], v[186:189], v[118:121]
	v_mfma_f32_16x16x32_bf16 v[114:117], v[158:161], v[186:189], v[114:117]
	v_mfma_f32_16x16x32_bf16 v[102:105], v[150:153], v[194:197], v[102:105]
	v_mfma_f32_16x16x32_bf16 v[98:101], v[158:161], v[194:197], v[98:101]
	v_mfma_f32_16x16x32_bf16 v[86:89], v[150:153], v[202:205], v[86:89]
	v_mfma_f32_16x16x32_bf16 v[82:85], v[158:161], v[202:205], v[82:85]
	v_mfma_f32_16x16x32_bf16 v[70:73], v[150:153], v[218:221], v[70:73]
	v_mfma_f32_16x16x32_bf16 v[66:69], v[158:161], v[218:221], v[66:69]
	s_setprio 0
	s_barrier
; #define PG8_STAGE(bufoff, gbase, voff) do { _Pragma("unroll") for (int _i = 0; _i < 2; ++_i) \
;         __builtin_amdgcn_global_load_lds((const unsigned*)((const char*)(gbase) + (voff)[_i]), (PG8_LAS unsigned*)(lds + (bufoff) + ldsw + _i * 8192), 16, 0, 0); } while (0)
; #define PG8_LDA(dst, b, h) do { _Pragma("unroll") for (int m = 0; m < 4; ++m) _Pragma("unroll") for (int k = 0; k < 2; ++k) dst[m][k] = *(const PG8_LAS bf16x8*)(lds + PG8_SA(b, h) + aoff + m * 2048 + k * 1024); } while (0)
; #define PG8_MMA(ai, bj, At, Bt) do { __builtin_amdgcn_s_setprio(1); _Pragma("unroll") for (int m = 0; m < 4; ++m) _Pragma("unroll") for (int n = 0; n < 2; ++n) _Pragma("unroll") for (int k = 0; k < 2; ++k) \
;         acc[ai][bj][m][n] = __builtin_amdgcn_mfma_f32_16x16x32_bf16(Bt[n][k], At[m][k], acc[ai][bj][m][n], 0, 0, 0); __builtin_amdgcn_s_setprio(0); } while (0)
; #define PG8_WAIT_V(n) asm volatile("s_waitcnt vmcnt(" #n ")" ::: "memory")
; #define PG8_WAIT_L(n) asm volatile("s_waitcnt lgkmcnt(" #n ")" ::: "memory")
; #define PG8_BAR __builtin_amdgcn_s_barrier()
; #define PG8_SCHED __builtin_amdgcn_sched_barrier(0)
; template <class Epi, class Sched, bool ALIGN_EPI = false, bool SP2 = false>
; __device__ __forceinline__ void gemm_phase(PG8_LAS unsigned char* lds, const Gemm g, const Sched& S, const Epi& E, const int wave_id) {
;     ...
;         for (int t = 0; t < nt; t += 2) {
;             const bool last = (t == nt - 2);
;     ...
;             PG8_LDA(At, 1, 1); PG8_STAGE(PG8_SB(1, 0), b3, voffB); PG8_STAGE(PG8_SB(1, 1), b3 + hstepB, voffB); PG8_STAGE(PG8_SA(1, 0), a3, voffA);
;             PG8_WAIT_V(8); PG8_WAIT_L(0); PG8_BAR; PG8_MMA(1, 0, At, B0); PG8_MMA(1, 1, At, B1); PG8_BAR; PG8_SCHED;
	s_add_i32 s12, s39, s35
	v_lshl_add_u64 v[222:223], v[222:223], 0, s[62:63]
	s_mov_b32 m0, s12
	ds_read_b128 v[182:185], v212 offset:49152
	ds_read_b128 v[186:189], v212 offset:50176
	ds_read_b128 v[190:193], v212 offset:51200
	ds_read_b128 v[194:197], v212 offset:52224
	ds_read_b128 v[198:201], v212 offset:53248
	ds_read_b128 v[202:205], v212 offset:54272
	ds_read_b128 v[214:217], v212 offset:55296
	ds_read_b128 v[218:221], v212 offset:56320
	global_load_lds_dwordx4 v[222:223], off
	s_add_i32 m0, s12, 0x2000
	s_add_u32 s12, s28, 0x80080
	v_lshl_add_u64 v[222:223], v[224:225], 0, s[62:63]
	s_addc_u32 s13, s29, 0
	s_add_i32 s28, vcc_hi, s35
	global_load_lds_dwordx4 v[222:223], off
	v_lshl_add_u64 v[222:223], s[12:13], 0, v[164:165]
	s_mov_b32 m0, s28
	s_nop 0
	global_load_lds_dwordx4 v[222:223], off
	v_lshl_add_u64 v[222:223], s[12:13], 0, v[168:169]
	s_add_i32 m0, s28, 0x2000
	s_nop 0
	global_load_lds_dwordx4 v[222:223], off
	v_lshl_add_u64 v[222:223], v[234:235], 0, s[62:63]
	s_mov_b32 m0, s80
	s_nop 0
	global_load_lds_dwordx4 v[222:223], off
	v_lshl_add_u64 v[222:223], v[236:237], 0, s[62:63]
	s_mov_b32 m0, s81
	s_nop 0
	global_load_lds_dwordx4 v[222:223], off
	s_waitcnt vmcnt(8)
	s_waitcnt lgkmcnt(0)
	s_barrier
	s_setprio 1
	v_mfma_f32_16x16x32_bf16 v[62:65], v[122:125], v[182:185], v[62:65]
	v_mfma_f32_16x16x32_bf16 v[58:61], v[138:141], v[182:185], v[58:61]
	v_mfma_f32_16x16x32_bf16 v[46:49], v[122:125], v[190:193], v[46:49]
	v_mfma_f32_16x16x32_bf16 v[42:45], v[138:141], v[190:193], v[42:45]
	v_mfma_f32_16x16x32_bf16 v[30:33], v[122:125], v[198:201], v[30:33]
	v_mfma_f32_16x16x32_bf16 v[26:29], v[138:141], v[198:201], v[26:29]
	v_mfma_f32_16x16x32_bf16 v[14:17], v[122:125], v[214:217], v[14:17]
	v_mfma_f32_16x16x32_bf16 v[10:13], v[138:141], v[214:217], v[10:13]
	v_mfma_f32_16x16x32_bf16 v[62:65], v[134:137], v[186:189], v[62:65]
	v_mfma_f32_16x16x32_bf16 v[58:61], v[142:145], v[186:189], v[58:61]
	v_mfma_f32_16x16x32_bf16 v[46:49], v[134:137], v[194:197], v[46:49]
	v_mfma_f32_16x16x32_bf16 v[42:45], v[142:145], v[194:197], v[42:45]
	v_mfma_f32_16x16x32_bf16 v[30:33], v[134:137], v[202:205], v[30:33]
	v_mfma_f32_16x16x32_bf16 v[26:29], v[142:145], v[202:205], v[26:29]
	v_mfma_f32_16x16x32_bf16 v[14:17], v[134:137], v[218:221], v[14:17]
	v_mfma_f32_16x16x32_bf16 v[10:13], v[142:145], v[218:221], v[10:13]
	v_mfma_f32_16x16x32_bf16 v[54:57], v[146:149], v[182:185], v[54:57]
	v_mfma_f32_16x16x32_bf16 v[50:53], v[154:157], v[182:185], v[50:53]
	v_mfma_f32_16x16x32_bf16 v[38:41], v[146:149], v[190:193], v[38:41]
	v_mfma_f32_16x16x32_bf16 v[34:37], v[154:157], v[190:193], v[34:37]
	v_mfma_f32_16x16x32_bf16 v[22:25], v[146:149], v[198:201], v[22:25]
	v_mfma_f32_16x16x32_bf16 v[18:21], v[154:157], v[198:201], v[18:21]
	v_mfma_f32_16x16x32_bf16 v[6:9], v[146:149], v[214:217], v[6:9]
	v_mfma_f32_16x16x32_bf16 v[2:5], v[154:157], v[214:217], v[2:5]
	v_mfma_f32_16x16x32_bf16 v[54:57], v[150:153], v[186:189], v[54:57]
	v_mfma_f32_16x16x32_bf16 v[50:53], v[158:161], v[186:189], v[50:53]
	v_mfma_f32_16x16x32_bf16 v[38:41], v[150:153], v[194:197], v[38:41]
	v_mfma_f32_16x16x32_bf16 v[34:37], v[158:161], v[194:197], v[34:37]
	v_mfma_f32_16x16x32_bf16 v[22:25], v[150:153], v[202:205], v[22:25]
	v_mfma_f32_16x16x32_bf16 v[18:21], v[158:161], v[202:205], v[18:21]
	v_mfma_f32_16x16x32_bf16 v[6:9], v[150:153], v[218:221], v[6:9]
	v_mfma_f32_16x16x32_bf16 v[2:5], v[158:161], v[218:221], v[2:5]
	s_setprio 0
	s_barrier
	s_add_i32 vcc_lo, vcc_lo, 2
	s_add_u32 s38, s38, 0x100
	s_addc_u32 s91, s91, 0
	s_cmp_gt_u32 vcc_lo, 29
	s_mov_b64 s[12:13], s[10:11]
	s_cbranch_scc0 .LBB0_189
	s_and_b64 vcc, exec, s[20:21]
	s_cbranch_vccz .LBB0_192
	s_barrier

; #define PG8_STAGE(bufoff, gbase, voff) do { _Pragma("unroll") for (int _i = 0; _i < 2; ++_i) \
;         __builtin_amdgcn_global_load_lds((const unsigned*)((const char*)(gbase) + (voff)[_i]), (PG8_LAS unsigned*)(lds + (bufoff) + ldsw + _i * 8192), 16, 0, 0); } while (0)
; #define PG8_LDA(dst, b, h) do { _Pragma("unroll") for (int m = 0; m < 4; ++m) _Pragma("unroll") for (int k = 0; k < 2; ++k) dst[m][k] = *(const PG8_LAS bf16x8*)(lds + PG8_SA(b, h) + aoff + m * 2048 + k * 1024); } while (0)
; #define PG8_LDB(dst, b, h) do { _Pragma("unroll") for (int n = 0; n < 2; ++n) _Pragma("unroll") for (int k = 0; k < 2; ++k) dst[n][k] = *(const PG8_LAS bf16x8*)(lds + PG8_SB(b, h) + boff + n * 2048 + k * 1024); } while (0)
; #define PG8_MMA(ai, bj, At, Bt) do { __builtin_amdgcn_s_setprio(1); _Pragma("unroll") for (int m = 0; m < 4; ++m) _Pragma("unroll") for (int n = 0; n < 2; ++n) _Pragma("unroll") for (int k = 0; k < 2; ++k) \
;         acc[ai][bj][m][n] = __builtin_amdgcn_mfma_f32_16x16x32_bf16(Bt[n][k], At[m][k], acc[ai][bj][m][n], 0, 0, 0); __builtin_amdgcn_s_setprio(0); } while (0)
; #define PG8_WAIT_V(n) asm volatile("s_waitcnt vmcnt(" #n ")" ::: "memory")
; #define PG8_WAIT_L(n) asm volatile("s_waitcnt lgkmcnt(" #n ")" ::: "memory")
; #define PG8_BAR __builtin_amdgcn_s_barrier()
; template <class Epi, class Sched, bool ALIGN_EPI = false, bool SP2 = false>
; __device__ __forceinline__ void gemm_phase(PG8_LAS unsigned char* lds, const Gemm g, const Sched& S, const Epi& E, const int wave_id) {
;     ...
;             const char* a1 = cA + (size_t)(t + 1) * kstep;
;             const char* a2 = last ? nA : cA + (size_t)(t + 2) * kstep; const char* b2 = last ? nB : cB + (size_t)(t + 2) * kstep;
;             const char* a3 = a2 + kstep; const char* b3 = b2 + kstep;
;             if (last && has_next) S.a_ready(nxt);
;             if constexpr (SP2) {
;             PG8_LDB(B0, 0, 0); PG8_LDB(B1, 0, 1); PG8_SCHED; PG8_LDA(At, 0, 0); PG8_STAGE(PG8_SA(1, 1), a1 + hstepA, voffA);
;             PG8_WAIT_V(8); PG8_WAIT_L(0); PG8_BAR; PG8_MMA(0, 0, At, B0); PG8_MMA(0, 1, At, B1); PG8_BAR; PG8_SCHED;
;             PG8_LDA(At, 0, 1); PG8_STAGE(PG8_SB(0, 0), b2, voffB); PG8_STAGE(PG8_SB(0, 1), b2 + hstepB, voffB); PG8_STAGE(PG8_SA(0, 0), a2, voffA);
;             PG8_WAIT_V(8); PG8_WAIT_L(0); PG8_BAR; PG8_MMA(1, 0, At, B0); PG8_MMA(1, 1, At, B1); PG8_BAR; PG8_SCHED;
.LBB0_297:
	s_add_u32 s12, s10, 0xfffc0080
	s_addc_u32 s13, s11, -1
	s_add_i32 s20, 0, 0x10000
	s_cmp_eq_u32 vcc_lo, 12
	s_cselect_b32 s35, s15, s13
	s_cselect_b32 s34, s27, s12
	v_add_u32_e32 v0, s20, v206
	s_cselect_b32 s13, s25, s38
	s_cselect_b32 s12, s36, s37
	s_add_i32 vcc_hi, 0, 0x14000
	ds_read_b128 v[122:125], v0
	ds_read_b128 v[134:137], v0 offset:1024
	ds_read_b128 v[138:141], v0 offset:2048
	ds_read_b128 v[142:145], v0 offset:3072
	v_add_u32_e32 v0, vcc_hi, v206
	ds_read_b128 v[146:149], v0
	ds_read_b128 v[150:153], v0 offset:1024
	ds_read_b128 v[154:157], v0 offset:2048
	ds_read_b128 v[158:161], v0 offset:3072
	v_lshl_add_u64 v[222:223], s[10:11], 0, v[178:179]
	s_add_i32 m0, s17, 0xc000
	ds_read_b128 v[182:185], v212
	ds_read_b128 v[186:189], v212 offset:1024
	ds_read_b128 v[190:193], v212 offset:2048
	ds_read_b128 v[194:197], v212 offset:3072
	ds_read_b128 v[198:201], v212 offset:4096
	ds_read_b128 v[202:205], v212 offset:5120
	ds_read_b128 v[214:217], v212 offset:6144
	ds_read_b128 v[218:221], v212 offset:7168
	global_load_lds_dwordx4 v[222:223], off
	v_lshl_add_u64 v[222:223], s[10:11], 0, v[180:181]
	s_add_i32 m0, s17, 0xe000
	s_nop 0
	global_load_lds_dwordx4 v[222:223], off
	s_waitcnt vmcnt(8)
	s_waitcnt lgkmcnt(0)
	s_barrier
	s_setprio 1
	v_mfma_f32_16x16x32_bf16 v[130:133], v[122:125], v[182:185], v[130:133]
	v_mfma_f32_16x16x32_bf16 v[126:129], v[138:141], v[182:185], v[126:129]
	v_mfma_f32_16x16x32_bf16 v[110:113], v[122:125], v[190:193], v[110:113]
	v_mfma_f32_16x16x32_bf16 v[106:109], v[138:141], v[190:193], v[106:109]
	v_mfma_f32_16x16x32_bf16 v[94:97], v[122:125], v[198:201], v[94:97]
	v_mfma_f32_16x16x32_bf16 v[90:93], v[138:141], v[198:201], v[90:93]
	v_mfma_f32_16x16x32_bf16 v[78:81], v[122:125], v[214:217], v[78:81]
	v_mfma_f32_16x16x32_bf16 v[74:77], v[138:141], v[214:217], v[74:77]
	v_mfma_f32_16x16x32_bf16 v[130:133], v[134:137], v[186:189], v[130:133]
	v_mfma_f32_16x16x32_bf16 v[126:129], v[142:145], v[186:189], v[126:129]
	v_mfma_f32_16x16x32_bf16 v[110:113], v[134:137], v[194:197], v[110:113]
	v_mfma_f32_16x16x32_bf16 v[106:109], v[142:145], v[194:197], v[106:109]
	v_mfma_f32_16x16x32_bf16 v[94:97], v[134:137], v[202:205], v[94:97]
	v_mfma_f32_16x16x32_bf16 v[90:93], v[142:145], v[202:205], v[90:93]
	v_mfma_f32_16x16x32_bf16 v[78:81], v[134:137], v[218:221], v[78:81]
	v_mfma_f32_16x16x32_bf16 v[74:77], v[142:145], v[218:221], v[74:77]
	v_mfma_f32_16x16x32_bf16 v[118:121], v[146:149], v[182:185], v[118:121]
	v_mfma_f32_16x16x32_bf16 v[114:117], v[154:157], v[182:185], v[114:117]
	v_mfma_f32_16x16x32_bf16 v[102:105], v[146:149], v[190:193], v[102:105]
	v_mfma_f32_16x16x32_bf16 v[98:101], v[154:157], v[190:193], v[98:101]
	v_mfma_f32_16x16x32_bf16 v[86:89], v[146:149], v[198:201], v[86:89]
	v_mfma_f32_16x16x32_bf16 v[82:85], v[154:157], v[198:201], v[82:85]
	v_mfma_f32_16x16x32_bf16 v[70:73], v[146:149], v[214:217], v[70:73]
	v_mfma_f32_16x16x32_bf16 v[66:69], v[154:157], v[214:217], v[66:69]
	v_mfma_f32_16x16x32_bf16 v[118:121], v[150:153], v[186:189], v[118:121]
	v_mfma_f32_16x16x32_bf16 v[114:117], v[158:161], v[186:189], v[114:117]
	v_mfma_f32_16x16x32_bf16 v[102:105], v[150:153], v[194:197], v[102:105]
	v_mfma_f32_16x16x32_bf16 v[98:101], v[158:161], v[194:197], v[98:101]
	v_mfma_f32_16x16x32_bf16 v[86:89], v[150:153], v[202:205], v[86:89]
	v_mfma_f32_16x16x32_bf16 v[82:85], v[158:161], v[202:205], v[82:85]
	v_mfma_f32_16x16x32_bf16 v[70:73], v[150:153], v[218:221], v[70:73]
	v_mfma_f32_16x16x32_bf16 v[66:69], v[158:161], v[218:221], v[66:69]
	s_setprio 0
	s_barrier
	s_add_i32 s20, s20, s76
	v_lshl_add_u64 v[222:223], s[12:13], 0, v[164:165]
	s_mov_b32 m0, s20
	ds_read_b128 v[182:185], v212 offset:16384
	ds_read_b128 v[186:189], v212 offset:17408
	ds_read_b128 v[190:193], v212 offset:18432
	ds_read_b128 v[194:197], v212 offset:19456
	ds_read_b128 v[198:201], v212 offset:20480
	ds_read_b128 v[202:205], v212 offset:21504
	ds_read_b128 v[214:217], v212 offset:22528
	ds_read_b128 v[218:221], v212 offset:23552
	global_load_lds_dwordx4 v[222:223], off
	s_add_i32 m0, s20, 0x2000
	s_add_u32 s20, s12, 0x40000
	v_lshl_add_u64 v[224:225], s[12:13], 0, v[168:169]
	s_addc_u32 s21, s13, 0
	s_add_i32 vcc_hi, vcc_hi, s76
	global_load_lds_dwordx4 v[224:225], off
	v_lshl_add_u64 v[234:235], s[20:21], 0, v[164:165]
	s_mov_b32 m0, vcc_hi
	v_lshl_add_u64 v[236:237], s[34:35], 0, v[166:167]
	global_load_lds_dwordx4 v[234:235], off
	v_lshl_add_u64 v[234:235], s[20:21], 0, v[168:169]
	s_add_i32 m0, vcc_hi, 0x2000
	s_nop 0
	global_load_lds_dwordx4 v[234:235], off
	v_lshl_add_u64 v[234:235], s[34:35], 0, v[162:163]
	s_mov_b32 m0, s17
	s_nop 0
	global_load_lds_dwordx4 v[234:235], off
	s_mov_b32 m0, s19
	s_nop 0
	global_load_lds_dwordx4 v[236:237], off
	s_waitcnt vmcnt(8)
	s_waitcnt lgkmcnt(0)
	s_barrier
; #define PG8_STAGE(bufoff, gbase, voff) do { _Pragma("unroll") for (int _i = 0; _i < 2; ++_i) \
;         __builtin_amdgcn_global_load_lds((const unsigned*)((const char*)(gbase) + (voff)[_i]), (PG8_LAS unsigned*)(lds + (bufoff) + ldsw + _i * 8192), 16, 0, 0); } while (0)
; #define PG8_LDA(dst, b, h) do { _Pragma("unroll") for (int m = 0; m < 4; ++m) _Pragma("unroll") for (int k = 0; k < 2; ++k) dst[m][k] = *(const PG8_LAS bf16x8*)(lds + PG8_SA(b, h) + aoff + m * 2048 + k * 1024); } while (0)
; #define PG8_LDB(dst, b, h) do { _Pragma("unroll") for (int n = 0; n < 2; ++n) _Pragma("unroll") for (int k = 0; k < 2; ++k) dst[n][k] = *(const PG8_LAS bf16x8*)(lds + PG8_SB(b, h) + boff + n * 2048 + k * 1024); } while (0)
; #define PG8_MMA(ai, bj, At, Bt) do { __builtin_amdgcn_s_setprio(1); _Pragma("unroll") for (int m = 0; m < 4; ++m) _Pragma("unroll") for (int n = 0; n < 2; ++n) _Pragma("unroll") for (int k = 0; k < 2; ++k) \
;         acc[ai][bj][m][n] = __builtin_amdgcn_mfma_f32_16x16x32_bf16(Bt[n][k], At[m][k], acc[ai][bj][m][n], 0, 0, 0); __builtin_amdgcn_s_setprio(0); } while (0)
; #define PG8_WAIT_V(n) asm volatile("s_waitcnt vmcnt(" #n ")" ::: "memory")
; #define PG8_WAIT_L(n) asm volatile("s_waitcnt lgkmcnt(" #n ")" ::: "memory")
; #define PG8_BAR __builtin_amdgcn_s_barrier()
; #define PG8_SCHED __builtin_amdgcn_sched_barrier(0)
; template <class Epi, class Sched, bool ALIGN_EPI = false, bool SP2 = false>
; __device__ __forceinline__ void gemm_phase(PG8_LAS unsigned char* lds, const Gemm g, const Sched& S, const Epi& E, const int wave_id) {
;     ...
;             PG8_WAIT_V(8); PG8_WAIT_L(0); PG8_BAR; PG8_MMA(1, 0, At, B0); PG8_MMA(1, 1, At, B1); PG8_BAR; PG8_SCHED;
;             PG8_LDB(B0, 1, 0); PG8_LDB(B1, 1, 1); PG8_SCHED; PG8_LDA(At, 1, 0); PG8_STAGE(PG8_SA(0, 1), a2 + hstepA, voffA);
;             PG8_WAIT_V(8); PG8_WAIT_L(0); PG8_BAR; PG8_MMA(0, 0, At, B0); PG8_MMA(0, 1, At, B1); PG8_BAR; PG8_SCHED;
	s_setprio 1
	v_mfma_f32_16x16x32_bf16 v[62:65], v[122:125], v[182:185], v[62:65]
	v_mfma_f32_16x16x32_bf16 v[58:61], v[138:141], v[182:185], v[58:61]
	v_mfma_f32_16x16x32_bf16 v[46:49], v[122:125], v[190:193], v[46:49]
	v_mfma_f32_16x16x32_bf16 v[42:45], v[138:141], v[190:193], v[42:45]
	v_mfma_f32_16x16x32_bf16 v[30:33], v[122:125], v[198:201], v[30:33]
	v_mfma_f32_16x16x32_bf16 v[26:29], v[138:141], v[198:201], v[26:29]
	v_mfma_f32_16x16x32_bf16 v[14:17], v[122:125], v[214:217], v[14:17]
	v_mfma_f32_16x16x32_bf16 v[10:13], v[138:141], v[214:217], v[10:13]
	v_mfma_f32_16x16x32_bf16 v[62:65], v[134:137], v[186:189], v[62:65]
	v_mfma_f32_16x16x32_bf16 v[58:61], v[142:145], v[186:189], v[58:61]
	v_mfma_f32_16x16x32_bf16 v[46:49], v[134:137], v[194:197], v[46:49]
	v_mfma_f32_16x16x32_bf16 v[42:45], v[142:145], v[194:197], v[42:45]
	v_mfma_f32_16x16x32_bf16 v[30:33], v[134:137], v[202:205], v[30:33]
	v_mfma_f32_16x16x32_bf16 v[26:29], v[142:145], v[202:205], v[26:29]
	v_mfma_f32_16x16x32_bf16 v[14:17], v[134:137], v[218:221], v[14:17]
	v_mfma_f32_16x16x32_bf16 v[10:13], v[142:145], v[218:221], v[10:13]
	v_mfma_f32_16x16x32_bf16 v[54:57], v[146:149], v[182:185], v[54:57]
	v_mfma_f32_16x16x32_bf16 v[50:53], v[154:157], v[182:185], v[50:53]
	v_mfma_f32_16x16x32_bf16 v[38:41], v[146:149], v[190:193], v[38:41]
	v_mfma_f32_16x16x32_bf16 v[34:37], v[154:157], v[190:193], v[34:37]
	v_mfma_f32_16x16x32_bf16 v[22:25], v[146:149], v[198:201], v[22:25]
	v_mfma_f32_16x16x32_bf16 v[18:21], v[154:157], v[198:201], v[18:21]
	v_mfma_f32_16x16x32_bf16 v[6:9], v[146:149], v[214:217], v[6:9]
	v_mfma_f32_16x16x32_bf16 v[2:5], v[154:157], v[214:217], v[2:5]
	v_mfma_f32_16x16x32_bf16 v[54:57], v[150:153], v[186:189], v[54:57]
	v_mfma_f32_16x16x32_bf16 v[50:53], v[158:161], v[186:189], v[50:53]
	v_mfma_f32_16x16x32_bf16 v[38:41], v[150:153], v[194:197], v[38:41]
	v_mfma_f32_16x16x32_bf16 v[34:37], v[158:161], v[194:197], v[34:37]
	v_mfma_f32_16x16x32_bf16 v[22:25], v[150:153], v[202:205], v[22:25]
	v_mfma_f32_16x16x32_bf16 v[18:21], v[158:161], v[202:205], v[18:21]
	v_mfma_f32_16x16x32_bf16 v[6:9], v[150:153], v[218:221], v[6:9]
	v_mfma_f32_16x16x32_bf16 v[2:5], v[158:161], v[218:221], v[2:5]
	s_setprio 0
	s_barrier
	s_add_i32 vcc_hi, 0, 0x18000
	v_add_u32_e32 v0, vcc_hi, v206
	s_add_i32 s39, 0, 0x1c000
	ds_read_b128 v[122:125], v0
	ds_read_b128 v[134:137], v0 offset:1024
	ds_read_b128 v[138:141], v0 offset:2048
	ds_read_b128 v[142:145], v0 offset:3072
	v_add_u32_e32 v0, s39, v206
	ds_read_b128 v[146:149], v0
	ds_read_b128 v[150:153], v0 offset:1024
	ds_read_b128 v[154:157], v0 offset:2048
	ds_read_b128 v[158:161], v0 offset:3072
	s_add_u32 s20, s34, 0x40000
	s_addc_u32 s21, s35, 0
	s_mov_b32 m0, s77
	v_lshl_add_u64 v[240:241], s[20:21], 0, v[162:163]
	ds_read_b128 v[182:185], v212 offset:32768
	ds_read_b128 v[186:189], v212 offset:33792
	ds_read_b128 v[190:193], v212 offset:34816
	ds_read_b128 v[194:197], v212 offset:35840
	ds_read_b128 v[198:201], v212 offset:36864
	ds_read_b128 v[202:205], v212 offset:37888
	ds_read_b128 v[214:217], v212 offset:38912
	ds_read_b128 v[218:221], v212 offset:39936
	global_load_lds_dwordx4 v[240:241], off
	v_lshl_add_u64 v[240:241], s[20:21], 0, v[166:167]
	s_mov_b32 m0, s80
	s_nop 0
	global_load_lds_dwordx4 v[240:241], off
	s_waitcnt vmcnt(8)
	s_waitcnt lgkmcnt(0)
	s_barrier
	s_setprio 1
	v_mfma_f32_16x16x32_bf16 v[130:133], v[122:125], v[182:185], v[130:133]
	v_mfma_f32_16x16x32_bf16 v[126:129], v[138:141], v[182:185], v[126:129]
	v_mfma_f32_16x16x32_bf16 v[110:113], v[122:125], v[190:193], v[110:113]
	v_mfma_f32_16x16x32_bf16 v[106:109], v[138:141], v[190:193], v[106:109]
	v_mfma_f32_16x16x32_bf16 v[94:97], v[122:125], v[198:201], v[94:97]
	v_mfma_f32_16x16x32_bf16 v[90:93], v[138:141], v[198:201], v[90:93]
	v_mfma_f32_16x16x32_bf16 v[78:81], v[122:125], v[214:217], v[78:81]
	v_mfma_f32_16x16x32_bf16 v[74:77], v[138:141], v[214:217], v[74:77]
	v_mfma_f32_16x16x32_bf16 v[130:133], v[134:137], v[186:189], v[130:133]
	v_mfma_f32_16x16x32_bf16 v[126:129], v[142:145], v[186:189], v[126:129]
	v_mfma_f32_16x16x32_bf16 v[110:113], v[134:137], v[194:197], v[110:113]
	v_mfma_f32_16x16x32_bf16 v[106:109], v[142:145], v[194:197], v[106:109]
	v_mfma_f32_16x16x32_bf16 v[94:97], v[134:137], v[202:205], v[94:97]
	v_mfma_f32_16x16x32_bf16 v[90:93], v[142:145], v[202:205], v[90:93]
	v_mfma_f32_16x16x32_bf16 v[78:81], v[134:137], v[218:221], v[78:81]
	v_mfma_f32_16x16x32_bf16 v[74:77], v[142:145], v[218:221], v[74:77]
	v_mfma_f32_16x16x32_bf16 v[118:121], v[146:149], v[182:185], v[118:121]
	v_mfma_f32_16x16x32_bf16 v[114:117], v[154:157], v[182:185], v[114:117]
	v_mfma_f32_16x16x32_bf16 v[102:105], v[146:149], v[190:193], v[102:105]
	v_mfma_f32_16x16x32_bf16 v[98:101], v[154:157], v[190:193], v[98:101]
	v_mfma_f32_16x16x32_bf16 v[86:89], v[146:149], v[198:201], v[86:89]
	v_mfma_f32_16x16x32_bf16 v[82:85], v[154:157], v[198:201], v[82:85]
	v_mfma_f32_16x16x32_bf16 v[70:73], v[146:149], v[214:217], v[70:73]
	v_mfma_f32_16x16x32_bf16 v[66:69], v[154:157], v[214:217], v[66:69]
	v_mfma_f32_16x16x32_bf16 v[118:121], v[150:153], v[186:189], v[118:121]
	v_mfma_f32_16x16x32_bf16 v[114:117], v[158:161], v[186:189], v[114:117]
	v_mfma_f32_16x16x32_bf16 v[102:105], v[150:153], v[194:197], v[102:105]
	v_mfma_f32_16x16x32_bf16 v[98:101], v[158:161], v[194:197], v[98:101]
	v_mfma_f32_16x16x32_bf16 v[86:89], v[150:153], v[202:205], v[86:89]
	v_mfma_f32_16x16x32_bf16 v[82:85], v[158:161], v[202:205], v[82:85]
	v_mfma_f32_16x16x32_bf16 v[70:73], v[150:153], v[218:221], v[70:73]
	v_mfma_f32_16x16x32_bf16 v[66:69], v[158:161], v[218:221], v[66:69]
	s_setprio 0
	s_barrier
; #define PG8_STAGE(bufoff, gbase, voff) do { _Pragma("unroll") for (int _i = 0; _i < 2; ++_i) \
;         __builtin_amdgcn_global_load_lds((const unsigned*)((const char*)(gbase) + (voff)[_i]), (PG8_LAS unsigned*)(lds + (bufoff) + ldsw + _i * 8192), 16, 0, 0); } while (0)
; #define PG8_LDA(dst, b, h) do { _Pragma("unroll") for (int m = 0; m < 4; ++m) _Pragma("unroll") for (int k = 0; k < 2; ++k) dst[m][k] = *(const PG8_LAS bf16x8*)(lds + PG8_SA(b, h) + aoff + m * 2048 + k * 1024); } while (0)
; #define PG8_MMA(ai, bj, At, Bt) do { __builtin_amdgcn_s_setprio(1); _Pragma("unroll") for (int m = 0; m < 4; ++m) _Pragma("unroll") for (int n = 0; n < 2; ++n) _Pragma("unroll") for (int k = 0; k < 2; ++k) \
;         acc[ai][bj][m][n] = __builtin_amdgcn_mfma_f32_16x16x32_bf16(Bt[n][k], At[m][k], acc[ai][bj][m][n], 0, 0, 0); __builtin_amdgcn_s_setprio(0); } while (0)
; #define PG8_WAIT_V(n) asm volatile("s_waitcnt vmcnt(" #n ")" ::: "memory")
; #define PG8_WAIT_L(n) asm volatile("s_waitcnt lgkmcnt(" #n ")" ::: "memory")
; #define PG8_BAR __builtin_amdgcn_s_barrier()
; #define PG8_SCHED __builtin_amdgcn_sched_barrier(0)
; template <class Epi, class Sched, bool ALIGN_EPI = false, bool SP2 = false>
; __device__ __forceinline__ void gemm_phase(PG8_LAS unsigned char* lds, const Gemm g, const Sched& S, const Epi& E, const int wave_id) {
;     ...
;         for (int t = 0; t < nt; t += 2) {
;             const bool last = (t == nt - 2);
;     ...
;             PG8_LDA(At, 1, 1); PG8_STAGE(PG8_SB(1, 0), b3, voffB); PG8_STAGE(PG8_SB(1, 1), b3 + hstepB, voffB); PG8_STAGE(PG8_SA(1, 0), a3, voffA);
;             PG8_WAIT_V(8); PG8_WAIT_L(0); PG8_BAR; PG8_MMA(1, 0, At, B0); PG8_MMA(1, 1, At, B1); PG8_BAR; PG8_SCHED;
	s_add_i32 s20, vcc_hi, s76
	v_lshl_add_u64 v[222:223], v[222:223], 0, s[62:63]
	s_mov_b32 m0, s20
	ds_read_b128 v[182:185], v212 offset:49152
	ds_read_b128 v[186:189], v212 offset:50176
	ds_read_b128 v[190:193], v212 offset:51200
	ds_read_b128 v[194:197], v212 offset:52224
	ds_read_b128 v[198:201], v212 offset:53248
	ds_read_b128 v[202:205], v212 offset:54272
	ds_read_b128 v[214:217], v212 offset:55296
	ds_read_b128 v[218:221], v212 offset:56320
	global_load_lds_dwordx4 v[222:223], off
	s_add_i32 m0, s20, 0x2000
	s_add_u32 s12, s12, 0x40080
	v_lshl_add_u64 v[222:223], v[224:225], 0, s[62:63]
	s_addc_u32 s13, s13, 0
	s_add_i32 s20, s39, s76
	global_load_lds_dwordx4 v[222:223], off
	v_lshl_add_u64 v[222:223], s[12:13], 0, v[164:165]
	s_mov_b32 m0, s20
	s_nop 0
	global_load_lds_dwordx4 v[222:223], off
	v_lshl_add_u64 v[222:223], s[12:13], 0, v[168:169]
	s_add_i32 m0, s20, 0x2000
	s_nop 0
	global_load_lds_dwordx4 v[222:223], off
	v_lshl_add_u64 v[222:223], v[234:235], 0, s[62:63]
	s_mov_b32 m0, s82
	s_nop 0
	global_load_lds_dwordx4 v[222:223], off
	v_lshl_add_u64 v[222:223], v[236:237], 0, s[62:63]
	s_mov_b32 m0, s83
	s_nop 0
	global_load_lds_dwordx4 v[222:223], off
	s_waitcnt vmcnt(8)
	s_waitcnt lgkmcnt(0)
	s_barrier
	s_setprio 1
	v_mfma_f32_16x16x32_bf16 v[62:65], v[122:125], v[182:185], v[62:65]
	v_mfma_f32_16x16x32_bf16 v[58:61], v[138:141], v[182:185], v[58:61]
	v_mfma_f32_16x16x32_bf16 v[46:49], v[122:125], v[190:193], v[46:49]
	v_mfma_f32_16x16x32_bf16 v[42:45], v[138:141], v[190:193], v[42:45]
	v_mfma_f32_16x16x32_bf16 v[30:33], v[122:125], v[198:201], v[30:33]
	v_mfma_f32_16x16x32_bf16 v[26:29], v[138:141], v[198:201], v[26:29]
	v_mfma_f32_16x16x32_bf16 v[14:17], v[122:125], v[214:217], v[14:17]
	v_mfma_f32_16x16x32_bf16 v[10:13], v[138:141], v[214:217], v[10:13]
	v_mfma_f32_16x16x32_bf16 v[62:65], v[134:137], v[186:189], v[62:65]
	v_mfma_f32_16x16x32_bf16 v[58:61], v[142:145], v[186:189], v[58:61]
	v_mfma_f32_16x16x32_bf16 v[46:49], v[134:137], v[194:197], v[46:49]
	v_mfma_f32_16x16x32_bf16 v[42:45], v[142:145], v[194:197], v[42:45]
	v_mfma_f32_16x16x32_bf16 v[30:33], v[134:137], v[202:205], v[30:33]
	v_mfma_f32_16x16x32_bf16 v[26:29], v[142:145], v[202:205], v[26:29]
	v_mfma_f32_16x16x32_bf16 v[14:17], v[134:137], v[218:221], v[14:17]
	v_mfma_f32_16x16x32_bf16 v[10:13], v[142:145], v[218:221], v[10:13]
	v_mfma_f32_16x16x32_bf16 v[54:57], v[146:149], v[182:185], v[54:57]
	v_mfma_f32_16x16x32_bf16 v[50:53], v[154:157], v[182:185], v[50:53]
	v_mfma_f32_16x16x32_bf16 v[38:41], v[146:149], v[190:193], v[38:41]
	v_mfma_f32_16x16x32_bf16 v[34:37], v[154:157], v[190:193], v[34:37]
	v_mfma_f32_16x16x32_bf16 v[22:25], v[146:149], v[198:201], v[22:25]
	v_mfma_f32_16x16x32_bf16 v[18:21], v[154:157], v[198:201], v[18:21]
	v_mfma_f32_16x16x32_bf16 v[6:9], v[146:149], v[214:217], v[6:9]
	v_mfma_f32_16x16x32_bf16 v[2:5], v[154:157], v[214:217], v[2:5]
	v_mfma_f32_16x16x32_bf16 v[54:57], v[150:153], v[186:189], v[54:57]
	v_mfma_f32_16x16x32_bf16 v[50:53], v[158:161], v[186:189], v[50:53]
	v_mfma_f32_16x16x32_bf16 v[38:41], v[150:153], v[194:197], v[38:41]
	v_mfma_f32_16x16x32_bf16 v[34:37], v[158:161], v[194:197], v[34:37]
	v_mfma_f32_16x16x32_bf16 v[22:25], v[150:153], v[202:205], v[22:25]
	v_mfma_f32_16x16x32_bf16 v[18:21], v[158:161], v[202:205], v[18:21]
	v_mfma_f32_16x16x32_bf16 v[6:9], v[150:153], v[218:221], v[6:9]
	v_mfma_f32_16x16x32_bf16 v[2:5], v[158:161], v[218:221], v[2:5]
	s_setprio 0
	s_barrier
	s_add_i32 vcc_lo, vcc_lo, 2
	s_add_u32 s10, s10, 0x100
	s_addc_u32 s11, s11, 0
	s_add_u32 s37, s37, 0x100
	s_addc_u32 s38, s38, 0
	s_cmp_gt_u32 vcc_lo, 13
	s_cbranch_scc0 .LBB0_297
	s_and_b64 vcc, exec, s[22:23]
	s_cbranch_vccz .LBB0_300
	s_barrier

; #define PG8_STAGE(bufoff, gbase, voff) do { _Pragma("unroll") for (int _i = 0; _i < 2; ++_i) \
;         __builtin_amdgcn_global_load_lds((const unsigned*)((const char*)(gbase) + (voff)[_i]), (PG8_LAS unsigned*)(lds + (bufoff) + ldsw + _i * 8192), 16, 0, 0); } while (0)
; #define PG8_LDA(dst, b, h) do { _Pragma("unroll") for (int m = 0; m < 4; ++m) _Pragma("unroll") for (int k = 0; k < 2; ++k) dst[m][k] = *(const PG8_LAS bf16x8*)(lds + PG8_SA(b, h) + aoff + m * 2048 + k * 1024); } while (0)
; #define PG8_MMA(ai, bj, At, Bt) do { __builtin_amdgcn_s_setprio(1); _Pragma("unroll") for (int m = 0; m < 4; ++m) _Pragma("unroll") for (int n = 0; n < 2; ++n) _Pragma("unroll") for (int k = 0; k < 2; ++k) \
;         acc[ai][bj][m][n] = __builtin_amdgcn_mfma_f32_16x16x32_bf16(Bt[n][k], At[m][k], acc[ai][bj][m][n], 0, 0, 0); __builtin_amdgcn_s_setprio(0); } while (0)
; #define PG8_WAIT_V(n) asm volatile("s_waitcnt vmcnt(" #n ")" ::: "memory")
; #define PG8_WAIT_L(n) asm volatile("s_waitcnt lgkmcnt(" #n ")" ::: "memory")
; #define PG8_BAR __builtin_amdgcn_s_barrier()
; #define PG8_SCHED __builtin_amdgcn_sched_barrier(0)
; template <class Epi, class Sched, bool ALIGN_EPI = false, bool SP2 = false>
; __device__ __forceinline__ void gemm_phase(PG8_LAS unsigned char* lds, const Gemm g, const Sched& S, const Epi& E, const int wave_id) {
;     ...
;             PG8_WAIT_V(8); PG8_WAIT_L(0); PG8_BAR; PG8_MMA(0, 0, At, B0); PG8_MMA(0, 1, At, B1); PG8_BAR; PG8_SCHED;
;             PG8_LDA(At, 0, 1); PG8_STAGE(PG8_SB(0, 0), b2, voffB); PG8_STAGE(PG8_SB(0, 1), b2 + hstepB, voffB); PG8_STAGE(PG8_SA(0, 0), a2, voffA);
;             PG8_WAIT_V(8); PG8_WAIT_L(0); PG8_BAR; PG8_MMA(1, 0, At, B0); PG8_MMA(1, 1, At, B1); PG8_BAR; PG8_SCHED;
.Lrw_3:
	s_waitcnt lgkmcnt(0)
	s_barrier
	s_setprio 1
	v_mfma_f32_16x16x32_bf16 v[134:137], v[138:141], v[190:193], v[134:137]
	v_mfma_f32_16x16x32_bf16 v[130:133], v[146:149], v[190:193], v[130:133]
	v_mfma_f32_16x16x32_bf16 v[122:125], v[138:141], v[198:201], v[122:125]
	v_mfma_f32_16x16x32_bf16 v[114:117], v[146:149], v[198:201], v[114:117]
	v_mfma_f32_16x16x32_bf16 v[106:109], v[138:141], v[216:219], v[106:109]
	v_mfma_f32_16x16x32_bf16 v[98:101], v[146:149], v[216:219], v[98:101]
	v_mfma_f32_16x16x32_bf16 v[90:93], v[138:141], v[240:243], v[90:93]
	v_mfma_f32_16x16x32_bf16 v[82:85], v[146:149], v[240:243], v[82:85]
	v_mfma_f32_16x16x32_bf16 v[134:137], v[142:145], v[194:197], v[134:137]
	v_mfma_f32_16x16x32_bf16 v[130:133], v[150:153], v[194:197], v[130:133]
	v_mfma_f32_16x16x32_bf16 v[122:125], v[142:145], v[202:205], v[122:125]
	v_mfma_f32_16x16x32_bf16 v[114:117], v[150:153], v[202:205], v[114:117]
	v_mfma_f32_16x16x32_bf16 v[106:109], v[142:145], v[220:223], v[106:109]
	v_mfma_f32_16x16x32_bf16 v[98:101], v[150:153], v[220:223], v[98:101]
	v_mfma_f32_16x16x32_bf16 v[90:93], v[142:145], v[244:247], v[90:93]
	v_mfma_f32_16x16x32_bf16 v[82:85], v[150:153], v[244:247], v[82:85]
	v_mfma_f32_16x16x32_bf16 v[126:129], v[154:157], v[190:193], v[126:129]
	v_mfma_f32_16x16x32_bf16 v[118:121], v[162:165], v[190:193], v[118:121]
	v_mfma_f32_16x16x32_bf16 v[110:113], v[154:157], v[198:201], v[110:113]
	v_mfma_f32_16x16x32_bf16 v[102:105], v[162:165], v[198:201], v[102:105]
	v_mfma_f32_16x16x32_bf16 v[94:97], v[154:157], v[216:219], v[94:97]
	v_mfma_f32_16x16x32_bf16 v[86:89], v[162:165], v[216:219], v[86:89]
	v_mfma_f32_16x16x32_bf16 v[78:81], v[154:157], v[240:243], v[78:81]
	v_mfma_f32_16x16x32_bf16 v[74:77], v[162:165], v[240:243], v[74:77]
	v_mfma_f32_16x16x32_bf16 v[126:129], v[158:161], v[194:197], v[126:129]
	v_mfma_f32_16x16x32_bf16 v[118:121], v[166:169], v[194:197], v[118:121]
	v_mfma_f32_16x16x32_bf16 v[110:113], v[158:161], v[202:205], v[110:113]
	v_mfma_f32_16x16x32_bf16 v[102:105], v[166:169], v[202:205], v[102:105]
	v_mfma_f32_16x16x32_bf16 v[94:97], v[158:161], v[220:223], v[94:97]
	v_mfma_f32_16x16x32_bf16 v[86:89], v[166:169], v[220:223], v[86:89]
	v_mfma_f32_16x16x32_bf16 v[78:81], v[158:161], v[244:247], v[78:81]
	v_mfma_f32_16x16x32_bf16 v[74:77], v[166:169], v[244:247], v[74:77]
	s_setprio 0
	s_barrier
	s_add_i32 s0, s35, s23
	v_lshl_add_u64 v[206:207], s[26:27], 0, v[180:181]
	s_mov_b32 m0, s0
	ds_read_b128 v[190:193], v215 offset:16384
	ds_read_b128 v[194:197], v215 offset:17408
	ds_read_b128 v[198:201], v215 offset:18432
	ds_read_b128 v[202:205], v215 offset:19456
	ds_read_b128 v[216:219], v215 offset:20480
	ds_read_b128 v[220:223], v215 offset:21504
	ds_read_b128 v[240:243], v215 offset:22528
	ds_read_b128 v[244:247], v215 offset:23552
	global_load_lds_dwordx4 v[206:207], off
	s_add_i32 m0, s0, 0x2000
	s_add_u32 s0, s26, 0x40000
	v_lshl_add_u64 v[224:225], s[26:27], 0, v[184:185]
	s_addc_u32 s1, s27, 0
	s_add_i32 s35, s36, s23
	global_load_lds_dwordx4 v[224:225], off
	v_lshl_add_u64 v[234:235], s[0:1], 0, v[180:181]
	s_mov_b32 m0, s35
	v_lshl_add_u64 v[236:237], s[28:29], 0, v[182:183]
	global_load_lds_dwordx4 v[234:235], off
	v_lshl_add_u64 v[234:235], s[0:1], 0, v[184:185]
	s_add_i32 m0, s35, 0x2000
	s_nop 0
	global_load_lds_dwordx4 v[234:235], off
	v_lshl_add_u64 v[234:235], s[28:29], 0, v[178:179]
	s_mov_b32 m0, s25
	s_nop 0
	global_load_lds_dwordx4 v[234:235], off
	s_mov_b32 m0, s30
	s_nop 0
	global_load_lds_dwordx4 v[236:237], off
	s_waitcnt vmcnt(24)
	s_cmp_eq_u32 s98, 1
	s_cbranch_scc1 .Lrw_4
	s_waitcnt vmcnt(8)
.Lrw_4:
	s_mov_b32 s98, 0
	s_waitcnt lgkmcnt(0)
	s_barrier
	s_setprio 1
	v_mfma_f32_16x16x32_bf16 v[70:73], v[138:141], v[190:193], v[70:73]
	v_mfma_f32_16x16x32_bf16 v[66:69], v[146:149], v[190:193], v[66:69]
	v_mfma_f32_16x16x32_bf16 v[58:61], v[138:141], v[198:201], v[58:61]
	v_mfma_f32_16x16x32_bf16 v[50:53], v[146:149], v[198:201], v[50:53]
	v_mfma_f32_16x16x32_bf16 v[42:45], v[138:141], v[216:219], v[42:45]
	v_mfma_f32_16x16x32_bf16 v[34:37], v[146:149], v[216:219], v[34:37]
	v_mfma_f32_16x16x32_bf16 v[26:29], v[138:141], v[240:243], v[26:29]
	v_mfma_f32_16x16x32_bf16 v[18:21], v[146:149], v[240:243], v[18:21]
	v_mfma_f32_16x16x32_bf16 v[70:73], v[142:145], v[194:197], v[70:73]
	v_mfma_f32_16x16x32_bf16 v[66:69], v[150:153], v[194:197], v[66:69]
	v_mfma_f32_16x16x32_bf16 v[58:61], v[142:145], v[202:205], v[58:61]
	v_mfma_f32_16x16x32_bf16 v[50:53], v[150:153], v[202:205], v[50:53]
	v_mfma_f32_16x16x32_bf16 v[42:45], v[142:145], v[220:223], v[42:45]
	v_mfma_f32_16x16x32_bf16 v[34:37], v[150:153], v[220:223], v[34:37]
	v_mfma_f32_16x16x32_bf16 v[26:29], v[142:145], v[244:247], v[26:29]
	v_mfma_f32_16x16x32_bf16 v[18:21], v[150:153], v[244:247], v[18:21]
	v_mfma_f32_16x16x32_bf16 v[62:65], v[154:157], v[190:193], v[62:65]
	v_mfma_f32_16x16x32_bf16 v[54:57], v[162:165], v[190:193], v[54:57]
	v_mfma_f32_16x16x32_bf16 v[46:49], v[154:157], v[198:201], v[46:49]
	v_mfma_f32_16x16x32_bf16 v[38:41], v[162:165], v[198:201], v[38:41]
	v_mfma_f32_16x16x32_bf16 v[30:33], v[154:157], v[216:219], v[30:33]
	v_mfma_f32_16x16x32_bf16 v[22:25], v[162:165], v[216:219], v[22:25]
	v_mfma_f32_16x16x32_bf16 v[14:17], v[154:157], v[240:243], v[14:17]
	v_mfma_f32_16x16x32_bf16 v[10:13], v[162:165], v[240:243], v[10:13]
	v_mfma_f32_16x16x32_bf16 v[62:65], v[158:161], v[194:197], v[62:65]
	v_mfma_f32_16x16x32_bf16 v[54:57], v[166:169], v[194:197], v[54:57]
	v_mfma_f32_16x16x32_bf16 v[46:49], v[158:161], v[202:205], v[46:49]
	v_mfma_f32_16x16x32_bf16 v[38:41], v[166:169], v[202:205], v[38:41]
	v_mfma_f32_16x16x32_bf16 v[30:33], v[158:161], v[220:223], v[30:33]
	v_mfma_f32_16x16x32_bf16 v[22:25], v[166:169], v[220:223], v[22:25]
	v_mfma_f32_16x16x32_bf16 v[14:17], v[158:161], v[244:247], v[14:17]
	v_mfma_f32_16x16x32_bf16 v[10:13], v[166:169], v[244:247], v[10:13]
	s_setprio 0
	s_barrier
; #define PG8_STAGE(bufoff, gbase, voff) do { _Pragma("unroll") for (int _i = 0; _i < 2; ++_i) \
;         __builtin_amdgcn_global_load_lds((const unsigned*)((const char*)(gbase) + (voff)[_i]), (PG8_LAS unsigned*)(lds + (bufoff) + ldsw + _i * 8192), 16, 0, 0); } while (0)
; #define PG8_LDA(dst, b, h) do { _Pragma("unroll") for (int m = 0; m < 4; ++m) _Pragma("unroll") for (int k = 0; k < 2; ++k) dst[m][k] = *(const PG8_LAS bf16x8*)(lds + PG8_SA(b, h) + aoff + m * 2048 + k * 1024); } while (0)
; #define PG8_LDB(dst, b, h) do { _Pragma("unroll") for (int n = 0; n < 2; ++n) _Pragma("unroll") for (int k = 0; k < 2; ++k) dst[n][k] = *(const PG8_LAS bf16x8*)(lds + PG8_SB(b, h) + boff + n * 2048 + k * 1024); } while (0)
; #define PG8_MMA(ai, bj, At, Bt) do { __builtin_amdgcn_s_setprio(1); _Pragma("unroll") for (int m = 0; m < 4; ++m) _Pragma("unroll") for (int n = 0; n < 2; ++n) _Pragma("unroll") for (int k = 0; k < 2; ++k) \
;         acc[ai][bj][m][n] = __builtin_amdgcn_mfma_f32_16x16x32_bf16(Bt[n][k], At[m][k], acc[ai][bj][m][n], 0, 0, 0); __builtin_amdgcn_s_setprio(0); } while (0)
; #define PG8_WAIT_V(n) asm volatile("s_waitcnt vmcnt(" #n ")" ::: "memory")
; #define PG8_WAIT_L(n) asm volatile("s_waitcnt lgkmcnt(" #n ")" ::: "memory")
; #define PG8_BAR __builtin_amdgcn_s_barrier()
; #define PG8_SCHED __builtin_amdgcn_sched_barrier(0)
; template <class Epi, class Sched, bool ALIGN_EPI = false, bool SP2 = false>
; __device__ __forceinline__ void gemm_phase(PG8_LAS unsigned char* lds, const Gemm g, const Sched& S, const Epi& E, const int wave_id) {
;     ...
;             PG8_LDB(B0, 1, 0); PG8_LDB(B1, 1, 1); PG8_SCHED; PG8_LDA(At, 1, 0); PG8_STAGE(PG8_SA(0, 1), a2 + hstepA, voffA);
;             PG8_WAIT_V(8); PG8_WAIT_L(0); PG8_BAR; PG8_MMA(0, 0, At, B0); PG8_MMA(0, 1, At, B1); PG8_BAR; PG8_SCHED;
	s_add_i32 s35, 0, 0x18000
	v_add_u32_e32 v0, s35, v210
	s_add_i32 s36, 0, 0x1c000
	ds_read_b128 v[138:141], v0
	ds_read_b128 v[142:145], v0 offset:1024
	ds_read_b128 v[146:149], v0 offset:2048
	ds_read_b128 v[150:153], v0 offset:3072
	v_add_u32_e32 v0, s36, v210
	ds_read_b128 v[154:157], v0
	ds_read_b128 v[158:161], v0 offset:1024
	ds_read_b128 v[162:165], v0 offset:2048
	ds_read_b128 v[166:169], v0 offset:3072
	s_add_u32 s0, s28, 0x40000
	s_addc_u32 s1, s29, 0
	s_mov_b32 m0, s31
	v_lshl_add_u64 v[248:249], s[0:1], 0, v[178:179]
	ds_read_b128 v[190:193], v215 offset:32768
	ds_read_b128 v[194:197], v215 offset:33792
	ds_read_b128 v[198:201], v215 offset:34816
	ds_read_b128 v[202:205], v215 offset:35840
	ds_read_b128 v[216:219], v215 offset:36864
	ds_read_b128 v[220:223], v215 offset:37888
	ds_read_b128 v[240:243], v215 offset:38912
	ds_read_b128 v[244:247], v215 offset:39936
	global_load_lds_dwordx4 v[248:249], off
	v_lshl_add_u64 v[248:249], s[0:1], 0, v[182:183]
	s_mov_b32 m0, s34
	s_nop 0
	global_load_lds_dwordx4 v[248:249], off
	s_waitcnt vmcnt(8)
	s_waitcnt lgkmcnt(0)
	s_barrier
	s_setprio 1
	v_mfma_f32_16x16x32_bf16 v[134:137], v[138:141], v[190:193], v[134:137]
	v_mfma_f32_16x16x32_bf16 v[130:133], v[146:149], v[190:193], v[130:133]
	v_mfma_f32_16x16x32_bf16 v[122:125], v[138:141], v[198:201], v[122:125]
	v_mfma_f32_16x16x32_bf16 v[114:117], v[146:149], v[198:201], v[114:117]
	v_mfma_f32_16x16x32_bf16 v[106:109], v[138:141], v[216:219], v[106:109]
	v_mfma_f32_16x16x32_bf16 v[98:101], v[146:149], v[216:219], v[98:101]
	v_mfma_f32_16x16x32_bf16 v[90:93], v[138:141], v[240:243], v[90:93]
	v_mfma_f32_16x16x32_bf16 v[82:85], v[146:149], v[240:243], v[82:85]
	v_mfma_f32_16x16x32_bf16 v[134:137], v[142:145], v[194:197], v[134:137]
	v_mfma_f32_16x16x32_bf16 v[130:133], v[150:153], v[194:197], v[130:133]
	v_mfma_f32_16x16x32_bf16 v[122:125], v[142:145], v[202:205], v[122:125]
	v_mfma_f32_16x16x32_bf16 v[114:117], v[150:153], v[202:205], v[114:117]
	v_mfma_f32_16x16x32_bf16 v[106:109], v[142:145], v[220:223], v[106:109]
	v_mfma_f32_16x16x32_bf16 v[98:101], v[150:153], v[220:223], v[98:101]
	v_mfma_f32_16x16x32_bf16 v[90:93], v[142:145], v[244:247], v[90:93]
	v_mfma_f32_16x16x32_bf16 v[82:85], v[150:153], v[244:247], v[82:85]
	v_mfma_f32_16x16x32_bf16 v[126:129], v[154:157], v[190:193], v[126:129]
	v_mfma_f32_16x16x32_bf16 v[118:121], v[162:165], v[190:193], v[118:121]
	v_mfma_f32_16x16x32_bf16 v[110:113], v[154:157], v[198:201], v[110:113]
	v_mfma_f32_16x16x32_bf16 v[102:105], v[162:165], v[198:201], v[102:105]
	v_mfma_f32_16x16x32_bf16 v[94:97], v[154:157], v[216:219], v[94:97]
	v_mfma_f32_16x16x32_bf16 v[86:89], v[162:165], v[216:219], v[86:89]
	v_mfma_f32_16x16x32_bf16 v[78:81], v[154:157], v[240:243], v[78:81]
	v_mfma_f32_16x16x32_bf16 v[74:77], v[162:165], v[240:243], v[74:77]
	v_mfma_f32_16x16x32_bf16 v[126:129], v[158:161], v[194:197], v[126:129]
	v_mfma_f32_16x16x32_bf16 v[118:121], v[166:169], v[194:197], v[118:121]
	v_mfma_f32_16x16x32_bf16 v[110:113], v[158:161], v[202:205], v[110:113]
	v_mfma_f32_16x16x32_bf16 v[102:105], v[166:169], v[202:205], v[102:105]
	v_mfma_f32_16x16x32_bf16 v[94:97], v[158:161], v[220:223], v[94:97]
	v_mfma_f32_16x16x32_bf16 v[86:89], v[166:169], v[220:223], v[86:89]
	v_mfma_f32_16x16x32_bf16 v[78:81], v[158:161], v[244:247], v[78:81]
	v_mfma_f32_16x16x32_bf16 v[74:77], v[166:169], v[244:247], v[74:77]
	s_setprio 0
	s_barrier
; #define PG8_STAGE(bufoff, gbase, voff) do { _Pragma("unroll") for (int _i = 0; _i < 2; ++_i) \
;         __builtin_amdgcn_global_load_lds((const unsigned*)((const char*)(gbase) + (voff)[_i]), (PG8_LAS unsigned*)(lds + (bufoff) + ldsw + _i * 8192), 16, 0, 0); } while (0)
; #define PG8_LDA(dst, b, h) do { _Pragma("unroll") for (int m = 0; m < 4; ++m) _Pragma("unroll") for (int k = 0; k < 2; ++k) dst[m][k] = *(const PG8_LAS bf16x8*)(lds + PG8_SA(b, h) + aoff + m * 2048 + k * 1024); } while (0)
; #define PG8_MMA(ai, bj, At, Bt) do { __builtin_amdgcn_s_setprio(1); _Pragma("unroll") for (int m = 0; m < 4; ++m) _Pragma("unroll") for (int n = 0; n < 2; ++n) _Pragma("unroll") for (int k = 0; k < 2; ++k) \
;         acc[ai][bj][m][n] = __builtin_amdgcn_mfma_f32_16x16x32_bf16(Bt[n][k], At[m][k], acc[ai][bj][m][n], 0, 0, 0); __builtin_amdgcn_s_setprio(0); } while (0)
; #define PG8_WAIT_V(n) asm volatile("s_waitcnt vmcnt(" #n ")" ::: "memory")
; #define PG8_WAIT_L(n) asm volatile("s_waitcnt lgkmcnt(" #n ")" ::: "memory")
; #define PG8_BAR __builtin_amdgcn_s_barrier()
; #define PG8_SCHED __builtin_amdgcn_sched_barrier(0)
; template <class Epi, class Sched, bool ALIGN_EPI = false, bool SP2 = false>
; __device__ __forceinline__ void gemm_phase(PG8_LAS unsigned char* lds, const Gemm g, const Sched& S, const Epi& E, const int wave_id) {
;     ...
;         for (int t = 0; t < nt; t += 2) {
;             const bool last = (t == nt - 2);
;     ...
;             PG8_LDA(At, 1, 1); PG8_STAGE(PG8_SB(1, 0), b3, voffB); PG8_STAGE(PG8_SB(1, 1), b3 + hstepB, voffB); PG8_STAGE(PG8_SA(1, 0), a3, voffA);
;             PG8_WAIT_V(8); PG8_WAIT_L(0); PG8_BAR; PG8_MMA(1, 0, At, B0); PG8_MMA(1, 1, At, B1); PG8_BAR; PG8_SCHED;
	s_add_i32 s0, s35, s23
	v_lshl_add_u64 v[206:207], v[206:207], 0, s[62:63]
	s_mov_b32 m0, s0
	ds_read_b128 v[190:193], v215 offset:49152
	ds_read_b128 v[194:197], v215 offset:50176
	ds_read_b128 v[198:201], v215 offset:51200
	ds_read_b128 v[202:205], v215 offset:52224
	ds_read_b128 v[216:219], v215 offset:53248
	ds_read_b128 v[220:223], v215 offset:54272
	ds_read_b128 v[240:243], v215 offset:55296
	ds_read_b128 v[244:247], v215 offset:56320
	global_load_lds_dwordx4 v[206:207], off
	s_add_i32 m0, s0, 0x2000
	s_add_u32 s0, s26, 0x40080
	v_lshl_add_u64 v[206:207], v[224:225], 0, s[62:63]
	s_addc_u32 s1, s27, 0
	s_add_i32 s26, s36, s23
	global_load_lds_dwordx4 v[206:207], off
	v_lshl_add_u64 v[206:207], s[0:1], 0, v[180:181]
	s_mov_b32 m0, s26
	s_nop 0
	global_load_lds_dwordx4 v[206:207], off
	v_lshl_add_u64 v[206:207], s[0:1], 0, v[184:185]
	s_add_i32 m0, s26, 0x2000
	s_nop 0
	global_load_lds_dwordx4 v[206:207], off
	v_lshl_add_u64 v[206:207], v[234:235], 0, s[62:63]
	s_mov_b32 m0, s44
	s_nop 0
	global_load_lds_dwordx4 v[206:207], off
	v_lshl_add_u64 v[206:207], v[236:237], 0, s[62:63]
	s_mov_b32 m0, s45
	s_nop 0
	global_load_lds_dwordx4 v[206:207], off
	s_waitcnt vmcnt(8)
	s_waitcnt lgkmcnt(0)
	s_barrier
	s_setprio 1
	v_mfma_f32_16x16x32_bf16 v[70:73], v[138:141], v[190:193], v[70:73]
	v_mfma_f32_16x16x32_bf16 v[66:69], v[146:149], v[190:193], v[66:69]
	v_mfma_f32_16x16x32_bf16 v[58:61], v[138:141], v[198:201], v[58:61]
	v_mfma_f32_16x16x32_bf16 v[50:53], v[146:149], v[198:201], v[50:53]
	v_mfma_f32_16x16x32_bf16 v[42:45], v[138:141], v[216:219], v[42:45]
	v_mfma_f32_16x16x32_bf16 v[34:37], v[146:149], v[216:219], v[34:37]
	v_mfma_f32_16x16x32_bf16 v[26:29], v[138:141], v[240:243], v[26:29]
	v_mfma_f32_16x16x32_bf16 v[18:21], v[146:149], v[240:243], v[18:21]
	v_mfma_f32_16x16x32_bf16 v[70:73], v[142:145], v[194:197], v[70:73]
	v_mfma_f32_16x16x32_bf16 v[66:69], v[150:153], v[194:197], v[66:69]
	v_mfma_f32_16x16x32_bf16 v[58:61], v[142:145], v[202:205], v[58:61]
	v_mfma_f32_16x16x32_bf16 v[50:53], v[150:153], v[202:205], v[50:53]
	v_mfma_f32_16x16x32_bf16 v[42:45], v[142:145], v[220:223], v[42:45]
	v_mfma_f32_16x16x32_bf16 v[34:37], v[150:153], v[220:223], v[34:37]
	v_mfma_f32_16x16x32_bf16 v[26:29], v[142:145], v[244:247], v[26:29]
	v_mfma_f32_16x16x32_bf16 v[18:21], v[150:153], v[244:247], v[18:21]
	v_mfma_f32_16x16x32_bf16 v[62:65], v[154:157], v[190:193], v[62:65]
	v_mfma_f32_16x16x32_bf16 v[54:57], v[162:165], v[190:193], v[54:57]
	v_mfma_f32_16x16x32_bf16 v[46:49], v[154:157], v[198:201], v[46:49]
	v_mfma_f32_16x16x32_bf16 v[38:41], v[162:165], v[198:201], v[38:41]
	v_mfma_f32_16x16x32_bf16 v[30:33], v[154:157], v[216:219], v[30:33]
	v_mfma_f32_16x16x32_bf16 v[22:25], v[162:165], v[216:219], v[22:25]
	v_mfma_f32_16x16x32_bf16 v[14:17], v[154:157], v[240:243], v[14:17]
	v_mfma_f32_16x16x32_bf16 v[10:13], v[162:165], v[240:243], v[10:13]
	v_mfma_f32_16x16x32_bf16 v[62:65], v[158:161], v[194:197], v[62:65]
	v_mfma_f32_16x16x32_bf16 v[54:57], v[166:169], v[194:197], v[54:57]
	v_mfma_f32_16x16x32_bf16 v[46:49], v[158:161], v[202:205], v[46:49]
	v_mfma_f32_16x16x32_bf16 v[38:41], v[166:169], v[202:205], v[38:41]
	v_mfma_f32_16x16x32_bf16 v[30:33], v[158:161], v[220:223], v[30:33]
	v_mfma_f32_16x16x32_bf16 v[22:25], v[166:169], v[220:223], v[22:25]
	v_mfma_f32_16x16x32_bf16 v[14:17], v[158:161], v[244:247], v[14:17]
	v_mfma_f32_16x16x32_bf16 v[10:13], v[166:169], v[244:247], v[10:13]
	s_setprio 0
	s_barrier
	s_add_i32 s5, s5, 2
	s_add_u32 s8, s8, 0x100
	s_addc_u32 s9, s9, 0
	s_add_u32 vcc_hi, vcc_hi, 0x100
	s_addc_u32 s4, s4, 0
	s_cmp_gt_u32 s5, 13
	s_cbranch_scc0 .LBB0_576

; #define PG8_STAGE(bufoff, gbase, voff) do { _Pragma("unroll") for (int _i = 0; _i < 2; ++_i) \
;         __builtin_amdgcn_global_load_lds((const unsigned*)((const char*)(gbase) + (voff)[_i]), (PG8_LAS unsigned*)(lds + (bufoff) + ldsw + _i * 8192), 16, 0, 0); } while (0)
; #define PG8_LDA(dst, b, h) do { _Pragma("unroll") for (int m = 0; m < 4; ++m) _Pragma("unroll") for (int k = 0; k < 2; ++k) dst[m][k] = *(const PG8_LAS bf16x8*)(lds + PG8_SA(b, h) + aoff + m * 2048 + k * 1024); } while (0)
; #define PG8_MMA(ai, bj, At, Bt) do { __builtin_amdgcn_s_setprio(1); _Pragma("unroll") for (int m = 0; m < 4; ++m) _Pragma("unroll") for (int n = 0; n < 2; ++n) _Pragma("unroll") for (int k = 0; k < 2; ++k) \
;         acc[ai][bj][m][n] = __builtin_amdgcn_mfma_f32_16x16x32_bf16(Bt[n][k], At[m][k], acc[ai][bj][m][n], 0, 0, 0); __builtin_amdgcn_s_setprio(0); } while (0)
; #define PG8_WAIT_V(n) asm volatile("s_waitcnt vmcnt(" #n ")" ::: "memory")
; #define PG8_WAIT_L(n) asm volatile("s_waitcnt lgkmcnt(" #n ")" ::: "memory")
; #define PG8_BAR __builtin_amdgcn_s_barrier()
; #define PG8_SCHED __builtin_amdgcn_sched_barrier(0)
; template <class Epi, class Sched, bool ALIGN_EPI = false, bool SP2 = false>
; __device__ __forceinline__ void gemm_phase(PG8_LAS unsigned char* lds, const Gemm g, const Sched& S, const Epi& E, const int wave_id) {
;     ...
;             PG8_WAIT_V(8); PG8_WAIT_L(0); PG8_BAR; PG8_MMA(0, 0, At, B0); PG8_MMA(0, 1, At, B1); PG8_BAR; PG8_SCHED;
;             PG8_LDA(At, 0, 1); PG8_STAGE(PG8_SB(0, 0), b2, voffB); PG8_STAGE(PG8_SB(0, 1), b2 + hstepB, voffB); PG8_STAGE(PG8_SA(0, 0), a2, voffA);
;             PG8_WAIT_V(8); PG8_WAIT_L(0); PG8_BAR; PG8_MMA(1, 0, At, B0); PG8_MMA(1, 1, At, B1); PG8_BAR; PG8_SCHED;
.Lrw_5:
	s_waitcnt lgkmcnt(0)
	s_barrier
	s_setprio 1
	v_mfma_f32_16x16x32_bf16 v[166:169], v[114:117], v[190:193], v[166:169]
	v_mfma_f32_16x16x32_bf16 v[162:165], v[122:125], v[190:193], v[162:165]
	v_mfma_f32_16x16x32_bf16 v[134:137], v[114:117], v[202:205], v[134:137]
	v_mfma_f32_16x16x32_bf16 v[126:129], v[122:125], v[202:205], v[126:129]
	v_mfma_f32_16x16x32_bf16 v[102:105], v[114:117], v[210:213], v[102:105]
	v_mfma_f32_16x16x32_bf16 v[98:101], v[122:125], v[210:213], v[98:101]
	v_mfma_f32_16x16x32_bf16 v[86:89], v[114:117], v[218:221], v[86:89]
	v_mfma_f32_16x16x32_bf16 v[82:85], v[122:125], v[218:221], v[82:85]
	v_mfma_f32_16x16x32_bf16 v[166:169], v[118:121], v[194:197], v[166:169]
	v_mfma_f32_16x16x32_bf16 v[162:165], v[130:133], v[194:197], v[162:165]
	v_mfma_f32_16x16x32_bf16 v[134:137], v[118:121], v[206:209], v[134:137]
	v_mfma_f32_16x16x32_bf16 v[126:129], v[130:133], v[206:209], v[126:129]
	v_mfma_f32_16x16x32_bf16 v[102:105], v[118:121], v[214:217], v[102:105]
	v_mfma_f32_16x16x32_bf16 v[98:101], v[130:133], v[214:217], v[98:101]
	v_mfma_f32_16x16x32_bf16 v[86:89], v[118:121], v[222:225], v[86:89]
	v_mfma_f32_16x16x32_bf16 v[82:85], v[130:133], v[222:225], v[82:85]
	v_mfma_f32_16x16x32_bf16 v[158:161], v[138:141], v[190:193], v[158:161]
	v_mfma_f32_16x16x32_bf16 v[146:149], v[150:153], v[190:193], v[146:149]
	v_mfma_f32_16x16x32_bf16 v[110:113], v[138:141], v[202:205], v[110:113]
	v_mfma_f32_16x16x32_bf16 v[106:109], v[150:153], v[202:205], v[106:109]
	v_mfma_f32_16x16x32_bf16 v[94:97], v[138:141], v[210:213], v[94:97]
	v_mfma_f32_16x16x32_bf16 v[90:93], v[150:153], v[210:213], v[90:93]
	v_mfma_f32_16x16x32_bf16 v[78:81], v[138:141], v[218:221], v[78:81]
	v_mfma_f32_16x16x32_bf16 v[74:77], v[150:153], v[218:221], v[74:77]
	v_mfma_f32_16x16x32_bf16 v[158:161], v[142:145], v[194:197], v[158:161]
	v_mfma_f32_16x16x32_bf16 v[146:149], v[154:157], v[194:197], v[146:149]
	v_mfma_f32_16x16x32_bf16 v[110:113], v[142:145], v[206:209], v[110:113]
	v_mfma_f32_16x16x32_bf16 v[106:109], v[154:157], v[206:209], v[106:109]
	v_mfma_f32_16x16x32_bf16 v[94:97], v[142:145], v[214:217], v[94:97]
	v_mfma_f32_16x16x32_bf16 v[90:93], v[154:157], v[214:217], v[90:93]
	v_mfma_f32_16x16x32_bf16 v[78:81], v[142:145], v[222:225], v[78:81]
	v_mfma_f32_16x16x32_bf16 v[74:77], v[154:157], v[222:225], v[74:77]
	s_setprio 0
	s_barrier
	s_add_i32 s1, s38, s23
	v_lshl_add_u64 v[198:199], s[26:27], 0, v[180:181]
	s_mov_b32 m0, s1
	ds_read_b128 v[190:193], v245 offset:16384
	ds_read_b128 v[194:197], v245 offset:17408
	ds_read_b128 v[202:205], v245 offset:18432
	ds_read_b128 v[206:209], v245 offset:19456
	ds_read_b128 v[210:213], v245 offset:20480
	ds_read_b128 v[214:217], v245 offset:21504
	ds_read_b128 v[218:221], v245 offset:22528
	ds_read_b128 v[222:225], v245 offset:23552
	global_load_lds_dwordx4 v[198:199], off
	s_add_i32 m0, s1, 0x2000
	s_add_u32 s38, s26, 0x40000
	v_lshl_add_u64 v[234:235], s[26:27], 0, v[184:185]
	s_addc_u32 s39, s27, 0
	s_add_i32 s0, s0, s23
	global_load_lds_dwordx4 v[234:235], off
	v_lshl_add_u64 v[236:237], s[38:39], 0, v[180:181]
	s_mov_b32 m0, s0
	v_lshl_add_u64 v[246:247], s[28:29], 0, v[182:183]
	global_load_lds_dwordx4 v[236:237], off
	v_lshl_add_u64 v[236:237], s[38:39], 0, v[184:185]
	s_add_i32 m0, s0, 0x2000
	s_nop 0
	global_load_lds_dwordx4 v[236:237], off
	v_lshl_add_u64 v[236:237], s[28:29], 0, v[178:179]
	s_mov_b32 m0, s30
	s_nop 0
	global_load_lds_dwordx4 v[236:237], off
	s_mov_b32 m0, s31
	s_nop 0
	global_load_lds_dwordx4 v[246:247], off
	s_waitcnt vmcnt(24)
	s_cmp_eq_u32 s98, 1
	s_cbranch_scc1 .Lrw_6
	s_waitcnt vmcnt(8)
.Lrw_6:
	s_mov_b32 s98, 0
	s_waitcnt lgkmcnt(0)
	s_barrier
	s_setprio 1
	v_mfma_f32_16x16x32_bf16 v[70:73], v[114:117], v[190:193], v[70:73]
	v_mfma_f32_16x16x32_bf16 v[66:69], v[122:125], v[190:193], v[66:69]
	v_mfma_f32_16x16x32_bf16 v[54:57], v[114:117], v[202:205], v[54:57]
	v_mfma_f32_16x16x32_bf16 v[50:53], v[122:125], v[202:205], v[50:53]
	v_mfma_f32_16x16x32_bf16 v[38:41], v[114:117], v[210:213], v[38:41]
	v_mfma_f32_16x16x32_bf16 v[34:37], v[122:125], v[210:213], v[34:37]
	v_mfma_f32_16x16x32_bf16 v[22:25], v[114:117], v[218:221], v[22:25]
	v_mfma_f32_16x16x32_bf16 v[18:21], v[122:125], v[218:221], v[18:21]
	v_mfma_f32_16x16x32_bf16 v[70:73], v[118:121], v[194:197], v[70:73]
	v_mfma_f32_16x16x32_bf16 v[66:69], v[130:133], v[194:197], v[66:69]
	v_mfma_f32_16x16x32_bf16 v[54:57], v[118:121], v[206:209], v[54:57]
	v_mfma_f32_16x16x32_bf16 v[50:53], v[130:133], v[206:209], v[50:53]
	v_mfma_f32_16x16x32_bf16 v[38:41], v[118:121], v[214:217], v[38:41]
	v_mfma_f32_16x16x32_bf16 v[34:37], v[130:133], v[214:217], v[34:37]
	v_mfma_f32_16x16x32_bf16 v[22:25], v[118:121], v[222:225], v[22:25]
	v_mfma_f32_16x16x32_bf16 v[18:21], v[130:133], v[222:225], v[18:21]
	v_mfma_f32_16x16x32_bf16 v[62:65], v[138:141], v[190:193], v[62:65]
	v_mfma_f32_16x16x32_bf16 v[58:61], v[150:153], v[190:193], v[58:61]
	v_mfma_f32_16x16x32_bf16 v[46:49], v[138:141], v[202:205], v[46:49]
	v_mfma_f32_16x16x32_bf16 v[42:45], v[150:153], v[202:205], v[42:45]
	v_mfma_f32_16x16x32_bf16 v[30:33], v[138:141], v[210:213], v[30:33]
	v_mfma_f32_16x16x32_bf16 v[26:29], v[150:153], v[210:213], v[26:29]
	v_mfma_f32_16x16x32_bf16 v[14:17], v[138:141], v[218:221], v[14:17]
	v_mfma_f32_16x16x32_bf16 v[10:13], v[150:153], v[218:221], v[10:13]
	v_mfma_f32_16x16x32_bf16 v[62:65], v[142:145], v[194:197], v[62:65]
	v_mfma_f32_16x16x32_bf16 v[58:61], v[154:157], v[194:197], v[58:61]
	v_mfma_f32_16x16x32_bf16 v[46:49], v[142:145], v[206:209], v[46:49]
	v_mfma_f32_16x16x32_bf16 v[42:45], v[154:157], v[206:209], v[42:45]
	v_mfma_f32_16x16x32_bf16 v[30:33], v[142:145], v[214:217], v[30:33]
	v_mfma_f32_16x16x32_bf16 v[26:29], v[154:157], v[214:217], v[26:29]
	v_mfma_f32_16x16x32_bf16 v[14:17], v[142:145], v[222:225], v[14:17]
	v_mfma_f32_16x16x32_bf16 v[10:13], v[154:157], v[222:225], v[10:13]
	s_setprio 0
	s_barrier
; #define PG8_STAGE(bufoff, gbase, voff) do { _Pragma("unroll") for (int _i = 0; _i < 2; ++_i) \
;         __builtin_amdgcn_global_load_lds((const unsigned*)((const char*)(gbase) + (voff)[_i]), (PG8_LAS unsigned*)(lds + (bufoff) + ldsw + _i * 8192), 16, 0, 0); } while (0)
; #define PG8_LDA(dst, b, h) do { _Pragma("unroll") for (int m = 0; m < 4; ++m) _Pragma("unroll") for (int k = 0; k < 2; ++k) dst[m][k] = *(const PG8_LAS bf16x8*)(lds + PG8_SA(b, h) + aoff + m * 2048 + k * 1024); } while (0)
; #define PG8_LDB(dst, b, h) do { _Pragma("unroll") for (int n = 0; n < 2; ++n) _Pragma("unroll") for (int k = 0; k < 2; ++k) dst[n][k] = *(const PG8_LAS bf16x8*)(lds + PG8_SB(b, h) + boff + n * 2048 + k * 1024); } while (0)
; #define PG8_MMA(ai, bj, At, Bt) do { __builtin_amdgcn_s_setprio(1); _Pragma("unroll") for (int m = 0; m < 4; ++m) _Pragma("unroll") for (int n = 0; n < 2; ++n) _Pragma("unroll") for (int k = 0; k < 2; ++k) \
;         acc[ai][bj][m][n] = __builtin_amdgcn_mfma_f32_16x16x32_bf16(Bt[n][k], At[m][k], acc[ai][bj][m][n], 0, 0, 0); __builtin_amdgcn_s_setprio(0); } while (0)
; #define PG8_WAIT_V(n) asm volatile("s_waitcnt vmcnt(" #n ")" ::: "memory")
; #define PG8_WAIT_L(n) asm volatile("s_waitcnt lgkmcnt(" #n ")" ::: "memory")
; #define PG8_BAR __builtin_amdgcn_s_barrier()
; #define PG8_SCHED __builtin_amdgcn_sched_barrier(0)
; template <class Epi, class Sched, bool ALIGN_EPI = false, bool SP2 = false>
; __device__ __forceinline__ void gemm_phase(PG8_LAS unsigned char* lds, const Gemm g, const Sched& S, const Epi& E, const int wave_id) {
;     ...
;             PG8_LDB(B0, 1, 0); PG8_LDB(B1, 1, 1); PG8_SCHED; PG8_LDA(At, 1, 0); PG8_STAGE(PG8_SA(0, 1), a2 + hstepA, voffA);
;             PG8_WAIT_V(8); PG8_WAIT_L(0); PG8_BAR; PG8_MMA(0, 0, At, B0); PG8_MMA(0, 1, At, B1); PG8_BAR; PG8_SCHED;
	s_add_i32 s0, 0, 0x18000
	v_add_u32_e32 v0, s0, v240
	s_add_i32 s1, 0, 0x1c000
	ds_read_b128 v[114:117], v0
	ds_read_b128 v[118:121], v0 offset:1024
	ds_read_b128 v[122:125], v0 offset:2048
	ds_read_b128 v[130:133], v0 offset:3072
	v_add_u32_e32 v0, s1, v240
	ds_read_b128 v[138:141], v0
	ds_read_b128 v[142:145], v0 offset:1024
	ds_read_b128 v[150:153], v0 offset:2048
	ds_read_b128 v[154:157], v0 offset:3072
	s_add_u32 s28, s28, 0x40000
	s_addc_u32 s29, s29, 0
	s_mov_b32 m0, s34
	v_lshl_add_u64 v[248:249], s[28:29], 0, v[178:179]
	ds_read_b128 v[190:193], v245 offset:32768
	ds_read_b128 v[194:197], v245 offset:33792
	ds_read_b128 v[202:205], v245 offset:34816
	ds_read_b128 v[206:209], v245 offset:35840
	ds_read_b128 v[210:213], v245 offset:36864
	ds_read_b128 v[214:217], v245 offset:37888
	ds_read_b128 v[218:221], v245 offset:38912
	ds_read_b128 v[222:225], v245 offset:39936
	global_load_lds_dwordx4 v[248:249], off
	v_lshl_add_u64 v[248:249], s[28:29], 0, v[182:183]
	s_mov_b32 m0, s35
	s_nop 0
	global_load_lds_dwordx4 v[248:249], off
	s_waitcnt vmcnt(8)
	s_waitcnt lgkmcnt(0)
	s_barrier
	s_setprio 1
	v_mfma_f32_16x16x32_bf16 v[166:169], v[114:117], v[190:193], v[166:169]
	v_mfma_f32_16x16x32_bf16 v[162:165], v[122:125], v[190:193], v[162:165]
	v_mfma_f32_16x16x32_bf16 v[134:137], v[114:117], v[202:205], v[134:137]
	v_mfma_f32_16x16x32_bf16 v[126:129], v[122:125], v[202:205], v[126:129]
	v_mfma_f32_16x16x32_bf16 v[102:105], v[114:117], v[210:213], v[102:105]
	v_mfma_f32_16x16x32_bf16 v[98:101], v[122:125], v[210:213], v[98:101]
	v_mfma_f32_16x16x32_bf16 v[86:89], v[114:117], v[218:221], v[86:89]
	v_mfma_f32_16x16x32_bf16 v[82:85], v[122:125], v[218:221], v[82:85]
	v_mfma_f32_16x16x32_bf16 v[166:169], v[118:121], v[194:197], v[166:169]
	v_mfma_f32_16x16x32_bf16 v[162:165], v[130:133], v[194:197], v[162:165]
	v_mfma_f32_16x16x32_bf16 v[134:137], v[118:121], v[206:209], v[134:137]
	v_mfma_f32_16x16x32_bf16 v[126:129], v[130:133], v[206:209], v[126:129]
	v_mfma_f32_16x16x32_bf16 v[102:105], v[118:121], v[214:217], v[102:105]
	v_mfma_f32_16x16x32_bf16 v[98:101], v[130:133], v[214:217], v[98:101]
	v_mfma_f32_16x16x32_bf16 v[86:89], v[118:121], v[222:225], v[86:89]
	v_mfma_f32_16x16x32_bf16 v[82:85], v[130:133], v[222:225], v[82:85]
	v_mfma_f32_16x16x32_bf16 v[158:161], v[138:141], v[190:193], v[158:161]
	v_mfma_f32_16x16x32_bf16 v[146:149], v[150:153], v[190:193], v[146:149]
	v_mfma_f32_16x16x32_bf16 v[110:113], v[138:141], v[202:205], v[110:113]
	v_mfma_f32_16x16x32_bf16 v[106:109], v[150:153], v[202:205], v[106:109]
	v_mfma_f32_16x16x32_bf16 v[94:97], v[138:141], v[210:213], v[94:97]
	v_mfma_f32_16x16x32_bf16 v[90:93], v[150:153], v[210:213], v[90:93]
	v_mfma_f32_16x16x32_bf16 v[78:81], v[138:141], v[218:221], v[78:81]
	v_mfma_f32_16x16x32_bf16 v[74:77], v[150:153], v[218:221], v[74:77]
	v_mfma_f32_16x16x32_bf16 v[158:161], v[142:145], v[194:197], v[158:161]
	v_mfma_f32_16x16x32_bf16 v[146:149], v[154:157], v[194:197], v[146:149]
	v_mfma_f32_16x16x32_bf16 v[110:113], v[142:145], v[206:209], v[110:113]
	v_mfma_f32_16x16x32_bf16 v[106:109], v[154:157], v[206:209], v[106:109]
	v_mfma_f32_16x16x32_bf16 v[94:97], v[142:145], v[214:217], v[94:97]
	v_mfma_f32_16x16x32_bf16 v[90:93], v[154:157], v[214:217], v[90:93]
	v_mfma_f32_16x16x32_bf16 v[78:81], v[142:145], v[222:225], v[78:81]
	v_mfma_f32_16x16x32_bf16 v[74:77], v[154:157], v[222:225], v[74:77]
	s_setprio 0
	s_barrier
; #define PG8_STAGE(bufoff, gbase, voff) do { _Pragma("unroll") for (int _i = 0; _i < 2; ++_i) \
;         __builtin_amdgcn_global_load_lds((const unsigned*)((const char*)(gbase) + (voff)[_i]), (PG8_LAS unsigned*)(lds + (bufoff) + ldsw + _i * 8192), 16, 0, 0); } while (0)
; #define PG8_LDA(dst, b, h) do { _Pragma("unroll") for (int m = 0; m < 4; ++m) _Pragma("unroll") for (int k = 0; k < 2; ++k) dst[m][k] = *(const PG8_LAS bf16x8*)(lds + PG8_SA(b, h) + aoff + m * 2048 + k * 1024); } while (0)
; #define PG8_MMA(ai, bj, At, Bt) do { __builtin_amdgcn_s_setprio(1); _Pragma("unroll") for (int m = 0; m < 4; ++m) _Pragma("unroll") for (int n = 0; n < 2; ++n) _Pragma("unroll") for (int k = 0; k < 2; ++k) \
;         acc[ai][bj][m][n] = __builtin_amdgcn_mfma_f32_16x16x32_bf16(Bt[n][k], At[m][k], acc[ai][bj][m][n], 0, 0, 0); __builtin_amdgcn_s_setprio(0); } while (0)
; #define PG8_WAIT_V(n) asm volatile("s_waitcnt vmcnt(" #n ")" ::: "memory")
; #define PG8_WAIT_L(n) asm volatile("s_waitcnt lgkmcnt(" #n ")" ::: "memory")
; #define PG8_BAR __builtin_amdgcn_s_barrier()
; #define PG8_SCHED __builtin_amdgcn_sched_barrier(0)
; template <class Epi, class Sched, bool ALIGN_EPI = false, bool SP2 = false>
; __device__ __forceinline__ void gemm_phase(PG8_LAS unsigned char* lds, const Gemm g, const Sched& S, const Epi& E, const int wave_id) {
;     ...
;         for (int t = 0; t < nt; t += 2) {
;     ...
;             PG8_LDA(At, 1, 1); PG8_STAGE(PG8_SB(1, 0), b3, voffB); PG8_STAGE(PG8_SB(1, 1), b3 + hstepB, voffB); PG8_STAGE(PG8_SA(1, 0), a3, voffA);
;             PG8_WAIT_V(8); PG8_WAIT_L(0); PG8_BAR; PG8_MMA(1, 0, At, B0); PG8_MMA(1, 1, At, B1); PG8_BAR; PG8_SCHED;
	s_add_i32 s0, s0, s23
	v_lshl_add_u64 v[198:199], v[198:199], 0, s[62:63]
	s_mov_b32 m0, s0
	ds_read_b128 v[190:193], v245 offset:49152
	ds_read_b128 v[194:197], v245 offset:50176
	ds_read_b128 v[202:205], v245 offset:51200
	ds_read_b128 v[206:209], v245 offset:52224
	ds_read_b128 v[210:213], v245 offset:53248
	ds_read_b128 v[214:217], v245 offset:54272
	ds_read_b128 v[218:221], v245 offset:55296
	ds_read_b128 v[222:225], v245 offset:56320
	global_load_lds_dwordx4 v[198:199], off
	s_add_i32 m0, s0, 0x2000
	s_add_u32 s26, s26, 0x40080
	v_lshl_add_u64 v[198:199], v[234:235], 0, s[62:63]
	s_addc_u32 s27, s27, 0
	s_add_i32 s0, s1, s23
	global_load_lds_dwordx4 v[198:199], off
	v_lshl_add_u64 v[198:199], s[26:27], 0, v[180:181]
	s_mov_b32 m0, s0
	s_nop 0
	global_load_lds_dwordx4 v[198:199], off
	v_lshl_add_u64 v[198:199], s[26:27], 0, v[184:185]
	s_add_i32 m0, s0, 0x2000
	s_nop 0
	global_load_lds_dwordx4 v[198:199], off
	v_lshl_add_u64 v[198:199], v[236:237], 0, s[62:63]
	s_mov_b32 m0, s45
	s_nop 0
	global_load_lds_dwordx4 v[198:199], off
	v_lshl_add_u64 v[198:199], v[246:247], 0, s[62:63]
	s_mov_b32 m0, s76
	s_nop 0
	global_load_lds_dwordx4 v[198:199], off
	s_waitcnt vmcnt(8)
	s_waitcnt lgkmcnt(0)
	s_barrier
	s_setprio 1
	v_mfma_f32_16x16x32_bf16 v[70:73], v[114:117], v[190:193], v[70:73]
	v_mfma_f32_16x16x32_bf16 v[66:69], v[122:125], v[190:193], v[66:69]
	v_mfma_f32_16x16x32_bf16 v[54:57], v[114:117], v[202:205], v[54:57]
	v_mfma_f32_16x16x32_bf16 v[50:53], v[122:125], v[202:205], v[50:53]
	v_mfma_f32_16x16x32_bf16 v[38:41], v[114:117], v[210:213], v[38:41]
	v_mfma_f32_16x16x32_bf16 v[34:37], v[122:125], v[210:213], v[34:37]
	v_mfma_f32_16x16x32_bf16 v[22:25], v[114:117], v[218:221], v[22:25]
	v_mfma_f32_16x16x32_bf16 v[18:21], v[122:125], v[218:221], v[18:21]
	v_mfma_f32_16x16x32_bf16 v[70:73], v[118:121], v[194:197], v[70:73]
	v_mfma_f32_16x16x32_bf16 v[66:69], v[130:133], v[194:197], v[66:69]
	v_mfma_f32_16x16x32_bf16 v[54:57], v[118:121], v[206:209], v[54:57]
	v_mfma_f32_16x16x32_bf16 v[50:53], v[130:133], v[206:209], v[50:53]
	v_mfma_f32_16x16x32_bf16 v[38:41], v[118:121], v[214:217], v[38:41]
	v_mfma_f32_16x16x32_bf16 v[34:37], v[130:133], v[214:217], v[34:37]
	v_mfma_f32_16x16x32_bf16 v[22:25], v[118:121], v[222:225], v[22:25]
	v_mfma_f32_16x16x32_bf16 v[18:21], v[130:133], v[222:225], v[18:21]
	v_mfma_f32_16x16x32_bf16 v[62:65], v[138:141], v[190:193], v[62:65]
	v_mfma_f32_16x16x32_bf16 v[58:61], v[150:153], v[190:193], v[58:61]
	v_mfma_f32_16x16x32_bf16 v[46:49], v[138:141], v[202:205], v[46:49]
	v_mfma_f32_16x16x32_bf16 v[42:45], v[150:153], v[202:205], v[42:45]
	v_mfma_f32_16x16x32_bf16 v[30:33], v[138:141], v[210:213], v[30:33]
	v_mfma_f32_16x16x32_bf16 v[26:29], v[150:153], v[210:213], v[26:29]
	v_mfma_f32_16x16x32_bf16 v[14:17], v[138:141], v[218:221], v[14:17]
	v_mfma_f32_16x16x32_bf16 v[10:13], v[150:153], v[218:221], v[10:13]
	v_mfma_f32_16x16x32_bf16 v[62:65], v[142:145], v[194:197], v[62:65]
	v_mfma_f32_16x16x32_bf16 v[58:61], v[154:157], v[194:197], v[58:61]
	v_mfma_f32_16x16x32_bf16 v[46:49], v[142:145], v[206:209], v[46:49]
	v_mfma_f32_16x16x32_bf16 v[42:45], v[154:157], v[206:209], v[42:45]
	v_mfma_f32_16x16x32_bf16 v[30:33], v[142:145], v[214:217], v[30:33]
	v_mfma_f32_16x16x32_bf16 v[26:29], v[154:157], v[214:217], v[26:29]
	v_mfma_f32_16x16x32_bf16 v[14:17], v[142:145], v[222:225], v[14:17]
	v_mfma_f32_16x16x32_bf16 v[10:13], v[154:157], v[222:225], v[10:13]
	s_setprio 0
	s_barrier
	s_add_i32 s37, s37, 2
	s_add_u32 s8, s8, 0x100
	s_addc_u32 s9, s9, 0
	s_add_u32 vcc_lo, vcc_lo, 0x100
	s_addc_u32 vcc_hi, vcc_hi, 0
	s_cmp_gt_u32 s37, 13
	s_cbranch_scc0 .LBB0_627
	s_and_b64 vcc, exec, s[12:13]
	s_cbranch_vccz .LBB0_630
	s_barrier
